# weight f32->bf16 transposition: the 32 serialized ds_read2+wait+cvt round trips per 64x64 item issued as 8 groups of 4 reads one group ahead with counted lgkmcnt (9 instances)
# baseline (speedup 1.0000x reference)
; #define LAS __attribute__((address_space(3)))
; __device__ __forceinline__ unsigned pk2(float lo, float hi) { unsigned r; asm volatile("v_cvt_pk_bf16_f32 %0, %1, %2" : "=v"(r) : "v"(lo), "v"(hi)); return r; }
; __device__ __forceinline__ void transpose_item(const float* __restrict__ W, int K, int N, bf16_t* __restrict__ WT, int drow0, LAS float* scr, int k0, int n0, int lane, const float* __restrict__ gk) {
;     ...
;     asm volatile("s_waitcnt lgkmcnt(0)" ::: "memory");
;     const int c = lane & 7;
; #pragma unroll
;     for (int j = 0; j < 8; ++j) { const int n = (lane >> 3) + 8 * j; const LAS float* s = scr + (8 * c) * 65 + n;
;         u32x4 o; o.x = pk2(s[0 * 65], s[1 * 65]); o.y = pk2(s[2 * 65], s[3 * 65]); o.z = pk2(s[4 * 65], s[5 * 65]); o.w = pk2(s[6 * 65], s[7 * 65]);
;         *(u32x4*)(WT + (size_t)(drow0 + n) * K + k0 + 8 * c) = o; }
;     asm volatile("s_waitcnt lgkmcnt(0)" ::: "memory");
.LBB0_376:
	s_waitcnt vmcnt(0)
	ds_write2_b32 v76, v2, v3 offset1:65
	ds_write2_b32 v76, v12, v13 offset0:130 offset1:195
	v_add_u32_e32 v2, 0x400, v76
	ds_write2_b32 v2, v14, v15 offset0:4 offset1:69
	ds_write2_b32 v2, v16, v17 offset0:134 offset1:199
	v_add_u32_e32 v2, 0x800, v76
	ds_write2_b32 v2, v18, v19 offset0:8 offset1:73
	ds_write2_b32 v2, v20, v21 offset0:138 offset1:203
	v_add_u32_e32 v2, 0xc00, v76
	ds_write2_b32 v2, v22, v23 offset0:12 offset1:77
	ds_write2_b32 v2, v24, v25 offset0:142 offset1:207
	v_add_u32_e32 v2, 0x1000, v76
	ds_write2_b32 v2, v26, v27 offset0:16 offset1:81
	ds_write2_b32 v2, v28, v29 offset0:146 offset1:211
	v_add_u32_e32 v2, 0x1400, v76
	ds_write2_b32 v2, v30, v31 offset0:20 offset1:85
	ds_write2_b32 v2, v32, v33 offset0:150 offset1:215
	v_add_u32_e32 v2, 0x1800, v76
	ds_write2_b32 v2, v34, v35 offset0:24 offset1:89
	ds_write2_b32 v2, v36, v37 offset0:154 offset1:219
	v_add_u32_e32 v2, 0x1c00, v76
	ds_write2_b32 v2, v38, v39 offset0:28 offset1:93
	ds_write2_b32 v2, v40, v41 offset0:158 offset1:223
	v_add_u32_e32 v2, 0x2000, v76
	ds_write2_b32 v2, v42, v43 offset0:32 offset1:97
	ds_write2_b32 v2, v44, v45 offset0:162 offset1:227
	v_add_u32_e32 v2, 0x2400, v76
	ds_write2_b32 v2, v46, v47 offset0:36 offset1:101
	ds_write2_b32 v2, v48, v49 offset0:166 offset1:231
	v_add_u32_e32 v2, 0x2800, v76
	ds_write2_b32 v2, v50, v51 offset0:40 offset1:105
	ds_write2_b32 v2, v52, v53 offset0:170 offset1:235
	v_add_u32_e32 v2, 0x2c00, v76
	ds_write2_b32 v2, v54, v55 offset0:44 offset1:109
	ds_write2_b32 v2, v56, v57 offset0:174 offset1:239
	v_add_u32_e32 v2, 0x3000, v76
	ds_write2_b32 v2, v58, v59 offset0:48 offset1:113
	ds_write2_b32 v2, v60, v61 offset0:178 offset1:243
	v_add_u32_e32 v2, 0x3400, v76
	ds_write2_b32 v2, v62, v63 offset0:52 offset1:117
	ds_write2_b32 v2, v64, v65 offset0:182 offset1:247
	v_add_u32_e32 v2, 0x3800, v76
	ds_write2_b32 v2, v66, v67 offset0:56 offset1:121
	ds_write2_b32 v2, v68, v69 offset0:186 offset1:251
	v_add_u32_e32 v2, 0x3c00, v76
	ds_write2_b32 v2, v70, v71 offset0:60 offset1:125
	ds_write2_b32 v2, v72, v73 offset0:190 offset1:255
	s_waitcnt lgkmcnt(0)
	v_add_u32_e32 v22, 0x400, v78
	ds_read2_b32 v[24:25], v78 offset1:65
	ds_read2_b32 v[26:27], v78 offset0:130 offset1:195
	ds_read2_b32 v[28:29], v22 offset0:4 offset1:69
	ds_read2_b32 v[30:31], v22 offset0:134 offset1:199
	ds_read2_b32 v[32:33], v78 offset0:8 offset1:73
	ds_read2_b32 v[34:35], v78 offset0:138 offset1:203
	ds_read2_b32 v[36:37], v22 offset0:12 offset1:77
	ds_read2_b32 v[38:39], v22 offset0:142 offset1:207
	s_waitcnt lgkmcnt(4)
	v_cvt_pk_bf16_f32 v12, v24, v25
	v_cvt_pk_bf16_f32 v13, v26, v27
	s_sub_i32 s18, 0, s37
	v_cvt_pk_bf16_f32 v14, v28, v29
	s_add_i32 s18, s18, s33
	v_cvt_pk_bf16_f32 v15, v30, v31
	v_add_u32_e32 v2, s18, v77
	v_ashrrev_i32_e32 v3, 31, v2
	v_lshl_add_u64 v[16:17], s[12:13], 1, v[0:1]
	v_lshlrev_b64 v[20:21], 12, v[2:3]
	v_lshl_add_u64 v[20:21], v[16:17], 0, v[20:21]
	ds_read2_b32 v[24:25], v78 offset0:16 offset1:81
	ds_read2_b32 v[26:27], v78 offset0:146 offset1:211
	ds_read2_b32 v[28:29], v22 offset0:20 offset1:85
	ds_read2_b32 v[30:31], v22 offset0:150 offset1:215
	s_waitcnt lgkmcnt(4)
	global_store_dwordx4 v[20:21], v[12:15], off
	s_nop 1
	v_readlane_b32 s12, v254, 25
	s_add_i32 s14, s14, s12
	v_cvt_pk_bf16_f32 v12, v32, v33
	v_cvt_pk_bf16_f32 v13, v34, v35
	v_cvt_pk_bf16_f32 v14, v36, v37
	v_cvt_pk_bf16_f32 v15, v38, v39
	v_add_u32_e32 v18, 8, v2
	v_ashrrev_i32_e32 v19, 31, v18
	v_lshlrev_b64 v[18:19], 12, v[18:19]
	v_lshl_add_u64 v[18:19], v[16:17], 0, v[18:19]
	ds_read2_b32 v[32:33], v78 offset0:24 offset1:89
	ds_read2_b32 v[34:35], v78 offset0:154 offset1:219
	ds_read2_b32 v[36:37], v22 offset0:28 offset1:93
	ds_read2_b32 v[38:39], v22 offset0:158 offset1:223
	s_waitcnt lgkmcnt(4)
	global_store_dwordx4 v[18:19], v[12:15], off
	s_nop 1
	s_add_i32 s33, s33, s36
	s_cmp_ge_i32 s14, s15
	v_cvt_pk_bf16_f32 v12, v24, v25
	v_cvt_pk_bf16_f32 v13, v26, v27
	v_cvt_pk_bf16_f32 v14, v28, v29
	v_cvt_pk_bf16_f32 v15, v30, v31
	v_add_u32_e32 v18, 16, v2
	v_ashrrev_i32_e32 v19, 31, v18
	v_lshlrev_b64 v[18:19], 12, v[18:19]
	v_lshl_add_u64 v[18:19], v[16:17], 0, v[18:19]
	ds_read2_b32 v[24:25], v78 offset0:32 offset1:97
	ds_read2_b32 v[26:27], v78 offset0:162 offset1:227
	ds_read2_b32 v[28:29], v22 offset0:36 offset1:101
	ds_read2_b32 v[30:31], v22 offset0:166 offset1:231
	s_waitcnt lgkmcnt(4)
	global_store_dwordx4 v[18:19], v[12:15], off
	s_nop 1
	s_nop 0
	v_cvt_pk_bf16_f32 v12, v32, v33
	v_cvt_pk_bf16_f32 v13, v34, v35
	v_cvt_pk_bf16_f32 v14, v36, v37
	v_cvt_pk_bf16_f32 v15, v38, v39
	v_add_u32_e32 v18, 24, v2
	v_ashrrev_i32_e32 v19, 31, v18
	v_lshlrev_b64 v[18:19], 12, v[18:19]
	v_lshl_add_u64 v[18:19], v[16:17], 0, v[18:19]
	ds_read2_b32 v[32:33], v78 offset0:40 offset1:105
	ds_read2_b32 v[34:35], v78 offset0:170 offset1:235
	ds_read2_b32 v[36:37], v22 offset0:44 offset1:109
	ds_read2_b32 v[38:39], v22 offset0:174 offset1:239
	s_waitcnt lgkmcnt(4)
	global_store_dwordx4 v[18:19], v[12:15], off
	s_nop 1
	s_nop 0
	v_cvt_pk_bf16_f32 v12, v24, v25
	v_cvt_pk_bf16_f32 v13, v26, v27
	v_cvt_pk_bf16_f32 v14, v28, v29
	v_cvt_pk_bf16_f32 v15, v30, v31
	v_add_u32_e32 v18, 32, v2
	v_ashrrev_i32_e32 v19, 31, v18
	v_lshlrev_b64 v[18:19], 12, v[18:19]
	v_lshl_add_u64 v[18:19], v[16:17], 0, v[18:19]
	ds_read2_b32 v[24:25], v78 offset0:48 offset1:113
	ds_read2_b32 v[26:27], v78 offset0:178 offset1:243
	ds_read2_b32 v[28:29], v22 offset0:52 offset1:117
	ds_read2_b32 v[30:31], v22 offset0:182 offset1:247
	s_waitcnt lgkmcnt(4)
	global_store_dwordx4 v[18:19], v[12:15], off
	s_nop 1
	s_nop 0
	v_cvt_pk_bf16_f32 v12, v32, v33
	v_cvt_pk_bf16_f32 v13, v34, v35
	v_cvt_pk_bf16_f32 v14, v36, v37
	v_cvt_pk_bf16_f32 v15, v38, v39
	v_add_u32_e32 v18, 40, v2
	v_ashrrev_i32_e32 v19, 31, v18
	v_lshlrev_b64 v[18:19], 12, v[18:19]
	ds_read2_b32 v[32:33], v78 offset0:56 offset1:121
	ds_read2_b32 v[34:35], v78 offset0:186 offset1:251
	ds_read2_b32 v[36:37], v22 offset0:60 offset1:125
	ds_read2_b32 v[38:39], v22 offset0:190 offset1:255
	s_waitcnt lgkmcnt(4)
	v_lshl_add_u64 v[18:19], v[16:17], 0, v[18:19]
	global_store_dwordx4 v[18:19], v[12:15], off
	s_nop 1
	s_nop 0
	v_cvt_pk_bf16_f32 v12, v24, v25
	v_add_u32_e32 v20, 48, v2
	v_ashrrev_i32_e32 v21, 31, v20
	v_cvt_pk_bf16_f32 v13, v26, v27
	v_lshlrev_b64 v[20:21], 12, v[20:21]
	v_add_u32_e32 v2, 56, v2
	v_cvt_pk_bf16_f32 v14, v28, v29
	v_cvt_pk_bf16_f32 v15, v30, v31
	v_lshl_add_u64 v[20:21], v[16:17], 0, v[20:21]
	v_ashrrev_i32_e32 v3, 31, v2
	s_waitcnt lgkmcnt(0)
	global_store_dwordx4 v[20:21], v[12:15], off
	s_nop 1
	v_lshlrev_b64 v[2:3], 12, v[2:3]
	v_lshl_add_u64 v[2:3], v[16:17], 0, v[2:3]
	v_cvt_pk_bf16_f32 v12, v32, v33
	v_cvt_pk_bf16_f32 v13, v34, v35
	v_cvt_pk_bf16_f32 v14, v36, v37
	v_cvt_pk_bf16_f32 v15, v38, v39
	global_store_dwordx4 v[2:3], v[12:15], off
	s_nop 1
	s_waitcnt lgkmcnt(0)
	s_cbranch_scc1 .LBB0_379

; __device__ __forceinline__ void transpose_item(const float* __restrict__ W, int K, int N, bf16_t* __restrict__ WT, int drow0, LAS float* scr, int k0, int n0, int lane, const float* __restrict__ gk) {
;     const float* src = W + (size_t)k0 * N + n0 + lane;
; #pragma unroll
;     for (int hb = 0; hb < 1; ++hb) {
;         float v[64];
; #pragma unroll
;         for (int i = 0; i < 64; ++i) v[i] = __builtin_nontemporal_load(src + (size_t)(hb * 64 + i) * N);
; __device__ __forceinline__ void transpose_matrix(const float* W, int K, int N, bf16_t* WT, int mode, LAS float* scr, int gw, int NGW, int lane, const float* gA, const float* gB, int it_lo, int it_hi) {
;     ...
;     for (int j = (it_lo >> 3) + (gw >> 3); j < (it_hi >> 3); j += (NGW >> 3)) {
;         const int kb = (j / nblk) * 8 + w8, nb = j % nblk, n0 = nb * 64;
;         int drow0 = n0;
;         if (mode) { const int up = n0 >= DFF, j = n0 - up * DFF; drow0 = 256 * (j / 128) + (j % 128) + up * 128; }
;         transpose_item(W, K, N, WT, drow0, scr, kb * 64, n0, lane, gA ? (kb * 64 < 1024 ? gA : gB - 1024) : nullptr);
.LBB0_383:
	s_ashr_i32 s6, s8, 31
	s_lshr_b32 s6, s6, 27
	s_add_i32 s6, s8, s6
	s_ashr_i32 s14, s6, 5
	s_lshl_b32 s6, s14, 11
	s_sub_i32 s16, s12, s6
	s_lshl_b32 s6, s14, 9
	s_or_b32 s6, s6, s29
	s_ashr_i32 s7, s6, 31
	s_lshl_b64 s[18:19], s[6:7], 13
	s_add_u32 s15, s10, s18
	s_addc_u32 s18, s11, s19
	s_ashr_i32 s17, s16, 31
	s_lshl_b64 s[16:17], s[16:17], 2
	s_add_u32 s16, s15, s16
	s_addc_u32 s17, s18, s17
	v_lshl_add_u64 v[70:71], s[16:17], 0, v[112:113]
	v_add_co_u32_e32 v0, vcc, s37, v70
	global_load_dword v74, v112, s[16:17] nt
	s_nop 0
	v_addc_co_u32_e32 v1, vcc, 0, v71, vcc
	global_load_dword v75, v[0:1], off nt
	v_add_co_u32_e32 v0, vcc, s33, v70
	s_mul_i32 s14, s14, 0xff500000
	s_nop 0
	v_addc_co_u32_e32 v1, vcc, 0, v71, vcc
	global_load_dword v87, v[0:1], off nt
	v_add_co_u32_e32 v0, vcc, s48, v70
	s_add_i32 s8, s8, s27
	s_nop 0
	v_addc_co_u32_e32 v1, vcc, 0, v71, vcc
	global_load_dword v88, v[0:1], off nt
	v_add_co_u32_e32 v0, vcc, s50, v70
	s_add_i32 s12, s12, s13
	s_nop 0
	v_addc_co_u32_e32 v1, vcc, 0, v71, vcc
	v_add_co_u32_e32 v2, vcc, s51, v70
	global_load_dword v0, v[0:1], off nt
	s_nop 0
	v_addc_co_u32_e32 v3, vcc, 0, v71, vcc
	v_add_co_u32_e32 v14, vcc, s36, v70
	global_load_dword v3, v[2:3], off nt
	s_nop 0
	v_addc_co_u32_e32 v15, vcc, 0, v71, vcc
	global_load_dword v17, v[14:15], off nt
	v_add_co_u32_e32 v14, vcc, s54, v70
	s_cmp_ge_i32 s8, s9
	s_nop 0
	v_addc_co_u32_e32 v15, vcc, 0, v71, vcc
	global_load_dword v27, v[14:15], off nt
	v_add_co_u32_e32 v14, vcc, s24, v70
	s_nop 1
	v_addc_co_u32_e32 v15, vcc, 0, v71, vcc
	global_load_dword v1, v[14:15], off nt
	v_add_co_u32_e32 v14, vcc, s38, v70
	s_nop 1
	v_addc_co_u32_e32 v15, vcc, 0, v71, vcc
	v_add_co_u32_e32 v20, vcc, s46, v70
	global_load_dword v15, v[14:15], off nt
	s_nop 0
	v_addc_co_u32_e32 v21, vcc, 0, v71, vcc
	v_add_co_u32_e32 v22, vcc, s47, v70
	global_load_dword v21, v[20:21], off nt
	s_nop 0
	v_addc_co_u32_e32 v23, vcc, 0, v71, vcc
	global_load_dword v31, v[22:23], off nt
	v_add_co_u32_e32 v22, vcc, s25, v70
	s_nop 1
	v_addc_co_u32_e32 v23, vcc, 0, v71, vcc
	global_load_dword v2, v[22:23], off nt
	v_add_co_u32_e32 v22, vcc, s49, v70
	s_nop 1
	v_addc_co_u32_e32 v23, vcc, 0, v71, vcc
	global_load_dword v19, v[22:23], off nt
	v_add_co_u32_e32 v22, vcc, s52, v70
	s_nop 1
	v_addc_co_u32_e32 v23, vcc, 0, v71, vcc
	global_load_dword v24, v[22:23], off nt
	v_add_co_u32_e32 v22, vcc, s53, v70
	s_nop 1
	v_addc_co_u32_e32 v23, vcc, 0, v71, vcc
	global_load_dword v35, v[22:23], off nt
	v_add_co_u32_e32 v22, vcc, s55, v70
	s_nop 1
	v_addc_co_u32_e32 v23, vcc, 0, v71, vcc
	global_load_dword v14, v[22:23], off nt
	v_add_co_u32_e32 v22, vcc, s56, v70
	s_nop 1
	v_addc_co_u32_e32 v23, vcc, 0, v71, vcc
	v_add_co_u32_e32 v28, vcc, s57, v70
	global_load_dword v22, v[22:23], off nt
	s_nop 0
	v_addc_co_u32_e32 v29, vcc, 0, v71, vcc
	v_add_co_u32_e32 v32, vcc, s58, v70
	global_load_dword v28, v[28:29], off nt
	s_nop 0
	v_addc_co_u32_e32 v33, vcc, 0, v71, vcc
	global_load_dword v39, v[32:33], off nt
	v_add_co_u32_e32 v32, vcc, s59, v70
	s_nop 1
	v_addc_co_u32_e32 v33, vcc, 0, v71, vcc
	global_load_dword v16, v[32:33], off nt
	v_add_co_u32_e32 v32, vcc, s60, v70
	s_nop 1
	v_addc_co_u32_e32 v33, vcc, 0, v71, vcc
	global_load_dword v25, v[32:33], off nt
	v_add_co_u32_e32 v32, vcc, s61, v70
	s_nop 1
	v_addc_co_u32_e32 v33, vcc, 0, v71, vcc
	v_add_co_u32_e32 v36, vcc, s62, v70
	global_load_dword v32, v[32:33], off nt
	s_nop 0
	v_addc_co_u32_e32 v37, vcc, 0, v71, vcc
	global_load_dword v43, v[36:37], off nt
	v_add_co_u32_e32 v36, vcc, s63, v70
	s_nop 1
	v_addc_co_u32_e32 v37, vcc, 0, v71, vcc
	global_load_dword v20, v[36:37], off nt
	v_add_co_u32_e32 v36, vcc, s64, v70
	s_nop 1
	v_addc_co_u32_e32 v37, vcc, 0, v71, vcc
	global_load_dword v29, v[36:37], off nt
	v_add_co_u32_e32 v36, vcc, s65, v70
	s_nop 1
	v_addc_co_u32_e32 v37, vcc, 0, v71, vcc
	v_add_co_u32_e32 v40, vcc, s66, v70
	global_load_dword v36, v[36:37], off nt
	s_nop 0
	v_addc_co_u32_e32 v41, vcc, 0, v71, vcc
	global_load_dword v47, v[40:41], off nt
	v_add_co_u32_e32 v40, vcc, s67, v70
	s_nop 1
	v_addc_co_u32_e32 v41, vcc, 0, v71, vcc
	global_load_dword v23, v[40:41], off nt
	v_add_co_u32_e32 v40, vcc, s68, v70
	s_nop 1
	v_addc_co_u32_e32 v41, vcc, 0, v71, vcc
	global_load_dword v33, v[40:41], off nt
	v_add_co_u32_e32 v40, vcc, s73, v70
	s_nop 1
	v_addc_co_u32_e32 v41, vcc, 0, v71, vcc
	v_add_co_u32_e32 v44, vcc, s74, v70
	global_load_dword v40, v[40:41], off nt
	s_nop 0
	v_addc_co_u32_e32 v45, vcc, 0, v71, vcc
	global_load_dword v51, v[44:45], off nt
	v_add_co_u32_e32 v44, vcc, s75, v70
	s_nop 1
	v_addc_co_u32_e32 v45, vcc, 0, v71, vcc
	global_load_dword v26, v[44:45], off nt
	v_add_co_u32_e32 v44, vcc, s76, v70
	s_nop 1
	v_addc_co_u32_e32 v45, vcc, 0, v71, vcc
	global_load_dword v37, v[44:45], off nt
	v_add_co_u32_e32 v44, vcc, s77, v70
	s_nop 1
	v_addc_co_u32_e32 v45, vcc, 0, v71, vcc
	v_add_co_u32_e32 v48, vcc, s78, v70
	global_load_dword v44, v[44:45], off nt
	s_nop 0
	v_addc_co_u32_e32 v49, vcc, 0, v71, vcc
	global_load_dword v55, v[48:49], off nt
	v_add_co_u32_e32 v48, vcc, s79, v70
	s_nop 1
	v_addc_co_u32_e32 v49, vcc, 0, v71, vcc
	global_load_dword v30, v[48:49], off nt
	v_add_co_u32_e32 v48, vcc, s80, v70
	s_nop 1
	v_addc_co_u32_e32 v49, vcc, 0, v71, vcc
	global_load_dword v41, v[48:49], off nt
	v_add_co_u32_e32 v48, vcc, s81, v70
	s_nop 1
	v_addc_co_u32_e32 v49, vcc, 0, v71, vcc
	v_add_co_u32_e32 v52, vcc, s82, v70
	global_load_dword v48, v[48:49], off nt
	s_nop 0
	v_addc_co_u32_e32 v53, vcc, 0, v71, vcc
	global_load_dword v58, v[52:53], off nt
	v_add_co_u32_e32 v52, vcc, s83, v70
	s_nop 1
	v_addc_co_u32_e32 v53, vcc, 0, v71, vcc
; __device__ __forceinline__ void transpose_item(const float* __restrict__ W, int K, int N, bf16_t* __restrict__ WT, int drow0, LAS float* scr, int k0, int n0, int lane, const float* __restrict__ gk) {
;     ...
;         for (int i = 0; i < 64; ++i) v[i] = __builtin_nontemporal_load(src + (size_t)(hb * 64 + i) * N);
;         if (gk) {
; #pragma unroll
;             for (int i = 0; i < 64; ++i) v[i] *= gk[k0 + hb * 64 + i];
;         }
; #pragma unroll
;         for (int i = 0; i < 64; ++i) scr[(hb * 64 + i) * 65 + lane] = v[i];
;     }
;     asm volatile("s_waitcnt lgkmcnt(0)" ::: "memory");
	global_load_dword v34, v[52:53], off nt
	v_add_co_u32_e32 v52, vcc, s84, v70
	s_nop 1
	v_addc_co_u32_e32 v53, vcc, 0, v71, vcc
	global_load_dword v45, v[52:53], off nt
	v_add_co_u32_e32 v52, vcc, s85, v70
	s_nop 1
	v_addc_co_u32_e32 v53, vcc, 0, v71, vcc
	v_add_co_u32_e32 v56, vcc, s86, v70
	global_load_dword v52, v[52:53], off nt
	s_nop 0
	v_addc_co_u32_e32 v57, vcc, 0, v71, vcc
	global_load_dword v61, v[56:57], off nt
	v_add_co_u32_e32 v56, vcc, s87, v70
	s_nop 1
	v_addc_co_u32_e32 v57, vcc, 0, v71, vcc
	global_load_dword v38, v[56:57], off nt
	v_add_co_u32_e32 v56, vcc, s88, v70
	s_nop 1
	v_addc_co_u32_e32 v57, vcc, 0, v71, vcc
	global_load_dword v49, v[56:57], off nt
	v_add_co_u32_e32 v56, vcc, s89, v70
	s_nop 1
	v_addc_co_u32_e32 v57, vcc, 0, v71, vcc
	v_add_co_u32_e32 v62, vcc, s90, v70
	global_load_dword v56, v[56:57], off nt
	s_nop 0
	v_addc_co_u32_e32 v63, vcc, 0, v71, vcc
	global_load_dword v64, v[62:63], off nt
	v_add_co_u32_e32 v62, vcc, s91, v70
	s_nop 1
	v_addc_co_u32_e32 v63, vcc, 0, v71, vcc
	global_load_dword v42, v[62:63], off nt
	v_add_co_u32_e32 v62, vcc, s92, v70
	s_nop 1
	v_addc_co_u32_e32 v63, vcc, 0, v71, vcc
	global_load_dword v53, v[62:63], off nt
	v_add_co_u32_e32 v62, vcc, s93, v70
	s_nop 1
	v_addc_co_u32_e32 v63, vcc, 0, v71, vcc
	global_load_dword v59, v[62:63], off nt
	v_add_co_u32_e32 v62, vcc, s94, v70
	s_nop 1
	v_addc_co_u32_e32 v63, vcc, 0, v71, vcc
	global_load_dword v66, v[62:63], off nt
	v_add_co_u32_e32 v62, vcc, s95, v70
	s_nop 1
	v_addc_co_u32_e32 v63, vcc, 0, v71, vcc
	global_load_dword v46, v[62:63], off nt
	v_add_co_u32_e32 v62, vcc, s96, v70
	s_nop 1
	v_addc_co_u32_e32 v63, vcc, 0, v71, vcc
	global_load_dword v57, v[62:63], off nt
	v_add_co_u32_e32 v62, vcc, s97, v70
	s_nop 1
	v_addc_co_u32_e32 v63, vcc, 0, v71, vcc
	v_add_co_u32_e32 v68, vcc, s71, v70
	global_load_dword v62, v[62:63], off nt
	s_nop 0
	v_addc_co_u32_e32 v69, vcc, 0, v71, vcc
	v_add_co_u32_e32 v72, vcc, s39, v70
	global_load_dword v68, v[68:69], off nt
	s_nop 0
	v_addc_co_u32_e32 v73, vcc, 0, v71, vcc
	global_load_dword v50, v[72:73], off nt
	v_add_co_u32_e32 v72, vcc, s72, v70
	s_nop 1
	v_addc_co_u32_e32 v73, vcc, 0, v71, vcc
	global_load_dword v60, v[72:73], off nt
	v_add_co_u32_e32 v72, vcc, s28, v70
	s_nop 1
	v_addc_co_u32_e32 v73, vcc, 0, v71, vcc
	global_load_dword v65, v[72:73], off nt
	v_add_co_u32_e32 v72, vcc, s69, v70
	s_nop 1
	v_addc_co_u32_e32 v73, vcc, 0, v71, vcc
	global_load_dword v69, v[72:73], off nt
	v_add_co_u32_e32 v72, vcc, s30, v70
	s_nop 1
	v_addc_co_u32_e32 v73, vcc, 0, v71, vcc
	global_load_dword v54, v[72:73], off nt
	v_add_co_u32_e32 v72, vcc, s43, v70
	s_nop 1
	v_addc_co_u32_e32 v73, vcc, 0, v71, vcc
	global_load_dword v63, v[72:73], off nt
	v_add_co_u32_e32 v72, vcc, s22, v70
	s_nop 1
	v_addc_co_u32_e32 v73, vcc, 0, v71, vcc
	v_add_co_u32_e32 v70, vcc, s23, v70
	global_load_dword v67, v[72:73], off nt
	s_nop 0
	v_addc_co_u32_e32 v71, vcc, 0, v71, vcc
	global_load_dword v70, v[70:71], off nt
	v_add_u32_e32 v71, 0x400, v76
	s_waitcnt vmcnt(0)
	ds_write2_b32 v76, v74, v75 offset1:65
	ds_write2_b32 v76, v87, v88 offset0:130 offset1:195
	ds_write2_b32 v71, v0, v3 offset0:4 offset1:69
	ds_write2_b32 v71, v17, v27 offset0:134 offset1:199
	v_add_u32_e32 v0, 0x800, v76
	ds_write2_b32 v0, v1, v15 offset0:8 offset1:73
	ds_write2_b32 v0, v21, v31 offset0:138 offset1:203
	v_add_u32_e32 v0, 0xc00, v76
	ds_write2_b32 v0, v2, v19 offset0:12 offset1:77
	ds_write2_b32 v0, v24, v35 offset0:142 offset1:207
	v_add_u32_e32 v0, 0x1000, v76
	ds_write2_b32 v0, v14, v22 offset0:16 offset1:81
	ds_write2_b32 v0, v28, v39 offset0:146 offset1:211
	v_add_u32_e32 v0, 0x1400, v76
	ds_write2_b32 v0, v16, v25 offset0:20 offset1:85
	ds_write2_b32 v0, v32, v43 offset0:150 offset1:215
	v_add_u32_e32 v0, 0x1800, v76
	ds_write2_b32 v0, v20, v29 offset0:24 offset1:89
	ds_write2_b32 v0, v36, v47 offset0:154 offset1:219
	v_add_u32_e32 v0, 0x1c00, v76
	ds_write2_b32 v0, v23, v33 offset0:28 offset1:93
	ds_write2_b32 v0, v40, v51 offset0:158 offset1:223
	v_add_u32_e32 v0, 0x2000, v76
	ds_write2_b32 v0, v26, v37 offset0:32 offset1:97
	ds_write2_b32 v0, v44, v55 offset0:162 offset1:227
	v_add_u32_e32 v0, 0x2400, v76
	ds_write2_b32 v0, v30, v41 offset0:36 offset1:101
	ds_write2_b32 v0, v48, v58 offset0:166 offset1:231
	v_add_u32_e32 v0, 0x2800, v76
	ds_write2_b32 v0, v34, v45 offset0:40 offset1:105
	ds_write2_b32 v0, v52, v61 offset0:170 offset1:235
	v_add_u32_e32 v0, 0x2c00, v76
	ds_write2_b32 v0, v38, v49 offset0:44 offset1:109
	ds_write2_b32 v0, v56, v64 offset0:174 offset1:239
	v_add_u32_e32 v0, 0x3000, v76
	ds_write2_b32 v0, v42, v53 offset0:48 offset1:113
	ds_write2_b32 v0, v59, v66 offset0:178 offset1:243
	v_add_u32_e32 v0, 0x3400, v76
	ds_write2_b32 v0, v46, v57 offset0:52 offset1:117
	ds_write2_b32 v0, v62, v68 offset0:182 offset1:247
	v_add_u32_e32 v0, 0x3800, v76
	ds_write2_b32 v0, v50, v60 offset0:56 offset1:121
	ds_write2_b32 v0, v65, v69 offset0:186 offset1:251
	v_add_u32_e32 v0, 0x3c00, v76
	ds_write2_b32 v0, v54, v63 offset0:60 offset1:125
	ds_write2_b32 v0, v67, v70 offset0:190 offset1:255
	s_waitcnt lgkmcnt(0)
; #define LAS __attribute__((address_space(3)))
; __device__ __forceinline__ unsigned pk2(float lo, float hi) { unsigned r; asm volatile("v_cvt_pk_bf16_f32 %0, %1, %2" : "=v"(r) : "v"(lo), "v"(hi)); return r; }
; __device__ __forceinline__ void transpose_item(const float* __restrict__ W, int K, int N, bf16_t* __restrict__ WT, int drow0, LAS float* scr, int k0, int n0, int lane, const float* __restrict__ gk) {
;     ...
;     asm volatile("s_waitcnt lgkmcnt(0)" ::: "memory");
;     const int c = lane & 7;
; #pragma unroll
;     for (int j = 0; j < 8; ++j) { const int n = (lane >> 3) + 8 * j; const LAS float* s = scr + (8 * c) * 65 + n;
;         u32x4 o; o.x = pk2(s[0 * 65], s[1 * 65]); o.y = pk2(s[2 * 65], s[3 * 65]); o.z = pk2(s[4 * 65], s[5 * 65]); o.w = pk2(s[6 * 65], s[7 * 65]);
;         *(u32x4*)(WT + (size_t)(drow0 + n) * K + k0 + 8 * c) = o; }
;     asm volatile("s_waitcnt lgkmcnt(0)" ::: "memory");
	v_add_u32_e32 v19, 0x400, v78
	ds_read2_b32 v[22:23], v78 offset1:65
	ds_read2_b32 v[24:25], v78 offset0:130 offset1:195
	ds_read2_b32 v[26:27], v19 offset0:4 offset1:69
	ds_read2_b32 v[28:29], v19 offset0:134 offset1:199
	ds_read2_b32 v[30:31], v78 offset0:8 offset1:73
	ds_read2_b32 v[32:33], v78 offset0:138 offset1:203
	ds_read2_b32 v[34:35], v19 offset0:12 offset1:77
	ds_read2_b32 v[36:37], v19 offset0:142 offset1:207
	s_waitcnt lgkmcnt(4)
	v_cvt_pk_bf16_f32 v0, v22, v23
	v_cvt_pk_bf16_f32 v1, v24, v25
	v_cvt_pk_bf16_f32 v2, v26, v27
	v_cvt_pk_bf16_f32 v3, v28, v29
	v_add_u32_e32 v16, s14, v18
	v_lshl_add_u64 v[14:15], s[6:7], 1, v[12:13]
	v_ashrrev_i32_e32 v17, 31, v16
	v_lshl_add_u64 v[20:21], v[16:17], 1, v[14:15]
	global_store_dwordx4 v[20:21], v[0:3], off
	s_nop 1
	ds_read2_b32 v[22:23], v78 offset0:16 offset1:81
	ds_read2_b32 v[24:25], v78 offset0:146 offset1:211
	ds_read2_b32 v[26:27], v19 offset0:20 offset1:85
	ds_read2_b32 v[28:29], v19 offset0:150 offset1:215
	s_waitcnt lgkmcnt(4)
	s_mul_i32 s6, s27, 0x58000
	v_cvt_pk_bf16_f32 v0, v30, v31
	v_cvt_pk_bf16_f32 v1, v32, v33
	v_cvt_pk_bf16_f32 v2, v34, v35
	v_cvt_pk_bf16_f32 v3, v36, v37
	v_add_u32_e32 v20, 0xb000, v16
	v_ashrrev_i32_e32 v21, 31, v20
	v_lshl_add_u64 v[20:21], v[20:21], 1, v[14:15]
	global_store_dwordx4 v[20:21], v[0:3], off
	s_nop 1
	ds_read2_b32 v[30:31], v78 offset0:24 offset1:89
	ds_read2_b32 v[32:33], v78 offset0:154 offset1:219
	ds_read2_b32 v[34:35], v19 offset0:28 offset1:93
	ds_read2_b32 v[36:37], v19 offset0:158 offset1:223
	s_waitcnt lgkmcnt(4)
	v_add_u32_e32 v18, s6, v18
	v_cvt_pk_bf16_f32 v0, v22, v23
	v_cvt_pk_bf16_f32 v1, v24, v25
	v_cvt_pk_bf16_f32 v2, v26, v27
	v_cvt_pk_bf16_f32 v3, v28, v29
	v_add_u32_e32 v20, 0x16000, v16
	v_ashrrev_i32_e32 v21, 31, v20
	v_lshl_add_u64 v[20:21], v[20:21], 1, v[14:15]
	global_store_dwordx4 v[20:21], v[0:3], off
	s_nop 1
	ds_read2_b32 v[22:23], v78 offset0:32 offset1:97
	ds_read2_b32 v[24:25], v78 offset0:162 offset1:227
	ds_read2_b32 v[26:27], v19 offset0:36 offset1:101
	ds_read2_b32 v[28:29], v19 offset0:166 offset1:231
	s_waitcnt lgkmcnt(4)
	v_cvt_pk_bf16_f32 v0, v30, v31
	v_cvt_pk_bf16_f32 v1, v32, v33
	v_cvt_pk_bf16_f32 v2, v34, v35
	v_cvt_pk_bf16_f32 v3, v36, v37
	v_add_u32_e32 v20, 0x21000, v16
	v_ashrrev_i32_e32 v21, 31, v20
	v_lshl_add_u64 v[20:21], v[20:21], 1, v[14:15]
	global_store_dwordx4 v[20:21], v[0:3], off
	s_nop 1
	ds_read2_b32 v[30:31], v78 offset0:40 offset1:105
	ds_read2_b32 v[32:33], v78 offset0:170 offset1:235
	ds_read2_b32 v[34:35], v19 offset0:44 offset1:109
	ds_read2_b32 v[36:37], v19 offset0:174 offset1:239
	s_waitcnt lgkmcnt(4)
	v_cvt_pk_bf16_f32 v0, v22, v23
	v_cvt_pk_bf16_f32 v1, v24, v25
	v_cvt_pk_bf16_f32 v2, v26, v27
	v_cvt_pk_bf16_f32 v3, v28, v29
	v_add_u32_e32 v20, 0x2c000, v16
	v_ashrrev_i32_e32 v21, 31, v20
	v_lshl_add_u64 v[20:21], v[20:21], 1, v[14:15]
	global_store_dwordx4 v[20:21], v[0:3], off
	s_nop 1
	ds_read2_b32 v[22:23], v78 offset0:48 offset1:113
	ds_read2_b32 v[24:25], v78 offset0:178 offset1:243
	ds_read2_b32 v[26:27], v19 offset0:52 offset1:117
	ds_read2_b32 v[28:29], v19 offset0:182 offset1:247
	s_waitcnt lgkmcnt(4)
	v_cvt_pk_bf16_f32 v0, v30, v31
	v_cvt_pk_bf16_f32 v1, v32, v33
	v_cvt_pk_bf16_f32 v2, v34, v35
	v_cvt_pk_bf16_f32 v3, v36, v37
	v_add_u32_e32 v20, 0x37000, v16
	v_ashrrev_i32_e32 v21, 31, v20
	v_lshl_add_u64 v[20:21], v[20:21], 1, v[14:15]
	global_store_dwordx4 v[20:21], v[0:3], off
	s_nop 1
	ds_read2_b32 v[30:31], v78 offset0:56 offset1:121
	ds_read2_b32 v[32:33], v78 offset0:186 offset1:251
	ds_read2_b32 v[34:35], v19 offset0:60 offset1:125
	ds_read2_b32 v[36:37], v19 offset0:190 offset1:255
	s_waitcnt lgkmcnt(4)
	v_cvt_pk_bf16_f32 v0, v22, v23
	v_cvt_pk_bf16_f32 v1, v24, v25
	v_cvt_pk_bf16_f32 v2, v26, v27
	v_cvt_pk_bf16_f32 v3, v28, v29
	v_add_u32_e32 v20, 0x42000, v16
	v_ashrrev_i32_e32 v21, 31, v20
	v_lshl_add_u64 v[20:21], v[20:21], 1, v[14:15]
	global_store_dwordx4 v[20:21], v[0:3], off
	s_nop 1
	s_waitcnt lgkmcnt(0)
	v_add_u32_e32 v16, 0x4d000, v16
	v_cvt_pk_bf16_f32 v0, v30, v31
	v_ashrrev_i32_e32 v17, 31, v16
	v_cvt_pk_bf16_f32 v1, v32, v33
	v_lshl_add_u64 v[14:15], v[16:17], 1, v[14:15]
	v_cvt_pk_bf16_f32 v2, v34, v35
	v_cvt_pk_bf16_f32 v3, v36, v37
	global_store_dwordx4 v[14:15], v[0:3], off
	s_nop 1
	s_waitcnt lgkmcnt(0)
	s_cbranch_scc0 .LBB0_383

; __device__ __forceinline__ void transpose_item(const float* __restrict__ W, int K, int N, bf16_t* __restrict__ WT, int drow0, LAS float* scr, int k0, int n0, int lane, const float* __restrict__ gk) {
;     const float* src = W + (size_t)k0 * N + n0 + lane;
; #pragma unroll
;     for (int hb = 0; hb < 1; ++hb) {
;         float v[64];
; #pragma unroll
;         for (int i = 0; i < 64; ++i) v[i] = __builtin_nontemporal_load(src + (size_t)(hb * 64 + i) * N);
; __device__ __forceinline__ void transpose_matrix(const float* W, int K, int N, bf16_t* WT, int mode, LAS float* scr, int gw, int NGW, int lane, const float* gA, const float* gB, int it_lo, int it_hi) {
;     ...
;     for (int j = (it_lo >> 3) + (gw >> 3); j < (it_hi >> 3); j += (NGW >> 3)) {
;         const int kb = (j / nblk) * 8 + w8, nb = j % nblk, n0 = nb * 64;
;         int drow0 = n0;
;         if (mode) { const int up = n0 >= DFF, j = n0 - up * DFF; drow0 = 256 * (j / 128) + (j % 128) + up * 128; }
;         transpose_item(W, K, N, WT, drow0, scr, kb * 64, n0, lane, gA ? (kb * 64 < 1024 ? gA : gB - 1024) : nullptr);
.LBB0_387:
	s_mul_hi_i32 s6, s10, 0x38e38e39
	s_lshr_b32 s7, s6, 31
	s_ashr_i32 s6, s6, 4
	s_add_i32 s7, s6, s7
	s_mul_i32 s6, s7, 0xffffee00
	s_lshl_b32 s7, s7, 9
	s_or_b32 s8, s7, s29
	s_add_i32 s6, s14, s6
	s_ashr_i32 s9, s8, 31
	s_mul_i32 s16, s8, 0x4800
	s_mul_hi_i32 s7, s8, 0x4800
	s_add_u32 s18, s12, s16
	s_addc_u32 s19, s13, s7
	s_ashr_i32 s7, s6, 31
	s_lshl_b64 s[16:17], s[6:7], 2
	s_add_u32 s16, s18, s16
	s_addc_u32 s17, s19, s17
	v_lshl_add_u64 v[70:71], s[16:17], 0, v[112:113]
	v_add_co_u32_e32 v0, vcc, s24, v70
	global_load_dword v74, v112, s[16:17] nt
	s_nop 0
	v_addc_co_u32_e32 v1, vcc, 0, v71, vcc
	global_load_dword v75, v[0:1], off offset:2048 nt
	v_add_co_u32_e32 v0, vcc, s30, v70
	s_add_i32 s10, s10, s27
	s_nop 0
	v_addc_co_u32_e32 v1, vcc, 0, v71, vcc
	global_load_dword v87, v[0:1], off nt
	v_add_co_u32_e32 v0, vcc, s22, v70
	s_add_i32 s14, s14, s15
	s_nop 0
	v_addc_co_u32_e32 v1, vcc, 0, v71, vcc
	global_load_dword v88, v[0:1], off offset:2048 nt
	v_add_co_u32_e32 v0, vcc, s33, v70
	s_cmp_ge_i32 s10, s11
	s_nop 0
	v_addc_co_u32_e32 v1, vcc, 0, v71, vcc
	v_add_co_u32_e32 v2, vcc, s36, v70
	global_load_dword v0, v[0:1], off nt
	s_nop 0
	v_addc_co_u32_e32 v3, vcc, 0, v71, vcc
	v_add_co_u32_e32 v14, vcc, s23, v70
	global_load_dword v3, v[2:3], off offset:2048 nt
	s_nop 0
	v_addc_co_u32_e32 v15, vcc, 0, v71, vcc
	global_load_dword v17, v[14:15], off nt
	v_add_co_u32_e32 v14, vcc, s28, v70
	s_nop 1
	v_addc_co_u32_e32 v15, vcc, 0, v71, vcc
	global_load_dword v26, v[14:15], off offset:2048 nt
	v_add_co_u32_e32 v14, vcc, s37, v70
	s_nop 1
	v_addc_co_u32_e32 v15, vcc, 0, v71, vcc
	global_load_dword v1, v[14:15], off nt
	v_add_co_u32_e32 v14, vcc, s38, v70
	s_nop 1
	v_addc_co_u32_e32 v15, vcc, 0, v71, vcc
	v_add_co_u32_e32 v18, vcc, s43, v70
	global_load_dword v15, v[14:15], off offset:2048 nt
	s_nop 0
	v_addc_co_u32_e32 v19, vcc, 0, v71, vcc
	global_load_dword v20, v[18:19], off nt
	v_add_co_u32_e32 v18, vcc, s53, v70
	s_nop 1
	v_addc_co_u32_e32 v19, vcc, 0, v71, vcc
	global_load_dword v30, v[18:19], off offset:2048 nt
	v_add_co_u32_e32 v18, vcc, s46, v70
	s_nop 1
	v_addc_co_u32_e32 v19, vcc, 0, v71, vcc
	global_load_dword v2, v[18:19], off nt
	v_add_co_u32_e32 v18, vcc, s47, v70
	s_nop 1
	v_addc_co_u32_e32 v19, vcc, 0, v71, vcc
	v_add_co_u32_e32 v22, vcc, s54, v70
	global_load_dword v18, v[18:19], off offset:2048 nt
	s_nop 0
	v_addc_co_u32_e32 v23, vcc, 0, v71, vcc
	v_add_co_u32_e32 v24, vcc, s55, v70
	global_load_dword v23, v[22:23], off nt
	s_nop 0
	v_addc_co_u32_e32 v25, vcc, 0, v71, vcc
	global_load_dword v34, v[24:25], off offset:2048 nt
	v_add_co_u32_e32 v24, vcc, s48, v70
	s_nop 1
	v_addc_co_u32_e32 v25, vcc, 0, v71, vcc
	global_load_dword v14, v[24:25], off nt
	v_add_co_u32_e32 v24, vcc, s49, v70
	s_nop 1
	v_addc_co_u32_e32 v25, vcc, 0, v71, vcc
	global_load_dword v21, v[24:25], off offset:2048 nt
	v_add_co_u32_e32 v24, vcc, s56, v70
	s_nop 1
	v_addc_co_u32_e32 v25, vcc, 0, v71, vcc
	global_load_dword v27, v[24:25], off nt
	v_add_co_u32_e32 v24, vcc, s57, v70
	s_nop 1
	v_addc_co_u32_e32 v25, vcc, 0, v71, vcc
	global_load_dword v38, v[24:25], off offset:2048 nt
	v_add_co_u32_e32 v24, vcc, s50, v70
	s_nop 1
	v_addc_co_u32_e32 v25, vcc, 0, v71, vcc
	global_load_dword v16, v[24:25], off nt
	v_add_co_u32_e32 v24, vcc, s51, v70
	s_nop 1
	v_addc_co_u32_e32 v25, vcc, 0, v71, vcc
	v_add_co_u32_e32 v28, vcc, s58, v70
	global_load_dword v24, v[24:25], off offset:2048 nt
	s_nop 0
	v_addc_co_u32_e32 v29, vcc, 0, v71, vcc
	global_load_dword v31, v[28:29], off nt
	v_add_co_u32_e32 v28, vcc, s59, v70
	s_nop 1
	v_addc_co_u32_e32 v29, vcc, 0, v71, vcc
	global_load_dword v42, v[28:29], off offset:2048 nt
	v_add_co_u32_e32 v28, vcc, s52, v70
	s_nop 1
	v_addc_co_u32_e32 v29, vcc, 0, v71, vcc
	global_load_dword v19, v[28:29], off nt
	v_add_co_u32_e32 v28, vcc, s71, v70
	s_nop 1
	v_addc_co_u32_e32 v29, vcc, 0, v71, vcc
	v_add_co_u32_e32 v32, vcc, s60, v70
	global_load_dword v28, v[28:29], off offset:2048 nt
	s_nop 0
	v_addc_co_u32_e32 v33, vcc, 0, v71, vcc
	global_load_dword v35, v[32:33], off nt
	v_add_co_u32_e32 v32, vcc, s61, v70
	s_nop 1
	v_addc_co_u32_e32 v33, vcc, 0, v71, vcc
	global_load_dword v46, v[32:33], off offset:2048 nt
	v_add_co_u32_e32 v32, vcc, s39, v70
	s_nop 1
	v_addc_co_u32_e32 v33, vcc, 0, v71, vcc
	global_load_dword v22, v[32:33], off nt
	v_add_co_u32_e32 v32, vcc, s62, v70
	s_nop 1
	v_addc_co_u32_e32 v33, vcc, 0, v71, vcc
	v_add_co_u32_e32 v36, vcc, s63, v70
	global_load_dword v32, v[32:33], off offset:2048 nt
	s_nop 0
	v_addc_co_u32_e32 v37, vcc, 0, v71, vcc
	global_load_dword v39, v[36:37], off nt
	v_add_co_u32_e32 v36, vcc, s64, v70
	s_nop 1
	v_addc_co_u32_e32 v37, vcc, 0, v71, vcc
	global_load_dword v50, v[36:37], off offset:2048 nt
	v_add_co_u32_e32 v36, vcc, s25, v70
	s_nop 1
	v_addc_co_u32_e32 v37, vcc, 0, v71, vcc
	global_load_dword v25, v[36:37], off nt
	v_add_co_u32_e32 v36, vcc, s65, v70
	s_nop 1
	v_addc_co_u32_e32 v37, vcc, 0, v71, vcc
	v_add_co_u32_e32 v40, vcc, s66, v70
	global_load_dword v36, v[36:37], off offset:2048 nt
	s_nop 0
	v_addc_co_u32_e32 v41, vcc, 0, v71, vcc
	global_load_dword v43, v[40:41], off nt
	v_add_co_u32_e32 v40, vcc, s67, v70
	s_nop 1
	v_addc_co_u32_e32 v41, vcc, 0, v71, vcc
	global_load_dword v54, v[40:41], off offset:2048 nt
	v_add_co_u32_e32 v40, vcc, s68, v70
	s_nop 1
	v_addc_co_u32_e32 v41, vcc, 0, v71, vcc
	global_load_dword v29, v[40:41], off nt
	v_add_co_u32_e32 v40, vcc, s69, v70
	s_nop 1
	v_addc_co_u32_e32 v41, vcc, 0, v71, vcc
	v_add_co_u32_e32 v44, vcc, s72, v70
	global_load_dword v40, v[40:41], off offset:2048 nt
	s_nop 0
	v_addc_co_u32_e32 v45, vcc, 0, v71, vcc
; #define LAS __attribute__((address_space(3)))
; __device__ __forceinline__ void transpose_item(const float* __restrict__ W, int K, int N, bf16_t* __restrict__ WT, int drow0, LAS float* scr, int k0, int n0, int lane, const float* __restrict__ gk) {
;     const float* src = W + (size_t)k0 * N + n0 + lane;
; #pragma unroll
;     for (int hb = 0; hb < 1; ++hb) {
;         float v[64];
; #pragma unroll
;         for (int i = 0; i < 64; ++i) v[i] = __builtin_nontemporal_load(src + (size_t)(hb * 64 + i) * N);
;         if (gk) {
; #pragma unroll
;             for (int i = 0; i < 64; ++i) v[i] *= gk[k0 + hb * 64 + i];
;         }
; #pragma unroll
;         for (int i = 0; i < 64; ++i) scr[(hb * 64 + i) * 65 + lane] = v[i];
;     }
;     asm volatile("s_waitcnt lgkmcnt(0)" ::: "memory");
	global_load_dword v47, v[44:45], off nt
	v_add_co_u32_e32 v44, vcc, s73, v70
	s_nop 1
	v_addc_co_u32_e32 v45, vcc, 0, v71, vcc
	global_load_dword v57, v[44:45], off offset:2048 nt
	v_add_co_u32_e32 v44, vcc, s74, v70
	s_nop 1
	v_addc_co_u32_e32 v45, vcc, 0, v71, vcc
	global_load_dword v33, v[44:45], off nt
	v_add_co_u32_e32 v44, vcc, s75, v70
	s_nop 1
	v_addc_co_u32_e32 v45, vcc, 0, v71, vcc
	v_add_co_u32_e32 v48, vcc, s76, v70
	global_load_dword v44, v[44:45], off offset:2048 nt
	s_nop 0
	v_addc_co_u32_e32 v49, vcc, 0, v71, vcc
	global_load_dword v51, v[48:49], off nt
	v_add_co_u32_e32 v48, vcc, s77, v70
	s_nop 1
	v_addc_co_u32_e32 v49, vcc, 0, v71, vcc
	global_load_dword v60, v[48:49], off offset:2048 nt
	v_add_co_u32_e32 v48, vcc, s78, v70
	s_nop 1
	v_addc_co_u32_e32 v49, vcc, 0, v71, vcc
	global_load_dword v37, v[48:49], off nt
	v_add_co_u32_e32 v48, vcc, s79, v70
	s_nop 1
	v_addc_co_u32_e32 v49, vcc, 0, v71, vcc
	v_add_co_u32_e32 v52, vcc, s80, v70
	global_load_dword v48, v[48:49], off offset:2048 nt
	s_nop 0
	v_addc_co_u32_e32 v53, vcc, 0, v71, vcc
	global_load_dword v55, v[52:53], off nt
	v_add_co_u32_e32 v52, vcc, s81, v70
	s_nop 1
	v_addc_co_u32_e32 v53, vcc, 0, v71, vcc
	global_load_dword v63, v[52:53], off offset:2048 nt
	v_add_co_u32_e32 v52, vcc, s82, v70
	s_nop 1
	v_addc_co_u32_e32 v53, vcc, 0, v71, vcc
	global_load_dword v41, v[52:53], off nt
	v_add_co_u32_e32 v52, vcc, s83, v70
	s_nop 1
	v_addc_co_u32_e32 v53, vcc, 0, v71, vcc
	v_add_co_u32_e32 v58, vcc, s84, v70
	global_load_dword v52, v[52:53], off offset:2048 nt
	s_nop 0
	v_addc_co_u32_e32 v59, vcc, 0, v71, vcc
	v_add_co_u32_e32 v64, vcc, s85, v70
	global_load_dword v58, v[58:59], off nt
	s_nop 0
	v_addc_co_u32_e32 v65, vcc, 0, v71, vcc
	v_add_co_u32_e32 v66, vcc, s86, v70
	global_load_dword v65, v[64:65], off offset:2048 nt
	s_nop 0
	v_addc_co_u32_e32 v67, vcc, 0, v71, vcc
	global_load_dword v45, v[66:67], off nt
	v_add_co_u32_e32 v66, vcc, s87, v70
	s_nop 1
	v_addc_co_u32_e32 v67, vcc, 0, v71, vcc
	global_load_dword v56, v[66:67], off offset:2048 nt
	v_add_co_u32_e32 v66, vcc, s88, v70
	s_nop 1
	v_addc_co_u32_e32 v67, vcc, 0, v71, vcc
	global_load_dword v61, v[66:67], off nt
	v_add_co_u32_e32 v66, vcc, s89, v70
	s_nop 1
	v_addc_co_u32_e32 v67, vcc, 0, v71, vcc
	v_add_co_u32_e32 v68, vcc, s90, v70
	global_load_dword v67, v[66:67], off offset:2048 nt
	s_nop 0
	v_addc_co_u32_e32 v69, vcc, 0, v71, vcc
	global_load_dword v49, v[68:69], off nt
	v_add_co_u32_e32 v68, vcc, s91, v70
	s_nop 1
	v_addc_co_u32_e32 v69, vcc, 0, v71, vcc
	global_load_dword v59, v[68:69], off offset:2048 nt
	v_add_co_u32_e32 v68, vcc, s92, v70
	s_nop 1
	v_addc_co_u32_e32 v69, vcc, 0, v71, vcc
	global_load_dword v64, v[68:69], off nt
	v_add_co_u32_e32 v68, vcc, s93, v70
	s_nop 1
	v_addc_co_u32_e32 v69, vcc, 0, v71, vcc
	v_add_co_u32_e32 v72, vcc, s94, v70
	global_load_dword v68, v[68:69], off offset:2048 nt
	s_nop 0
	v_addc_co_u32_e32 v73, vcc, 0, v71, vcc
	global_load_dword v53, v[72:73], off nt
	v_add_co_u32_e32 v72, vcc, s95, v70
	s_nop 1
	v_addc_co_u32_e32 v73, vcc, 0, v71, vcc
	global_load_dword v62, v[72:73], off offset:2048 nt
	v_add_co_u32_e32 v72, vcc, s96, v70
	s_nop 1
	v_addc_co_u32_e32 v73, vcc, 0, v71, vcc
	v_add_co_u32_e32 v70, vcc, s97, v70
	global_load_dword v66, v[72:73], off nt
	s_nop 0
	v_addc_co_u32_e32 v71, vcc, 0, v71, vcc
	global_load_dword v69, v[70:71], off offset:2048 nt
	v_add_u32_e32 v70, 0x400, v76
	s_waitcnt vmcnt(0)
	ds_write2_b32 v76, v74, v75 offset1:65
	ds_write2_b32 v76, v87, v88 offset0:130 offset1:195
	ds_write2_b32 v70, v0, v3 offset0:4 offset1:69
	ds_write2_b32 v70, v17, v26 offset0:134 offset1:199
	v_add_u32_e32 v0, 0x800, v76
	ds_write2_b32 v0, v1, v15 offset0:8 offset1:73
	ds_write2_b32 v0, v20, v30 offset0:138 offset1:203
	v_add_u32_e32 v0, 0xc00, v76
	ds_write2_b32 v0, v2, v18 offset0:12 offset1:77
	ds_write2_b32 v0, v23, v34 offset0:142 offset1:207
	v_add_u32_e32 v0, 0x1000, v76
	ds_write2_b32 v0, v14, v21 offset0:16 offset1:81
	ds_write2_b32 v0, v27, v38 offset0:146 offset1:211
	v_add_u32_e32 v0, 0x1400, v76
	ds_write2_b32 v0, v16, v24 offset0:20 offset1:85
	ds_write2_b32 v0, v31, v42 offset0:150 offset1:215
	v_add_u32_e32 v0, 0x1800, v76
	ds_write2_b32 v0, v19, v28 offset0:24 offset1:89
	ds_write2_b32 v0, v35, v46 offset0:154 offset1:219
	v_add_u32_e32 v0, 0x1c00, v76
	ds_write2_b32 v0, v22, v32 offset0:28 offset1:93
	ds_write2_b32 v0, v39, v50 offset0:158 offset1:223
	v_add_u32_e32 v0, 0x2000, v76
	ds_write2_b32 v0, v25, v36 offset0:32 offset1:97
	ds_write2_b32 v0, v43, v54 offset0:162 offset1:227
	v_add_u32_e32 v0, 0x2400, v76
	ds_write2_b32 v0, v29, v40 offset0:36 offset1:101
	ds_write2_b32 v0, v47, v57 offset0:166 offset1:231
	v_add_u32_e32 v0, 0x2800, v76
	ds_write2_b32 v0, v33, v44 offset0:40 offset1:105
	ds_write2_b32 v0, v51, v60 offset0:170 offset1:235
	v_add_u32_e32 v0, 0x2c00, v76
	ds_write2_b32 v0, v37, v48 offset0:44 offset1:109
	ds_write2_b32 v0, v55, v63 offset0:174 offset1:239
	v_add_u32_e32 v0, 0x3000, v76
	ds_write2_b32 v0, v41, v52 offset0:48 offset1:113
	ds_write2_b32 v0, v58, v65 offset0:178 offset1:243
	v_add_u32_e32 v0, 0x3400, v76
	ds_write2_b32 v0, v45, v56 offset0:52 offset1:117
	ds_write2_b32 v0, v61, v67 offset0:182 offset1:247
	v_add_u32_e32 v0, 0x3800, v76
	ds_write2_b32 v0, v49, v59 offset0:56 offset1:121
	ds_write2_b32 v0, v64, v68 offset0:186 offset1:251
	v_add_u32_e32 v0, 0x3c00, v76
	ds_write2_b32 v0, v53, v62 offset0:60 offset1:125
	ds_write2_b32 v0, v66, v69 offset0:190 offset1:255
	s_waitcnt lgkmcnt(0)
; #define LAS __attribute__((address_space(3)))
; __device__ __forceinline__ unsigned pk2(float lo, float hi) { unsigned r; asm volatile("v_cvt_pk_bf16_f32 %0, %1, %2" : "=v"(r) : "v"(lo), "v"(hi)); return r; }
; __device__ __forceinline__ void transpose_item(const float* __restrict__ W, int K, int N, bf16_t* __restrict__ WT, int drow0, LAS float* scr, int k0, int n0, int lane, const float* __restrict__ gk) {
;     ...
;     const int c = lane & 7;
; #pragma unroll
;     for (int j = 0; j < 8; ++j) { const int n = (lane >> 3) + 8 * j; const LAS float* s = scr + (8 * c) * 65 + n;
;         u32x4 o; o.x = pk2(s[0 * 65], s[1 * 65]); o.y = pk2(s[2 * 65], s[3 * 65]); o.z = pk2(s[4 * 65], s[5 * 65]); o.w = pk2(s[6 * 65], s[7 * 65]);
;         *(u32x4*)(WT + (size_t)(drow0 + n) * K + k0 + 8 * c) = o; }
;     asm volatile("s_waitcnt lgkmcnt(0)" ::: "memory");
	v_add_u32_e32 v20, 0x400, v78
	ds_read2_b32 v[22:23], v78 offset1:65
	ds_read2_b32 v[24:25], v78 offset0:130 offset1:195
	ds_read2_b32 v[26:27], v20 offset0:4 offset1:69
	ds_read2_b32 v[28:29], v20 offset0:134 offset1:199
	ds_read2_b32 v[30:31], v78 offset0:8 offset1:73
	ds_read2_b32 v[32:33], v78 offset0:138 offset1:203
	ds_read2_b32 v[34:35], v20 offset0:12 offset1:77
	ds_read2_b32 v[36:37], v20 offset0:142 offset1:207
	s_waitcnt lgkmcnt(4)
	v_cvt_pk_bf16_f32 v0, v22, v23
	v_cvt_pk_bf16_f32 v1, v24, v25
	v_cvt_pk_bf16_f32 v2, v26, v27
	v_cvt_pk_bf16_f32 v3, v28, v29
	v_add_u32_e32 v16, s6, v77
	v_ashrrev_i32_e32 v17, 31, v16
	v_lshl_add_u64 v[14:15], s[8:9], 1, v[12:13]
	v_lshlrev_b64 v[18:19], 12, v[16:17]
	v_lshl_add_u64 v[18:19], v[14:15], 0, v[18:19]
	global_store_dwordx4 v[18:19], v[0:3], off
	s_nop 1
	ds_read2_b32 v[22:23], v78 offset0:16 offset1:81
	ds_read2_b32 v[24:25], v78 offset0:146 offset1:211
	ds_read2_b32 v[26:27], v20 offset0:20 offset1:85
	ds_read2_b32 v[28:29], v20 offset0:150 offset1:215
	s_waitcnt lgkmcnt(4)
	v_cvt_pk_bf16_f32 v0, v30, v31
	v_cvt_pk_bf16_f32 v1, v32, v33
	v_cvt_pk_bf16_f32 v2, v34, v35
	v_cvt_pk_bf16_f32 v3, v36, v37
	v_add_u32_e32 v18, 8, v16
	v_ashrrev_i32_e32 v19, 31, v18
	v_lshlrev_b64 v[18:19], 12, v[18:19]
	v_lshl_add_u64 v[18:19], v[14:15], 0, v[18:19]
	global_store_dwordx4 v[18:19], v[0:3], off
	s_nop 1
	ds_read2_b32 v[30:31], v78 offset0:24 offset1:89
	ds_read2_b32 v[32:33], v78 offset0:154 offset1:219
	ds_read2_b32 v[34:35], v20 offset0:28 offset1:93
	ds_read2_b32 v[36:37], v20 offset0:158 offset1:223
	s_waitcnt lgkmcnt(4)
	v_cvt_pk_bf16_f32 v0, v22, v23
	v_cvt_pk_bf16_f32 v1, v24, v25
	v_cvt_pk_bf16_f32 v2, v26, v27
	v_cvt_pk_bf16_f32 v3, v28, v29
	v_add_u32_e32 v18, 16, v16
	v_ashrrev_i32_e32 v19, 31, v18
	v_lshlrev_b64 v[18:19], 12, v[18:19]
	v_lshl_add_u64 v[18:19], v[14:15], 0, v[18:19]
	global_store_dwordx4 v[18:19], v[0:3], off
	s_nop 1
	ds_read2_b32 v[22:23], v78 offset0:32 offset1:97
	ds_read2_b32 v[24:25], v78 offset0:162 offset1:227
	ds_read2_b32 v[26:27], v20 offset0:36 offset1:101
	ds_read2_b32 v[28:29], v20 offset0:166 offset1:231
	s_waitcnt lgkmcnt(4)
	v_cvt_pk_bf16_f32 v0, v30, v31
	v_cvt_pk_bf16_f32 v1, v32, v33
	v_cvt_pk_bf16_f32 v2, v34, v35
	v_cvt_pk_bf16_f32 v3, v36, v37
	v_add_u32_e32 v18, 24, v16
	v_ashrrev_i32_e32 v19, 31, v18
	v_lshlrev_b64 v[18:19], 12, v[18:19]
	v_lshl_add_u64 v[18:19], v[14:15], 0, v[18:19]
	global_store_dwordx4 v[18:19], v[0:3], off
	s_nop 1
	ds_read2_b32 v[30:31], v78 offset0:40 offset1:105
	ds_read2_b32 v[32:33], v78 offset0:170 offset1:235
	ds_read2_b32 v[34:35], v20 offset0:44 offset1:109
	ds_read2_b32 v[36:37], v20 offset0:174 offset1:239
	s_waitcnt lgkmcnt(4)
	v_cvt_pk_bf16_f32 v0, v22, v23
	v_cvt_pk_bf16_f32 v1, v24, v25
	v_cvt_pk_bf16_f32 v2, v26, v27
	v_cvt_pk_bf16_f32 v3, v28, v29
	v_add_u32_e32 v18, 32, v16
	v_ashrrev_i32_e32 v19, 31, v18
	v_lshlrev_b64 v[18:19], 12, v[18:19]
	v_lshl_add_u64 v[18:19], v[14:15], 0, v[18:19]
	global_store_dwordx4 v[18:19], v[0:3], off
	s_nop 1
	ds_read2_b32 v[22:23], v78 offset0:48 offset1:113
	ds_read2_b32 v[24:25], v78 offset0:178 offset1:243
	ds_read2_b32 v[26:27], v20 offset0:52 offset1:117
	ds_read2_b32 v[28:29], v20 offset0:182 offset1:247
	s_waitcnt lgkmcnt(4)
	v_cvt_pk_bf16_f32 v0, v30, v31
	v_cvt_pk_bf16_f32 v1, v32, v33
	v_cvt_pk_bf16_f32 v2, v34, v35
	v_cvt_pk_bf16_f32 v3, v36, v37
	v_add_u32_e32 v18, 40, v16
	v_ashrrev_i32_e32 v19, 31, v18
	v_lshlrev_b64 v[18:19], 12, v[18:19]
	v_lshl_add_u64 v[18:19], v[14:15], 0, v[18:19]
	global_store_dwordx4 v[18:19], v[0:3], off
	s_nop 1
	ds_read2_b32 v[30:31], v78 offset0:56 offset1:121
	ds_read2_b32 v[32:33], v78 offset0:186 offset1:251
	ds_read2_b32 v[34:35], v20 offset0:60 offset1:125
	ds_read2_b32 v[36:37], v20 offset0:190 offset1:255
	s_waitcnt lgkmcnt(4)
	v_cvt_pk_bf16_f32 v0, v22, v23
	v_cvt_pk_bf16_f32 v1, v24, v25
	v_cvt_pk_bf16_f32 v2, v26, v27
	v_cvt_pk_bf16_f32 v3, v28, v29
	v_add_u32_e32 v18, 48, v16
	v_ashrrev_i32_e32 v19, 31, v18
	v_lshlrev_b64 v[18:19], 12, v[18:19]
	v_lshl_add_u64 v[18:19], v[14:15], 0, v[18:19]
	v_add_u32_e32 v16, 56, v16
	global_store_dwordx4 v[18:19], v[0:3], off
	s_nop 1
	s_waitcnt lgkmcnt(0)
	v_ashrrev_i32_e32 v17, 31, v16
	v_cvt_pk_bf16_f32 v0, v30, v31
	v_lshlrev_b64 v[16:17], 12, v[16:17]
	v_cvt_pk_bf16_f32 v1, v32, v33
	v_lshl_add_u64 v[14:15], v[14:15], 0, v[16:17]
	v_cvt_pk_bf16_f32 v2, v34, v35
	v_cvt_pk_bf16_f32 v3, v36, v37
	global_store_dwordx4 v[14:15], v[0:3], off
	s_nop 1
	s_waitcnt lgkmcnt(0)
	s_cbranch_scc0 .LBB0_387

; #define LAS __attribute__((address_space(3)))
; __device__ __forceinline__ void transpose_item(const float* __restrict__ W, int K, int N, bf16_t* __restrict__ WT, int drow0, LAS float* scr, int k0, int n0, int lane, const float* __restrict__ gk) {
;     const float* src = W + (size_t)k0 * N + n0 + lane;
; #pragma unroll
;     for (int hb = 0; hb < 1; ++hb) {
;         float v[64];
; #pragma unroll
;         for (int i = 0; i < 64; ++i) v[i] = __builtin_nontemporal_load(src + (size_t)(hb * 64 + i) * N);
; __device__ __forceinline__ void transpose_matrix(const float* W, int K, int N, bf16_t* WT, int mode, LAS float* scr, int gw, int NGW, int lane, const float* gA, const float* gB, int it_lo, int it_hi) {
;     const int nblk = N / 64, w8 = gw & 7;
;     for (int j = (it_lo >> 3) + (gw >> 3); j < (it_hi >> 3); j += (NGW >> 3)) {
;         const int kb = (j / nblk) * 8 + w8, nb = j % nblk, n0 = nb * 64;
;         int drow0 = n0;
;         if (mode) { const int up = n0 >= DFF, j = n0 - up * DFF; drow0 = 256 * (j / 128) + (j % 128) + up * 128; }
;         transpose_item(W, K, N, WT, drow0, scr, kb * 64, n0, lane, gA ? (kb * 64 < 1024 ? gA : gB - 1024) : nullptr);
.LBB0_392:
	s_mul_hi_i32 s0, s6, 0x2e8ba2e9
	s_lshr_b32 s1, s0, 31
	s_ashr_i32 s0, s0, 5
	s_add_i32 s0, s0, s1
	s_mul_i32 s1, s0, 0xffffff50
	s_mul_i32 s10, s0, 0xffffd400
	s_add_i32 s1, s6, s1
	s_add_i32 s12, s8, s10
	s_cmpk_gt_i32 s1, 0x57
	s_cselect_b32 s1, 0xea00, 0
	s_cselect_b32 s10, 0x80, 0
	s_add_i32 s1, s12, s1
	s_sext_i32_i16 s11, s1
	s_bfe_u32 s11, s11, 0x70018
	s_add_i32 s11, s1, s11
	s_sext_i32_i16 s13, s11
	s_and_b32 s11, s11, 0xff80
	s_sub_i32 s1, s1, s11
	s_lshl_b32 s13, s13, 1
	s_sext_i32_i16 s1, s1
	s_lshl_b32 s0, s0, 9
	s_and_b32 s13, s13, 0xffffff00
	s_add_i32 s10, s10, s1
	s_or_b32 s0, s0, s29
	s_add_i32 s10, s10, s13
	s_ashr_i32 s1, s0, 31
	s_mul_i32 s13, s0, 0xb000
	s_mul_hi_i32 s11, s0, 0xb000
	s_add_u32 s14, s4, s13
	s_addc_u32 s11, s5, s11
	s_ashr_i32 s13, s12, 31
	s_lshl_b64 s[12:13], s[12:13], 2
	s_add_u32 s12, s14, s12
	s_addc_u32 s13, s11, s13
	v_lshl_add_u64 v[70:71], s[12:13], 0, v[112:113]
	v_add_co_u32_e32 v0, vcc, s22, v70
	global_load_dword v74, v112, s[12:13] nt
	s_nop 0
	v_addc_co_u32_e32 v1, vcc, 0, v71, vcc
	global_load_dword v75, v[0:1], off nt
	v_add_co_u32_e32 v0, vcc, s15, v70
	s_add_i32 s6, s6, s27
	s_nop 0
	v_addc_co_u32_e32 v1, vcc, 0, v71, vcc
	global_load_dword v87, v[0:1], off nt
	v_add_co_u32_e32 v0, vcc, s23, v70
	s_add_i32 s8, s8, s9
	s_nop 0
	v_addc_co_u32_e32 v1, vcc, 0, v71, vcc
	global_load_dword v88, v[0:1], off nt
	v_add_co_u32_e32 v0, vcc, s16, v70
	s_cmp_ge_i32 s6, s7
	s_nop 0
	v_addc_co_u32_e32 v1, vcc, 0, v71, vcc
	v_add_co_u32_e32 v2, vcc, s24, v70
	global_load_dword v0, v[0:1], off nt
	s_nop 0
	v_addc_co_u32_e32 v3, vcc, 0, v71, vcc
	v_add_co_u32_e32 v14, vcc, s17, v70
	global_load_dword v3, v[2:3], off nt
	s_nop 0
	v_addc_co_u32_e32 v15, vcc, 0, v71, vcc
	global_load_dword v17, v[14:15], off nt
	v_add_co_u32_e32 v14, vcc, s25, v70
	s_nop 1
	v_addc_co_u32_e32 v15, vcc, 0, v71, vcc
	global_load_dword v26, v[14:15], off nt
	v_add_co_u32_e32 v14, vcc, s18, v70
	s_nop 1
	v_addc_co_u32_e32 v15, vcc, 0, v71, vcc
	global_load_dword v1, v[14:15], off nt
	v_add_co_u32_e32 v14, vcc, s28, v70
	s_nop 1
	v_addc_co_u32_e32 v15, vcc, 0, v71, vcc
	v_add_co_u32_e32 v18, vcc, s19, v70
	global_load_dword v15, v[14:15], off nt
	s_nop 0
	v_addc_co_u32_e32 v19, vcc, 0, v71, vcc
	global_load_dword v20, v[18:19], off nt
	v_add_co_u32_e32 v18, vcc, s33, v70
	s_nop 1
	v_addc_co_u32_e32 v19, vcc, 0, v71, vcc
	global_load_dword v30, v[18:19], off nt
	v_add_co_u32_e32 v18, vcc, s38, v70
	s_nop 1
	v_addc_co_u32_e32 v19, vcc, 0, v71, vcc
	global_load_dword v2, v[18:19], off nt
	v_add_co_u32_e32 v18, vcc, s43, v70
	s_nop 1
	v_addc_co_u32_e32 v19, vcc, 0, v71, vcc
	v_add_co_u32_e32 v22, vcc, s44, v70
	global_load_dword v18, v[18:19], off nt
	s_nop 0
	v_addc_co_u32_e32 v23, vcc, 0, v71, vcc
	v_add_co_u32_e32 v24, vcc, s45, v70
	global_load_dword v23, v[22:23], off nt
	s_nop 0
	v_addc_co_u32_e32 v25, vcc, 0, v71, vcc
	global_load_dword v34, v[24:25], off nt
	v_add_co_u32_e32 v24, vcc, s46, v70
	s_nop 1
	v_addc_co_u32_e32 v25, vcc, 0, v71, vcc
	global_load_dword v14, v[24:25], off nt
	v_add_co_u32_e32 v24, vcc, s47, v70
	s_nop 1
	v_addc_co_u32_e32 v25, vcc, 0, v71, vcc
	global_load_dword v21, v[24:25], off nt
	v_add_co_u32_e32 v24, vcc, s36, v70
	s_nop 1
	v_addc_co_u32_e32 v25, vcc, 0, v71, vcc
	global_load_dword v27, v[24:25], off nt
	v_add_co_u32_e32 v24, vcc, s48, v70
	s_nop 1
	v_addc_co_u32_e32 v25, vcc, 0, v71, vcc
	global_load_dword v38, v[24:25], off nt
	v_add_co_u32_e32 v24, vcc, s37, v70
	s_nop 1
	v_addc_co_u32_e32 v25, vcc, 0, v71, vcc
	global_load_dword v16, v[24:25], off nt
	v_add_co_u32_e32 v24, vcc, s49, v70
	s_nop 1
	v_addc_co_u32_e32 v25, vcc, 0, v71, vcc
	v_add_co_u32_e32 v28, vcc, s50, v70
	global_load_dword v24, v[24:25], off nt
	s_nop 0
	v_addc_co_u32_e32 v29, vcc, 0, v71, vcc
	global_load_dword v31, v[28:29], off nt
	v_add_co_u32_e32 v28, vcc, s51, v70
	s_nop 1
	v_addc_co_u32_e32 v29, vcc, 0, v71, vcc
	global_load_dword v42, v[28:29], off nt
	v_add_co_u32_e32 v28, vcc, s52, v70
	s_nop 1
	v_addc_co_u32_e32 v29, vcc, 0, v71, vcc
	global_load_dword v19, v[28:29], off nt
	v_add_co_u32_e32 v28, vcc, s53, v70
	s_nop 1
	v_addc_co_u32_e32 v29, vcc, 0, v71, vcc
	v_add_co_u32_e32 v32, vcc, s54, v70
	global_load_dword v28, v[28:29], off nt
	s_nop 0
	v_addc_co_u32_e32 v33, vcc, 0, v71, vcc
	global_load_dword v35, v[32:33], off nt
	v_add_co_u32_e32 v32, vcc, s55, v70
	s_nop 1
	v_addc_co_u32_e32 v33, vcc, 0, v71, vcc
	global_load_dword v46, v[32:33], off nt
	v_add_co_u32_e32 v32, vcc, s56, v70
	s_nop 1
	v_addc_co_u32_e32 v33, vcc, 0, v71, vcc
	global_load_dword v22, v[32:33], off nt
	v_add_co_u32_e32 v32, vcc, s57, v70
	s_nop 1
	v_addc_co_u32_e32 v33, vcc, 0, v71, vcc
	v_add_co_u32_e32 v36, vcc, s58, v70
	global_load_dword v32, v[32:33], off nt
	s_nop 0
	v_addc_co_u32_e32 v37, vcc, 0, v71, vcc
	global_load_dword v39, v[36:37], off nt
	v_add_co_u32_e32 v36, vcc, s59, v70
	s_nop 1
	v_addc_co_u32_e32 v37, vcc, 0, v71, vcc
	global_load_dword v50, v[36:37], off nt
	v_add_co_u32_e32 v36, vcc, s60, v70
	s_nop 1
	v_addc_co_u32_e32 v37, vcc, 0, v71, vcc
	global_load_dword v25, v[36:37], off nt
	v_add_co_u32_e32 v36, vcc, s61, v70
	s_nop 1
	v_addc_co_u32_e32 v37, vcc, 0, v71, vcc
	v_add_co_u32_e32 v40, vcc, s62, v70
	global_load_dword v36, v[36:37], off nt
	s_nop 0
	v_addc_co_u32_e32 v41, vcc, 0, v71, vcc
	global_load_dword v43, v[40:41], off nt
	v_add_co_u32_e32 v40, vcc, s63, v70
	s_nop 1
	v_addc_co_u32_e32 v41, vcc, 0, v71, vcc
	global_load_dword v54, v[40:41], off nt
	v_add_co_u32_e32 v40, vcc, s64, v70
	s_nop 1
	v_addc_co_u32_e32 v41, vcc, 0, v71, vcc
	global_load_dword v29, v[40:41], off nt
; __device__ __forceinline__ void transpose_item(const float* __restrict__ W, int K, int N, bf16_t* __restrict__ WT, int drow0, LAS float* scr, int k0, int n0, int lane, const float* __restrict__ gk) {
;     ...
;         for (int i = 0; i < 64; ++i) v[i] = __builtin_nontemporal_load(src + (size_t)(hb * 64 + i) * N);
;         if (gk) {
; #pragma unroll
;             for (int i = 0; i < 64; ++i) v[i] *= gk[k0 + hb * 64 + i];
;         }
; #pragma unroll
;         for (int i = 0; i < 64; ++i) scr[(hb * 64 + i) * 65 + lane] = v[i];
;     }
;     asm volatile("s_waitcnt lgkmcnt(0)" ::: "memory");
	v_add_co_u32_e32 v40, vcc, s65, v70
	s_nop 1
	v_addc_co_u32_e32 v41, vcc, 0, v71, vcc
	v_add_co_u32_e32 v44, vcc, s66, v70
	global_load_dword v40, v[40:41], off nt
	s_nop 0
	v_addc_co_u32_e32 v45, vcc, 0, v71, vcc
	global_load_dword v47, v[44:45], off nt
	v_add_co_u32_e32 v44, vcc, s67, v70
	s_nop 1
	v_addc_co_u32_e32 v45, vcc, 0, v71, vcc
	global_load_dword v57, v[44:45], off nt
	v_add_co_u32_e32 v44, vcc, s68, v70
	s_nop 1
	v_addc_co_u32_e32 v45, vcc, 0, v71, vcc
	global_load_dword v33, v[44:45], off nt
	v_add_co_u32_e32 v44, vcc, s69, v70
	s_nop 1
	v_addc_co_u32_e32 v45, vcc, 0, v71, vcc
	v_add_co_u32_e32 v48, vcc, s72, v70
	global_load_dword v44, v[44:45], off nt
	s_nop 0
	v_addc_co_u32_e32 v49, vcc, 0, v71, vcc
	global_load_dword v51, v[48:49], off nt
	v_add_co_u32_e32 v48, vcc, s73, v70
	s_nop 1
	v_addc_co_u32_e32 v49, vcc, 0, v71, vcc
	global_load_dword v60, v[48:49], off nt
	v_add_co_u32_e32 v48, vcc, s74, v70
	s_nop 1
	v_addc_co_u32_e32 v49, vcc, 0, v71, vcc
	global_load_dword v37, v[48:49], off nt
	v_add_co_u32_e32 v48, vcc, s75, v70
	s_nop 1
	v_addc_co_u32_e32 v49, vcc, 0, v71, vcc
	v_add_co_u32_e32 v52, vcc, s76, v70
	global_load_dword v48, v[48:49], off nt
	s_nop 0
	v_addc_co_u32_e32 v53, vcc, 0, v71, vcc
	global_load_dword v55, v[52:53], off nt
	v_add_co_u32_e32 v52, vcc, s77, v70
	s_nop 1
	v_addc_co_u32_e32 v53, vcc, 0, v71, vcc
	global_load_dword v63, v[52:53], off nt
	v_add_co_u32_e32 v52, vcc, s78, v70
	s_nop 1
	v_addc_co_u32_e32 v53, vcc, 0, v71, vcc
	global_load_dword v41, v[52:53], off nt
	v_add_co_u32_e32 v52, vcc, s79, v70
	s_nop 1
	v_addc_co_u32_e32 v53, vcc, 0, v71, vcc
	v_add_co_u32_e32 v58, vcc, s80, v70
	global_load_dword v52, v[52:53], off nt
	s_nop 0
	v_addc_co_u32_e32 v59, vcc, 0, v71, vcc
	v_add_co_u32_e32 v64, vcc, s81, v70
	global_load_dword v58, v[58:59], off nt
	s_nop 0
	v_addc_co_u32_e32 v65, vcc, 0, v71, vcc
	v_add_co_u32_e32 v66, vcc, s82, v70
	global_load_dword v65, v[64:65], off nt
	s_nop 0
	v_addc_co_u32_e32 v67, vcc, 0, v71, vcc
	global_load_dword v45, v[66:67], off nt
	v_add_co_u32_e32 v66, vcc, s83, v70
	s_nop 1
	v_addc_co_u32_e32 v67, vcc, 0, v71, vcc
	global_load_dword v56, v[66:67], off nt
	v_add_co_u32_e32 v66, vcc, s84, v70
	s_nop 1
	v_addc_co_u32_e32 v67, vcc, 0, v71, vcc
	global_load_dword v61, v[66:67], off nt
	v_add_co_u32_e32 v66, vcc, s85, v70
	s_nop 1
	v_addc_co_u32_e32 v67, vcc, 0, v71, vcc
	v_add_co_u32_e32 v68, vcc, s86, v70
	global_load_dword v67, v[66:67], off nt
	s_nop 0
	v_addc_co_u32_e32 v69, vcc, 0, v71, vcc
	global_load_dword v49, v[68:69], off nt
	v_add_co_u32_e32 v68, vcc, s87, v70
	s_nop 1
	v_addc_co_u32_e32 v69, vcc, 0, v71, vcc
	global_load_dword v59, v[68:69], off nt
	v_add_co_u32_e32 v68, vcc, s88, v70
	s_nop 1
	v_addc_co_u32_e32 v69, vcc, 0, v71, vcc
	global_load_dword v64, v[68:69], off nt
	v_add_co_u32_e32 v68, vcc, s89, v70
	s_nop 1
	v_addc_co_u32_e32 v69, vcc, 0, v71, vcc
	v_add_co_u32_e32 v72, vcc, s90, v70
	global_load_dword v68, v[68:69], off nt
	s_nop 0
	v_addc_co_u32_e32 v73, vcc, 0, v71, vcc
	global_load_dword v53, v[72:73], off nt
	v_add_co_u32_e32 v72, vcc, s91, v70
	s_nop 1
	v_addc_co_u32_e32 v73, vcc, 0, v71, vcc
	global_load_dword v62, v[72:73], off nt
	v_add_co_u32_e32 v72, vcc, s92, v70
	s_nop 1
	v_addc_co_u32_e32 v73, vcc, 0, v71, vcc
	v_add_co_u32_e32 v70, vcc, s93, v70
	global_load_dword v66, v[72:73], off nt
	s_nop 0
	v_addc_co_u32_e32 v71, vcc, 0, v71, vcc
	global_load_dword v69, v[70:71], off nt
	v_add_u32_e32 v70, 0x400, v76
	s_waitcnt vmcnt(0)
	ds_write2_b32 v76, v74, v75 offset1:65
	ds_write2_b32 v76, v87, v88 offset0:130 offset1:195
	ds_write2_b32 v70, v0, v3 offset0:4 offset1:69
	ds_write2_b32 v70, v17, v26 offset0:134 offset1:199
	v_add_u32_e32 v0, 0x800, v76
	ds_write2_b32 v0, v1, v15 offset0:8 offset1:73
	ds_write2_b32 v0, v20, v30 offset0:138 offset1:203
	v_add_u32_e32 v0, 0xc00, v76
	ds_write2_b32 v0, v2, v18 offset0:12 offset1:77
	ds_write2_b32 v0, v23, v34 offset0:142 offset1:207
	v_add_u32_e32 v0, 0x1000, v76
	ds_write2_b32 v0, v14, v21 offset0:16 offset1:81
	ds_write2_b32 v0, v27, v38 offset0:146 offset1:211
	v_add_u32_e32 v0, 0x1400, v76
	ds_write2_b32 v0, v16, v24 offset0:20 offset1:85
	ds_write2_b32 v0, v31, v42 offset0:150 offset1:215
	v_add_u32_e32 v0, 0x1800, v76
	ds_write2_b32 v0, v19, v28 offset0:24 offset1:89
	ds_write2_b32 v0, v35, v46 offset0:154 offset1:219
	v_add_u32_e32 v0, 0x1c00, v76
	ds_write2_b32 v0, v22, v32 offset0:28 offset1:93
	ds_write2_b32 v0, v39, v50 offset0:158 offset1:223
	v_add_u32_e32 v0, 0x2000, v76
	ds_write2_b32 v0, v25, v36 offset0:32 offset1:97
	ds_write2_b32 v0, v43, v54 offset0:162 offset1:227
	v_add_u32_e32 v0, 0x2400, v76
	ds_write2_b32 v0, v29, v40 offset0:36 offset1:101
	ds_write2_b32 v0, v47, v57 offset0:166 offset1:231
	v_add_u32_e32 v0, 0x2800, v76
	ds_write2_b32 v0, v33, v44 offset0:40 offset1:105
	ds_write2_b32 v0, v51, v60 offset0:170 offset1:235
	v_add_u32_e32 v0, 0x2c00, v76
	ds_write2_b32 v0, v37, v48 offset0:44 offset1:109
	ds_write2_b32 v0, v55, v63 offset0:174 offset1:239
	v_add_u32_e32 v0, 0x3000, v76
	ds_write2_b32 v0, v41, v52 offset0:48 offset1:113
	ds_write2_b32 v0, v58, v65 offset0:178 offset1:243
	v_add_u32_e32 v0, 0x3400, v76
	ds_write2_b32 v0, v45, v56 offset0:52 offset1:117
	ds_write2_b32 v0, v61, v67 offset0:182 offset1:247
	v_add_u32_e32 v0, 0x3800, v76
	ds_write2_b32 v0, v49, v59 offset0:56 offset1:121
	ds_write2_b32 v0, v64, v68 offset0:186 offset1:251
	v_add_u32_e32 v0, 0x3c00, v76
	ds_write2_b32 v0, v53, v62 offset0:60 offset1:125
	ds_write2_b32 v0, v66, v69 offset0:190 offset1:255
	s_waitcnt lgkmcnt(0)
; #define LAS __attribute__((address_space(3)))
; __device__ __forceinline__ unsigned pk2(float lo, float hi) { unsigned r; asm volatile("v_cvt_pk_bf16_f32 %0, %1, %2" : "=v"(r) : "v"(lo), "v"(hi)); return r; }
; __device__ __forceinline__ void transpose_item(const float* __restrict__ W, int K, int N, bf16_t* __restrict__ WT, int drow0, LAS float* scr, int k0, int n0, int lane, const float* __restrict__ gk) {
;     ...
;     const int c = lane & 7;
; #pragma unroll
;     for (int j = 0; j < 8; ++j) { const int n = (lane >> 3) + 8 * j; const LAS float* s = scr + (8 * c) * 65 + n;
;         u32x4 o; o.x = pk2(s[0 * 65], s[1 * 65]); o.y = pk2(s[2 * 65], s[3 * 65]); o.z = pk2(s[4 * 65], s[5 * 65]); o.w = pk2(s[6 * 65], s[7 * 65]);
;         *(u32x4*)(WT + (size_t)(drow0 + n) * K + k0 + 8 * c) = o; }
;     asm volatile("s_waitcnt lgkmcnt(0)" ::: "memory");
	v_add_u32_e32 v18, 0x400, v78
	ds_read2_b32 v[20:21], v78 offset1:65
	ds_read2_b32 v[22:23], v78 offset0:130 offset1:195
	ds_read2_b32 v[24:25], v18 offset0:4 offset1:69
	ds_read2_b32 v[26:27], v18 offset0:134 offset1:199
	ds_read2_b32 v[28:29], v78 offset0:8 offset1:73
	ds_read2_b32 v[30:31], v78 offset0:138 offset1:203
	ds_read2_b32 v[32:33], v18 offset0:12 offset1:77
	ds_read2_b32 v[34:35], v18 offset0:142 offset1:207
	s_waitcnt lgkmcnt(4)
	v_cvt_pk_bf16_f32 v0, v20, v21
	v_cvt_pk_bf16_f32 v1, v22, v23
	v_cvt_pk_bf16_f32 v2, v24, v25
	v_cvt_pk_bf16_f32 v3, v26, v27
	v_add_u32_e32 v16, s10, v77
	v_ashrrev_i32_e32 v17, 31, v16
	v_lshl_add_u64 v[14:15], s[0:1], 1, v[12:13]
	v_lshlrev_b64 v[16:17], 12, v[16:17]
	v_lshl_add_u64 v[16:17], v[14:15], 0, v[16:17]
	global_store_dwordx4 v[16:17], v[0:3], off
	s_nop 1
	ds_read2_b32 v[20:21], v78 offset0:16 offset1:81
	ds_read2_b32 v[22:23], v78 offset0:146 offset1:211
	ds_read2_b32 v[24:25], v18 offset0:20 offset1:85
	ds_read2_b32 v[26:27], v18 offset0:150 offset1:215
	s_waitcnt lgkmcnt(4)
	v_cvt_pk_bf16_f32 v0, v28, v29
	v_cvt_pk_bf16_f32 v1, v30, v31
	v_cvt_pk_bf16_f32 v2, v32, v33
	v_cvt_pk_bf16_f32 v3, v34, v35
	v_add_u32_e32 v16, s10, v79
	v_ashrrev_i32_e32 v17, 31, v16
	v_lshlrev_b64 v[16:17], 12, v[16:17]
	v_lshl_add_u64 v[16:17], v[14:15], 0, v[16:17]
	global_store_dwordx4 v[16:17], v[0:3], off
	s_nop 1
	ds_read2_b32 v[28:29], v78 offset0:24 offset1:89
	ds_read2_b32 v[30:31], v78 offset0:154 offset1:219
	ds_read2_b32 v[32:33], v18 offset0:28 offset1:93
	ds_read2_b32 v[34:35], v18 offset0:158 offset1:223
	s_waitcnt lgkmcnt(4)
	v_cvt_pk_bf16_f32 v0, v20, v21
	v_cvt_pk_bf16_f32 v1, v22, v23
	v_cvt_pk_bf16_f32 v2, v24, v25
	v_cvt_pk_bf16_f32 v3, v26, v27
	v_add_u32_e32 v16, s10, v80
	v_ashrrev_i32_e32 v17, 31, v16
	v_lshlrev_b64 v[16:17], 12, v[16:17]
	v_lshl_add_u64 v[16:17], v[14:15], 0, v[16:17]
	global_store_dwordx4 v[16:17], v[0:3], off
	s_nop 1
	ds_read2_b32 v[20:21], v78 offset0:32 offset1:97
	ds_read2_b32 v[22:23], v78 offset0:162 offset1:227
	ds_read2_b32 v[24:25], v18 offset0:36 offset1:101
	ds_read2_b32 v[26:27], v18 offset0:166 offset1:231
	s_waitcnt lgkmcnt(4)
	v_cvt_pk_bf16_f32 v0, v28, v29
	v_cvt_pk_bf16_f32 v1, v30, v31
	v_cvt_pk_bf16_f32 v2, v32, v33
	v_cvt_pk_bf16_f32 v3, v34, v35
	v_add_u32_e32 v16, s10, v81
	v_ashrrev_i32_e32 v17, 31, v16
	v_lshlrev_b64 v[16:17], 12, v[16:17]
	v_lshl_add_u64 v[16:17], v[14:15], 0, v[16:17]
	global_store_dwordx4 v[16:17], v[0:3], off
	s_nop 1
	ds_read2_b32 v[28:29], v78 offset0:40 offset1:105
	ds_read2_b32 v[30:31], v78 offset0:170 offset1:235
	ds_read2_b32 v[32:33], v18 offset0:44 offset1:109
	ds_read2_b32 v[34:35], v18 offset0:174 offset1:239
	s_waitcnt lgkmcnt(4)
	v_cvt_pk_bf16_f32 v0, v20, v21
	v_cvt_pk_bf16_f32 v1, v22, v23
	v_cvt_pk_bf16_f32 v2, v24, v25
	v_cvt_pk_bf16_f32 v3, v26, v27
	v_add_u32_e32 v16, s10, v82
	v_ashrrev_i32_e32 v17, 31, v16
	v_lshlrev_b64 v[16:17], 12, v[16:17]
	v_lshl_add_u64 v[16:17], v[14:15], 0, v[16:17]
	global_store_dwordx4 v[16:17], v[0:3], off
	s_nop 1
	ds_read2_b32 v[20:21], v78 offset0:48 offset1:113
	ds_read2_b32 v[22:23], v78 offset0:178 offset1:243
	ds_read2_b32 v[24:25], v18 offset0:52 offset1:117
	ds_read2_b32 v[26:27], v18 offset0:182 offset1:247
	s_waitcnt lgkmcnt(4)
	v_cvt_pk_bf16_f32 v0, v28, v29
	v_cvt_pk_bf16_f32 v1, v30, v31
	v_cvt_pk_bf16_f32 v2, v32, v33
	v_cvt_pk_bf16_f32 v3, v34, v35
	v_add_u32_e32 v16, s10, v83
	v_ashrrev_i32_e32 v17, 31, v16
	v_lshlrev_b64 v[16:17], 12, v[16:17]
	v_lshl_add_u64 v[16:17], v[14:15], 0, v[16:17]
	global_store_dwordx4 v[16:17], v[0:3], off
	s_nop 1
	ds_read2_b32 v[28:29], v78 offset0:56 offset1:121
	ds_read2_b32 v[30:31], v78 offset0:186 offset1:251
	ds_read2_b32 v[32:33], v18 offset0:60 offset1:125
	ds_read2_b32 v[34:35], v18 offset0:190 offset1:255
	s_waitcnt lgkmcnt(4)
	v_cvt_pk_bf16_f32 v0, v20, v21
	v_cvt_pk_bf16_f32 v1, v22, v23
	v_cvt_pk_bf16_f32 v2, v24, v25
	v_cvt_pk_bf16_f32 v3, v26, v27
	v_add_u32_e32 v16, s10, v84
	v_ashrrev_i32_e32 v17, 31, v16
	v_lshlrev_b64 v[16:17], 12, v[16:17]
	v_lshl_add_u64 v[16:17], v[14:15], 0, v[16:17]
	global_store_dwordx4 v[16:17], v[0:3], off
	s_nop 1
	s_waitcnt lgkmcnt(0)
	v_cvt_pk_bf16_f32 v0, v28, v29
	v_cvt_pk_bf16_f32 v1, v30, v31
	v_cvt_pk_bf16_f32 v2, v32, v33
	v_cvt_pk_bf16_f32 v3, v34, v35
	v_add_u32_e32 v16, s10, v85
	v_ashrrev_i32_e32 v17, 31, v16
	v_lshlrev_b64 v[16:17], 12, v[16:17]
	v_lshl_add_u64 v[14:15], v[14:15], 0, v[16:17]
	global_store_dwordx4 v[14:15], v[0:3], off
	s_nop 1
	s_waitcnt lgkmcnt(0)
	s_cbranch_scc0 .LBB0_392
	s_branch .LBB0_347

; #define LAS __attribute__((address_space(3)))
; __device__ __forceinline__ unsigned pk2(float lo, float hi) { unsigned r; asm volatile("v_cvt_pk_bf16_f32 %0, %1, %2" : "=v"(r) : "v"(lo), "v"(hi)); return r; }
; __device__ __forceinline__ void transpose_item(const float* __restrict__ W, int K, int N, bf16_t* __restrict__ WT, int drow0, LAS float* scr, int k0, int n0, int lane, const float* __restrict__ gk) {
;     ...
;         if (gk) {
; #pragma unroll
;             for (int i = 0; i < 64; ++i) v[i] *= gk[k0 + hb * 64 + i];
;         }
; #pragma unroll
;         for (int i = 0; i < 64; ++i) scr[(hb * 64 + i) * 65 + lane] = v[i];
;     }
;     asm volatile("s_waitcnt lgkmcnt(0)" ::: "memory");
;     const int c = lane & 7;
; #pragma unroll
;     for (int j = 0; j < 8; ++j) { const int n = (lane >> 3) + 8 * j; const LAS float* s = scr + (8 * c) * 65 + n;
;         u32x4 o; o.x = pk2(s[0 * 65], s[1 * 65]); o.y = pk2(s[2 * 65], s[3 * 65]); o.z = pk2(s[4 * 65], s[5 * 65]); o.w = pk2(s[6 * 65], s[7 * 65]);
;         *(u32x4*)(WT + (size_t)(drow0 + n) * K + k0 + 8 * c) = o; }
;     asm volatile("s_waitcnt lgkmcnt(0)" ::: "memory");
.LBB0_596:
	s_waitcnt vmcnt(0)
	ds_write2_b32 v76, v2, v3 offset1:65
	ds_write2_b32 v76, v12, v13 offset0:130 offset1:195
	v_add_u32_e32 v2, 0x400, v76
	ds_write2_b32 v2, v14, v15 offset0:4 offset1:69
	ds_write2_b32 v2, v16, v17 offset0:134 offset1:199
	v_add_u32_e32 v2, 0x800, v76
	ds_write2_b32 v2, v18, v19 offset0:8 offset1:73
	ds_write2_b32 v2, v20, v21 offset0:138 offset1:203
	v_add_u32_e32 v2, 0xc00, v76
	ds_write2_b32 v2, v22, v23 offset0:12 offset1:77
	ds_write2_b32 v2, v24, v25 offset0:142 offset1:207
	v_add_u32_e32 v2, 0x1000, v76
	ds_write2_b32 v2, v26, v27 offset0:16 offset1:81
	ds_write2_b32 v2, v28, v29 offset0:146 offset1:211
	v_add_u32_e32 v2, 0x1400, v76
	ds_write2_b32 v2, v30, v31 offset0:20 offset1:85
	ds_write2_b32 v2, v32, v33 offset0:150 offset1:215
	v_add_u32_e32 v2, 0x1800, v76
	ds_write2_b32 v2, v34, v35 offset0:24 offset1:89
	ds_write2_b32 v2, v36, v37 offset0:154 offset1:219
	v_add_u32_e32 v2, 0x1c00, v76
	ds_write2_b32 v2, v38, v39 offset0:28 offset1:93
	ds_write2_b32 v2, v40, v41 offset0:158 offset1:223
	v_add_u32_e32 v2, 0x2000, v76
	ds_write2_b32 v2, v42, v43 offset0:32 offset1:97
	ds_write2_b32 v2, v44, v45 offset0:162 offset1:227
	v_add_u32_e32 v2, 0x2400, v76
	ds_write2_b32 v2, v46, v47 offset0:36 offset1:101
	ds_write2_b32 v2, v48, v49 offset0:166 offset1:231
	v_add_u32_e32 v2, 0x2800, v76
	ds_write2_b32 v2, v50, v51 offset0:40 offset1:105
	ds_write2_b32 v2, v52, v53 offset0:170 offset1:235
	v_add_u32_e32 v2, 0x2c00, v76
	ds_write2_b32 v2, v54, v55 offset0:44 offset1:109
	ds_write2_b32 v2, v56, v57 offset0:174 offset1:239
	v_add_u32_e32 v2, 0x3000, v76
	ds_write2_b32 v2, v58, v59 offset0:48 offset1:113
	ds_write2_b32 v2, v60, v61 offset0:178 offset1:243
	v_add_u32_e32 v2, 0x3400, v76
	ds_write2_b32 v2, v62, v63 offset0:52 offset1:117
	ds_write2_b32 v2, v64, v65 offset0:182 offset1:247
	v_add_u32_e32 v2, 0x3800, v76
	ds_write2_b32 v2, v66, v67 offset0:56 offset1:121
	ds_write2_b32 v2, v68, v69 offset0:186 offset1:251
	v_add_u32_e32 v2, 0x3c00, v76
	ds_write2_b32 v2, v70, v71 offset0:60 offset1:125
	ds_write2_b32 v2, v72, v73 offset0:190 offset1:255
	s_waitcnt lgkmcnt(0)
	v_add_u32_e32 v22, 0x400, v78
	ds_read2_b32 v[24:25], v78 offset1:65
	ds_read2_b32 v[26:27], v78 offset0:130 offset1:195
	ds_read2_b32 v[28:29], v22 offset0:4 offset1:69
	ds_read2_b32 v[30:31], v22 offset0:134 offset1:199
	ds_read2_b32 v[32:33], v78 offset0:8 offset1:73
	ds_read2_b32 v[34:35], v78 offset0:138 offset1:203
	ds_read2_b32 v[36:37], v22 offset0:12 offset1:77
	ds_read2_b32 v[38:39], v22 offset0:142 offset1:207
	s_waitcnt lgkmcnt(4)
	v_cvt_pk_bf16_f32 v12, v24, v25
	v_cvt_pk_bf16_f32 v13, v26, v27
	s_sub_i32 s18, 0, s37
	v_cvt_pk_bf16_f32 v14, v28, v29
	s_add_i32 s18, s18, s33
	v_cvt_pk_bf16_f32 v15, v30, v31
	v_add_u32_e32 v2, s18, v77
	v_ashrrev_i32_e32 v3, 31, v2
	v_lshl_add_u64 v[16:17], s[12:13], 1, v[0:1]
	v_lshlrev_b64 v[20:21], 12, v[2:3]
	v_lshl_add_u64 v[20:21], v[16:17], 0, v[20:21]
	ds_read2_b32 v[24:25], v78 offset0:16 offset1:81
	ds_read2_b32 v[26:27], v78 offset0:146 offset1:211
	ds_read2_b32 v[28:29], v22 offset0:20 offset1:85
	ds_read2_b32 v[30:31], v22 offset0:150 offset1:215
	s_waitcnt lgkmcnt(4)
	global_store_dwordx4 v[20:21], v[12:15], off
	s_nop 1
	s_add_i32 s14, s14, s31
	s_add_i32 s33, s33, s36
	v_cvt_pk_bf16_f32 v12, v32, v33
	v_cvt_pk_bf16_f32 v13, v34, v35
	v_cvt_pk_bf16_f32 v14, v36, v37
	v_cvt_pk_bf16_f32 v15, v38, v39
	v_add_u32_e32 v18, 8, v2
	v_ashrrev_i32_e32 v19, 31, v18
	v_lshlrev_b64 v[18:19], 12, v[18:19]
	v_lshl_add_u64 v[18:19], v[16:17], 0, v[18:19]
	ds_read2_b32 v[32:33], v78 offset0:24 offset1:89
	ds_read2_b32 v[34:35], v78 offset0:154 offset1:219
	ds_read2_b32 v[36:37], v22 offset0:28 offset1:93
	ds_read2_b32 v[38:39], v22 offset0:158 offset1:223
	s_waitcnt lgkmcnt(4)
	global_store_dwordx4 v[18:19], v[12:15], off
	s_nop 1
	s_cmp_ge_i32 s14, s15
	v_cvt_pk_bf16_f32 v12, v24, v25
	v_cvt_pk_bf16_f32 v13, v26, v27
	v_cvt_pk_bf16_f32 v14, v28, v29
	v_cvt_pk_bf16_f32 v15, v30, v31
	v_add_u32_e32 v18, 16, v2
	v_ashrrev_i32_e32 v19, 31, v18
	v_lshlrev_b64 v[18:19], 12, v[18:19]
	v_lshl_add_u64 v[18:19], v[16:17], 0, v[18:19]
	ds_read2_b32 v[24:25], v78 offset0:32 offset1:97
	ds_read2_b32 v[26:27], v78 offset0:162 offset1:227
	ds_read2_b32 v[28:29], v22 offset0:36 offset1:101
	ds_read2_b32 v[30:31], v22 offset0:166 offset1:231
	s_waitcnt lgkmcnt(4)
	global_store_dwordx4 v[18:19], v[12:15], off
	s_nop 1
	s_nop 0
	v_cvt_pk_bf16_f32 v12, v32, v33
	v_cvt_pk_bf16_f32 v13, v34, v35
	v_cvt_pk_bf16_f32 v14, v36, v37
	v_cvt_pk_bf16_f32 v15, v38, v39
	v_add_u32_e32 v18, 24, v2
	v_ashrrev_i32_e32 v19, 31, v18
	v_lshlrev_b64 v[18:19], 12, v[18:19]
	v_lshl_add_u64 v[18:19], v[16:17], 0, v[18:19]
	ds_read2_b32 v[32:33], v78 offset0:40 offset1:105
	ds_read2_b32 v[34:35], v78 offset0:170 offset1:235
	ds_read2_b32 v[36:37], v22 offset0:44 offset1:109
	ds_read2_b32 v[38:39], v22 offset0:174 offset1:239
	s_waitcnt lgkmcnt(4)
	global_store_dwordx4 v[18:19], v[12:15], off
	s_nop 1
	s_nop 0
	v_cvt_pk_bf16_f32 v12, v24, v25
	v_cvt_pk_bf16_f32 v13, v26, v27
	v_cvt_pk_bf16_f32 v14, v28, v29
	v_cvt_pk_bf16_f32 v15, v30, v31
	v_add_u32_e32 v18, 32, v2
	v_ashrrev_i32_e32 v19, 31, v18
	v_lshlrev_b64 v[18:19], 12, v[18:19]
	v_lshl_add_u64 v[18:19], v[16:17], 0, v[18:19]
	ds_read2_b32 v[24:25], v78 offset0:48 offset1:113
	ds_read2_b32 v[26:27], v78 offset0:178 offset1:243
	ds_read2_b32 v[28:29], v22 offset0:52 offset1:117
	ds_read2_b32 v[30:31], v22 offset0:182 offset1:247
	s_waitcnt lgkmcnt(4)
	global_store_dwordx4 v[18:19], v[12:15], off
	s_nop 1
	s_nop 0
	v_cvt_pk_bf16_f32 v12, v32, v33
	v_cvt_pk_bf16_f32 v13, v34, v35
	v_cvt_pk_bf16_f32 v14, v36, v37
	v_cvt_pk_bf16_f32 v15, v38, v39
	v_add_u32_e32 v18, 40, v2
	v_ashrrev_i32_e32 v19, 31, v18
	v_lshlrev_b64 v[18:19], 12, v[18:19]
	ds_read2_b32 v[32:33], v78 offset0:56 offset1:121
	ds_read2_b32 v[34:35], v78 offset0:186 offset1:251
	ds_read2_b32 v[36:37], v22 offset0:60 offset1:125
	ds_read2_b32 v[38:39], v22 offset0:190 offset1:255
	s_waitcnt lgkmcnt(4)
	v_lshl_add_u64 v[18:19], v[16:17], 0, v[18:19]
	global_store_dwordx4 v[18:19], v[12:15], off
	s_nop 1
	s_nop 0
	v_cvt_pk_bf16_f32 v12, v24, v25
	v_add_u32_e32 v20, 48, v2
	v_ashrrev_i32_e32 v21, 31, v20
	v_cvt_pk_bf16_f32 v13, v26, v27
	v_lshlrev_b64 v[20:21], 12, v[20:21]
	v_add_u32_e32 v2, 56, v2
	v_cvt_pk_bf16_f32 v14, v28, v29
	v_cvt_pk_bf16_f32 v15, v30, v31
	v_lshl_add_u64 v[20:21], v[16:17], 0, v[20:21]
	v_ashrrev_i32_e32 v3, 31, v2
	s_waitcnt lgkmcnt(0)
	global_store_dwordx4 v[20:21], v[12:15], off
	s_nop 1
	v_lshlrev_b64 v[2:3], 12, v[2:3]
	v_lshl_add_u64 v[2:3], v[16:17], 0, v[2:3]
	v_cvt_pk_bf16_f32 v12, v32, v33
	v_cvt_pk_bf16_f32 v13, v34, v35
	v_cvt_pk_bf16_f32 v14, v36, v37
	v_cvt_pk_bf16_f32 v15, v38, v39
	global_store_dwordx4 v[2:3], v[12:15], off
	s_nop 1
	s_waitcnt lgkmcnt(0)
	s_cbranch_scc1 .LBB0_599

; #define LAS __attribute__((address_space(3)))
; __device__ __forceinline__ void transpose_item(const float* __restrict__ W, int K, int N, bf16_t* __restrict__ WT, int drow0, LAS float* scr, int k0, int n0, int lane, const float* __restrict__ gk) {
;     const float* src = W + (size_t)k0 * N + n0 + lane;
; #pragma unroll
;     for (int hb = 0; hb < 1; ++hb) {
;         float v[64];
; #pragma unroll
;         for (int i = 0; i < 64; ++i) v[i] = __builtin_nontemporal_load(src + (size_t)(hb * 64 + i) * N);
; __device__ __forceinline__ void transpose_matrix(const float* W, int K, int N, bf16_t* WT, int mode, LAS float* scr, int gw, int NGW, int lane, const float* gA, const float* gB, int it_lo, int it_hi) {
;     const int nblk = N / 64, w8 = gw & 7;
;     for (int j = (it_lo >> 3) + (gw >> 3); j < (it_hi >> 3); j += (NGW >> 3)) {
;         const int kb = (j / nblk) * 8 + w8, nb = j % nblk, n0 = nb * 64;
;         int drow0 = n0;
;         if (mode) { const int up = n0 >= DFF, j = n0 - up * DFF; drow0 = 256 * (j / 128) + (j % 128) + up * 128; }
;         transpose_item(W, K, N, WT, drow0, scr, kb * 64, n0, lane, gA ? (kb * 64 < 1024 ? gA : gB - 1024) : nullptr);
.LBB0_603:
	s_ashr_i32 s6, s8, 31
	s_lshr_b32 s6, s6, 27
	s_add_i32 s6, s8, s6
	s_ashr_i32 s14, s6, 5
	s_lshl_b32 s6, s14, 11
	s_sub_i32 s16, s12, s6
	s_lshl_b32 s6, s14, 9
	s_or_b32 s6, s6, s40
	s_ashr_i32 s7, s6, 31
	s_lshl_b64 s[18:19], s[6:7], 13
	s_add_u32 s15, s10, s18
	s_addc_u32 s18, s11, s19
	s_ashr_i32 s17, s16, 31
	s_lshl_b64 s[16:17], s[16:17], 2
	s_add_u32 s16, s15, s16
	s_addc_u32 s17, s18, s17
	v_lshl_add_u64 v[70:71], s[16:17], 0, v[112:113]
	v_add_co_u32_e32 v0, vcc, s37, v70
	global_load_dword v74, v112, s[16:17] nt
	s_nop 0
	v_addc_co_u32_e32 v1, vcc, 0, v71, vcc
	global_load_dword v75, v[0:1], off nt
	v_add_co_u32_e32 v0, vcc, s33, v70
	s_mul_i32 s14, s14, 0xff500000
	s_nop 0
	v_addc_co_u32_e32 v1, vcc, 0, v71, vcc
	global_load_dword v87, v[0:1], off nt
	v_add_co_u32_e32 v0, vcc, s48, v70
	s_add_i32 s8, s8, s31
	s_nop 0
	v_addc_co_u32_e32 v1, vcc, 0, v71, vcc
	global_load_dword v88, v[0:1], off nt
	v_add_co_u32_e32 v0, vcc, s50, v70
	s_add_i32 s12, s12, s13
	s_nop 0
	v_addc_co_u32_e32 v1, vcc, 0, v71, vcc
	v_add_co_u32_e32 v2, vcc, s51, v70
	global_load_dword v0, v[0:1], off nt
	s_nop 0
	v_addc_co_u32_e32 v3, vcc, 0, v71, vcc
	v_add_co_u32_e32 v14, vcc, s36, v70
	global_load_dword v3, v[2:3], off nt
	s_nop 0
	v_addc_co_u32_e32 v15, vcc, 0, v71, vcc
	global_load_dword v17, v[14:15], off nt
	v_add_co_u32_e32 v14, vcc, s54, v70
	s_cmp_ge_i32 s8, s9
	s_nop 0
	v_addc_co_u32_e32 v15, vcc, 0, v71, vcc
	global_load_dword v27, v[14:15], off nt
	v_add_co_u32_e32 v14, vcc, s24, v70
	s_nop 1
	v_addc_co_u32_e32 v15, vcc, 0, v71, vcc
	global_load_dword v1, v[14:15], off nt
	v_add_co_u32_e32 v14, vcc, s38, v70
	s_nop 1
	v_addc_co_u32_e32 v15, vcc, 0, v71, vcc
	v_add_co_u32_e32 v20, vcc, s46, v70
	global_load_dword v15, v[14:15], off nt
	s_nop 0
	v_addc_co_u32_e32 v21, vcc, 0, v71, vcc
	v_add_co_u32_e32 v22, vcc, s47, v70
	global_load_dword v21, v[20:21], off nt
	s_nop 0
	v_addc_co_u32_e32 v23, vcc, 0, v71, vcc
	global_load_dword v31, v[22:23], off nt
	v_add_co_u32_e32 v22, vcc, s25, v70
	s_nop 1
	v_addc_co_u32_e32 v23, vcc, 0, v71, vcc
	global_load_dword v2, v[22:23], off nt
	v_add_co_u32_e32 v22, vcc, s49, v70
	s_nop 1
	v_addc_co_u32_e32 v23, vcc, 0, v71, vcc
	global_load_dword v19, v[22:23], off nt
	v_add_co_u32_e32 v22, vcc, s52, v70
	s_nop 1
	v_addc_co_u32_e32 v23, vcc, 0, v71, vcc
	global_load_dword v24, v[22:23], off nt
	v_add_co_u32_e32 v22, vcc, s53, v70
	s_nop 1
	v_addc_co_u32_e32 v23, vcc, 0, v71, vcc
	global_load_dword v35, v[22:23], off nt
	v_add_co_u32_e32 v22, vcc, s55, v70
	s_nop 1
	v_addc_co_u32_e32 v23, vcc, 0, v71, vcc
	global_load_dword v14, v[22:23], off nt
	v_add_co_u32_e32 v22, vcc, s56, v70
	s_nop 1
	v_addc_co_u32_e32 v23, vcc, 0, v71, vcc
	v_add_co_u32_e32 v28, vcc, s57, v70
	global_load_dword v22, v[22:23], off nt
	s_nop 0
	v_addc_co_u32_e32 v29, vcc, 0, v71, vcc
	v_add_co_u32_e32 v32, vcc, s58, v70
	global_load_dword v28, v[28:29], off nt
	s_nop 0
	v_addc_co_u32_e32 v33, vcc, 0, v71, vcc
	global_load_dword v39, v[32:33], off nt
	v_add_co_u32_e32 v32, vcc, s59, v70
	s_nop 1
	v_addc_co_u32_e32 v33, vcc, 0, v71, vcc
	global_load_dword v16, v[32:33], off nt
	v_add_co_u32_e32 v32, vcc, s60, v70
	s_nop 1
	v_addc_co_u32_e32 v33, vcc, 0, v71, vcc
	global_load_dword v25, v[32:33], off nt
	v_add_co_u32_e32 v32, vcc, s61, v70
	s_nop 1
	v_addc_co_u32_e32 v33, vcc, 0, v71, vcc
	v_add_co_u32_e32 v36, vcc, s62, v70
	global_load_dword v32, v[32:33], off nt
	s_nop 0
	v_addc_co_u32_e32 v37, vcc, 0, v71, vcc
	global_load_dword v43, v[36:37], off nt
	v_add_co_u32_e32 v36, vcc, s63, v70
	s_nop 1
	v_addc_co_u32_e32 v37, vcc, 0, v71, vcc
	global_load_dword v20, v[36:37], off nt
	v_add_co_u32_e32 v36, vcc, s64, v70
	s_nop 1
	v_addc_co_u32_e32 v37, vcc, 0, v71, vcc
	global_load_dword v29, v[36:37], off nt
	v_add_co_u32_e32 v36, vcc, s65, v70
	s_nop 1
	v_addc_co_u32_e32 v37, vcc, 0, v71, vcc
	v_add_co_u32_e32 v40, vcc, s66, v70
	global_load_dword v36, v[36:37], off nt
	s_nop 0
	v_addc_co_u32_e32 v41, vcc, 0, v71, vcc
	global_load_dword v47, v[40:41], off nt
	v_add_co_u32_e32 v40, vcc, s67, v70
	s_nop 1
	v_addc_co_u32_e32 v41, vcc, 0, v71, vcc
	global_load_dword v23, v[40:41], off nt
	v_add_co_u32_e32 v40, vcc, s68, v70
	s_nop 1
	v_addc_co_u32_e32 v41, vcc, 0, v71, vcc
	global_load_dword v33, v[40:41], off nt
	v_add_co_u32_e32 v40, vcc, s73, v70
	s_nop 1
	v_addc_co_u32_e32 v41, vcc, 0, v71, vcc
	v_add_co_u32_e32 v44, vcc, s74, v70
	global_load_dword v40, v[40:41], off nt
	s_nop 0
	v_addc_co_u32_e32 v45, vcc, 0, v71, vcc
	global_load_dword v51, v[44:45], off nt
	v_add_co_u32_e32 v44, vcc, s75, v70
	s_nop 1
	v_addc_co_u32_e32 v45, vcc, 0, v71, vcc
	global_load_dword v26, v[44:45], off nt
	v_add_co_u32_e32 v44, vcc, s76, v70
	s_nop 1
	v_addc_co_u32_e32 v45, vcc, 0, v71, vcc
	global_load_dword v37, v[44:45], off nt
	v_add_co_u32_e32 v44, vcc, s77, v70
	s_nop 1
	v_addc_co_u32_e32 v45, vcc, 0, v71, vcc
	v_add_co_u32_e32 v48, vcc, s78, v70
	global_load_dword v44, v[44:45], off nt
	s_nop 0
	v_addc_co_u32_e32 v49, vcc, 0, v71, vcc
	global_load_dword v55, v[48:49], off nt
	v_add_co_u32_e32 v48, vcc, s79, v70
	s_nop 1
	v_addc_co_u32_e32 v49, vcc, 0, v71, vcc
	global_load_dword v30, v[48:49], off nt
	v_add_co_u32_e32 v48, vcc, s80, v70
	s_nop 1
	v_addc_co_u32_e32 v49, vcc, 0, v71, vcc
	global_load_dword v41, v[48:49], off nt
	v_add_co_u32_e32 v48, vcc, s81, v70
	s_nop 1
	v_addc_co_u32_e32 v49, vcc, 0, v71, vcc
	v_add_co_u32_e32 v52, vcc, s82, v70
	global_load_dword v48, v[48:49], off nt
	s_nop 0
	v_addc_co_u32_e32 v53, vcc, 0, v71, vcc
	global_load_dword v58, v[52:53], off nt
	v_add_co_u32_e32 v52, vcc, s83, v70
	s_nop 1
	v_addc_co_u32_e32 v53, vcc, 0, v71, vcc
; __device__ __forceinline__ void transpose_item(const float* __restrict__ W, int K, int N, bf16_t* __restrict__ WT, int drow0, LAS float* scr, int k0, int n0, int lane, const float* __restrict__ gk) {
;     ...
;         for (int i = 0; i < 64; ++i) v[i] = __builtin_nontemporal_load(src + (size_t)(hb * 64 + i) * N);
;         if (gk) {
; #pragma unroll
;             for (int i = 0; i < 64; ++i) v[i] *= gk[k0 + hb * 64 + i];
;         }
; #pragma unroll
;         for (int i = 0; i < 64; ++i) scr[(hb * 64 + i) * 65 + lane] = v[i];
;     }
;     asm volatile("s_waitcnt lgkmcnt(0)" ::: "memory");
	global_load_dword v34, v[52:53], off nt
	v_add_co_u32_e32 v52, vcc, s84, v70
	s_nop 1
	v_addc_co_u32_e32 v53, vcc, 0, v71, vcc
	global_load_dword v45, v[52:53], off nt
	v_add_co_u32_e32 v52, vcc, s85, v70
	s_nop 1
	v_addc_co_u32_e32 v53, vcc, 0, v71, vcc
	v_add_co_u32_e32 v56, vcc, s86, v70
	global_load_dword v52, v[52:53], off nt
	s_nop 0
	v_addc_co_u32_e32 v57, vcc, 0, v71, vcc
	global_load_dword v61, v[56:57], off nt
	v_add_co_u32_e32 v56, vcc, s87, v70
	s_nop 1
	v_addc_co_u32_e32 v57, vcc, 0, v71, vcc
	global_load_dword v38, v[56:57], off nt
	v_add_co_u32_e32 v56, vcc, s88, v70
	s_nop 1
	v_addc_co_u32_e32 v57, vcc, 0, v71, vcc
	global_load_dword v49, v[56:57], off nt
	v_add_co_u32_e32 v56, vcc, s89, v70
	s_nop 1
	v_addc_co_u32_e32 v57, vcc, 0, v71, vcc
	v_add_co_u32_e32 v62, vcc, s90, v70
	global_load_dword v56, v[56:57], off nt
	s_nop 0
	v_addc_co_u32_e32 v63, vcc, 0, v71, vcc
	global_load_dword v64, v[62:63], off nt
	v_add_co_u32_e32 v62, vcc, s91, v70
	s_nop 1
	v_addc_co_u32_e32 v63, vcc, 0, v71, vcc
	global_load_dword v42, v[62:63], off nt
	v_add_co_u32_e32 v62, vcc, s92, v70
	s_nop 1
	v_addc_co_u32_e32 v63, vcc, 0, v71, vcc
	global_load_dword v53, v[62:63], off nt
	v_add_co_u32_e32 v62, vcc, s93, v70
	s_nop 1
	v_addc_co_u32_e32 v63, vcc, 0, v71, vcc
	global_load_dword v59, v[62:63], off nt
	v_add_co_u32_e32 v62, vcc, s94, v70
	s_nop 1
	v_addc_co_u32_e32 v63, vcc, 0, v71, vcc
	global_load_dword v66, v[62:63], off nt
	v_add_co_u32_e32 v62, vcc, s95, v70
	s_nop 1
	v_addc_co_u32_e32 v63, vcc, 0, v71, vcc
	global_load_dword v46, v[62:63], off nt
	v_add_co_u32_e32 v62, vcc, s96, v70
	s_nop 1
	v_addc_co_u32_e32 v63, vcc, 0, v71, vcc
	global_load_dword v57, v[62:63], off nt
	v_add_co_u32_e32 v62, vcc, s97, v70
	s_nop 1
	v_addc_co_u32_e32 v63, vcc, 0, v71, vcc
	v_add_co_u32_e32 v68, vcc, s71, v70
	global_load_dword v62, v[62:63], off nt
	s_nop 0
	v_addc_co_u32_e32 v69, vcc, 0, v71, vcc
	v_add_co_u32_e32 v72, vcc, s39, v70
	global_load_dword v68, v[68:69], off nt
	s_nop 0
	v_addc_co_u32_e32 v73, vcc, 0, v71, vcc
	global_load_dword v50, v[72:73], off nt
	v_add_co_u32_e32 v72, vcc, s72, v70
	s_nop 1
	v_addc_co_u32_e32 v73, vcc, 0, v71, vcc
	global_load_dword v60, v[72:73], off nt
	v_add_co_u32_e32 v72, vcc, s29, v70
	s_nop 1
	v_addc_co_u32_e32 v73, vcc, 0, v71, vcc
	global_load_dword v65, v[72:73], off nt
	v_add_co_u32_e32 v72, vcc, s69, v70
	s_nop 1
	v_addc_co_u32_e32 v73, vcc, 0, v71, vcc
	global_load_dword v69, v[72:73], off nt
	v_add_co_u32_e32 v72, vcc, s30, v70
	s_nop 1
	v_addc_co_u32_e32 v73, vcc, 0, v71, vcc
	global_load_dword v54, v[72:73], off nt
	v_add_co_u32_e32 v72, vcc, s43, v70
	s_nop 1
	v_addc_co_u32_e32 v73, vcc, 0, v71, vcc
	global_load_dword v63, v[72:73], off nt
	v_add_co_u32_e32 v72, vcc, s23, v70
	s_nop 1
	v_addc_co_u32_e32 v73, vcc, 0, v71, vcc
	v_add_co_u32_e32 v70, vcc, s28, v70
	global_load_dword v67, v[72:73], off nt
	s_nop 0
	v_addc_co_u32_e32 v71, vcc, 0, v71, vcc
	global_load_dword v70, v[70:71], off nt
	v_add_u32_e32 v71, 0x400, v76
	s_waitcnt vmcnt(0)
	ds_write2_b32 v76, v74, v75 offset1:65
	ds_write2_b32 v76, v87, v88 offset0:130 offset1:195
	ds_write2_b32 v71, v0, v3 offset0:4 offset1:69
	ds_write2_b32 v71, v17, v27 offset0:134 offset1:199
	v_add_u32_e32 v0, 0x800, v76
	ds_write2_b32 v0, v1, v15 offset0:8 offset1:73
	ds_write2_b32 v0, v21, v31 offset0:138 offset1:203
	v_add_u32_e32 v0, 0xc00, v76
	ds_write2_b32 v0, v2, v19 offset0:12 offset1:77
	ds_write2_b32 v0, v24, v35 offset0:142 offset1:207
	v_add_u32_e32 v0, 0x1000, v76
	ds_write2_b32 v0, v14, v22 offset0:16 offset1:81
	ds_write2_b32 v0, v28, v39 offset0:146 offset1:211
	v_add_u32_e32 v0, 0x1400, v76
	ds_write2_b32 v0, v16, v25 offset0:20 offset1:85
	ds_write2_b32 v0, v32, v43 offset0:150 offset1:215
	v_add_u32_e32 v0, 0x1800, v76
	ds_write2_b32 v0, v20, v29 offset0:24 offset1:89
	ds_write2_b32 v0, v36, v47 offset0:154 offset1:219
	v_add_u32_e32 v0, 0x1c00, v76
	ds_write2_b32 v0, v23, v33 offset0:28 offset1:93
	ds_write2_b32 v0, v40, v51 offset0:158 offset1:223
	v_add_u32_e32 v0, 0x2000, v76
	ds_write2_b32 v0, v26, v37 offset0:32 offset1:97
	ds_write2_b32 v0, v44, v55 offset0:162 offset1:227
	v_add_u32_e32 v0, 0x2400, v76
	ds_write2_b32 v0, v30, v41 offset0:36 offset1:101
	ds_write2_b32 v0, v48, v58 offset0:166 offset1:231
	v_add_u32_e32 v0, 0x2800, v76
	ds_write2_b32 v0, v34, v45 offset0:40 offset1:105
	ds_write2_b32 v0, v52, v61 offset0:170 offset1:235
	v_add_u32_e32 v0, 0x2c00, v76
	ds_write2_b32 v0, v38, v49 offset0:44 offset1:109
	ds_write2_b32 v0, v56, v64 offset0:174 offset1:239
	v_add_u32_e32 v0, 0x3000, v76
	ds_write2_b32 v0, v42, v53 offset0:48 offset1:113
	ds_write2_b32 v0, v59, v66 offset0:178 offset1:243
	v_add_u32_e32 v0, 0x3400, v76
	ds_write2_b32 v0, v46, v57 offset0:52 offset1:117
	ds_write2_b32 v0, v62, v68 offset0:182 offset1:247
	v_add_u32_e32 v0, 0x3800, v76
	ds_write2_b32 v0, v50, v60 offset0:56 offset1:121
	ds_write2_b32 v0, v65, v69 offset0:186 offset1:251
	v_add_u32_e32 v0, 0x3c00, v76
	ds_write2_b32 v0, v54, v63 offset0:60 offset1:125
	ds_write2_b32 v0, v67, v70 offset0:190 offset1:255
	s_waitcnt lgkmcnt(0)
; #define LAS __attribute__((address_space(3)))
; __device__ __forceinline__ unsigned pk2(float lo, float hi) { unsigned r; asm volatile("v_cvt_pk_bf16_f32 %0, %1, %2" : "=v"(r) : "v"(lo), "v"(hi)); return r; }
; __device__ __forceinline__ void transpose_item(const float* __restrict__ W, int K, int N, bf16_t* __restrict__ WT, int drow0, LAS float* scr, int k0, int n0, int lane, const float* __restrict__ gk) {
;     ...
;     const int c = lane & 7;
; #pragma unroll
;     for (int j = 0; j < 8; ++j) { const int n = (lane >> 3) + 8 * j; const LAS float* s = scr + (8 * c) * 65 + n;
;         u32x4 o; o.x = pk2(s[0 * 65], s[1 * 65]); o.y = pk2(s[2 * 65], s[3 * 65]); o.z = pk2(s[4 * 65], s[5 * 65]); o.w = pk2(s[6 * 65], s[7 * 65]);
;         *(u32x4*)(WT + (size_t)(drow0 + n) * K + k0 + 8 * c) = o; }
;     asm volatile("s_waitcnt lgkmcnt(0)" ::: "memory");
	v_add_u32_e32 v19, 0x400, v78
	ds_read2_b32 v[22:23], v78 offset1:65
	ds_read2_b32 v[24:25], v78 offset0:130 offset1:195
	ds_read2_b32 v[26:27], v19 offset0:4 offset1:69
	ds_read2_b32 v[28:29], v19 offset0:134 offset1:199
	ds_read2_b32 v[30:31], v78 offset0:8 offset1:73
	ds_read2_b32 v[32:33], v78 offset0:138 offset1:203
	ds_read2_b32 v[34:35], v19 offset0:12 offset1:77
	ds_read2_b32 v[36:37], v19 offset0:142 offset1:207
	s_waitcnt lgkmcnt(4)
	v_cvt_pk_bf16_f32 v0, v22, v23
	v_cvt_pk_bf16_f32 v1, v24, v25
	v_cvt_pk_bf16_f32 v2, v26, v27
	v_cvt_pk_bf16_f32 v3, v28, v29
	v_add_u32_e32 v16, s14, v18
	v_lshl_add_u64 v[14:15], s[6:7], 1, v[12:13]
	v_ashrrev_i32_e32 v17, 31, v16
	v_lshl_add_u64 v[20:21], v[16:17], 1, v[14:15]
	global_store_dwordx4 v[20:21], v[0:3], off
	s_nop 1
	ds_read2_b32 v[22:23], v78 offset0:16 offset1:81
	ds_read2_b32 v[24:25], v78 offset0:146 offset1:211
	ds_read2_b32 v[26:27], v19 offset0:20 offset1:85
	ds_read2_b32 v[28:29], v19 offset0:150 offset1:215
	s_waitcnt lgkmcnt(4)
	s_mul_i32 s6, s31, 0x58000
	v_cvt_pk_bf16_f32 v0, v30, v31
	v_cvt_pk_bf16_f32 v1, v32, v33
	v_cvt_pk_bf16_f32 v2, v34, v35
	v_cvt_pk_bf16_f32 v3, v36, v37
	v_add_u32_e32 v20, 0xb000, v16
	v_ashrrev_i32_e32 v21, 31, v20
	v_lshl_add_u64 v[20:21], v[20:21], 1, v[14:15]
	global_store_dwordx4 v[20:21], v[0:3], off
	s_nop 1
	ds_read2_b32 v[30:31], v78 offset0:24 offset1:89
	ds_read2_b32 v[32:33], v78 offset0:154 offset1:219
	ds_read2_b32 v[34:35], v19 offset0:28 offset1:93
	ds_read2_b32 v[36:37], v19 offset0:158 offset1:223
	s_waitcnt lgkmcnt(4)
	v_add_u32_e32 v18, s6, v18
	v_cvt_pk_bf16_f32 v0, v22, v23
	v_cvt_pk_bf16_f32 v1, v24, v25
	v_cvt_pk_bf16_f32 v2, v26, v27
	v_cvt_pk_bf16_f32 v3, v28, v29
	v_add_u32_e32 v20, 0x16000, v16
	v_ashrrev_i32_e32 v21, 31, v20
	v_lshl_add_u64 v[20:21], v[20:21], 1, v[14:15]
	global_store_dwordx4 v[20:21], v[0:3], off
	s_nop 1
	ds_read2_b32 v[22:23], v78 offset0:32 offset1:97
	ds_read2_b32 v[24:25], v78 offset0:162 offset1:227
	ds_read2_b32 v[26:27], v19 offset0:36 offset1:101
	ds_read2_b32 v[28:29], v19 offset0:166 offset1:231
	s_waitcnt lgkmcnt(4)
	v_cvt_pk_bf16_f32 v0, v30, v31
	v_cvt_pk_bf16_f32 v1, v32, v33
	v_cvt_pk_bf16_f32 v2, v34, v35
	v_cvt_pk_bf16_f32 v3, v36, v37
	v_add_u32_e32 v20, 0x21000, v16
	v_ashrrev_i32_e32 v21, 31, v20
	v_lshl_add_u64 v[20:21], v[20:21], 1, v[14:15]
	global_store_dwordx4 v[20:21], v[0:3], off
	s_nop 1
	ds_read2_b32 v[30:31], v78 offset0:40 offset1:105
	ds_read2_b32 v[32:33], v78 offset0:170 offset1:235
	ds_read2_b32 v[34:35], v19 offset0:44 offset1:109
	ds_read2_b32 v[36:37], v19 offset0:174 offset1:239
	s_waitcnt lgkmcnt(4)
	v_cvt_pk_bf16_f32 v0, v22, v23
	v_cvt_pk_bf16_f32 v1, v24, v25
	v_cvt_pk_bf16_f32 v2, v26, v27
	v_cvt_pk_bf16_f32 v3, v28, v29
	v_add_u32_e32 v20, 0x2c000, v16
	v_ashrrev_i32_e32 v21, 31, v20
	v_lshl_add_u64 v[20:21], v[20:21], 1, v[14:15]
	global_store_dwordx4 v[20:21], v[0:3], off
	s_nop 1
	ds_read2_b32 v[22:23], v78 offset0:48 offset1:113
	ds_read2_b32 v[24:25], v78 offset0:178 offset1:243
	ds_read2_b32 v[26:27], v19 offset0:52 offset1:117
	ds_read2_b32 v[28:29], v19 offset0:182 offset1:247
	s_waitcnt lgkmcnt(4)
	v_cvt_pk_bf16_f32 v0, v30, v31
	v_cvt_pk_bf16_f32 v1, v32, v33
	v_cvt_pk_bf16_f32 v2, v34, v35
	v_cvt_pk_bf16_f32 v3, v36, v37
	v_add_u32_e32 v20, 0x37000, v16
	v_ashrrev_i32_e32 v21, 31, v20
	v_lshl_add_u64 v[20:21], v[20:21], 1, v[14:15]
	global_store_dwordx4 v[20:21], v[0:3], off
	s_nop 1
	ds_read2_b32 v[30:31], v78 offset0:56 offset1:121
	ds_read2_b32 v[32:33], v78 offset0:186 offset1:251
	ds_read2_b32 v[34:35], v19 offset0:60 offset1:125
	ds_read2_b32 v[36:37], v19 offset0:190 offset1:255
	s_waitcnt lgkmcnt(4)
	v_cvt_pk_bf16_f32 v0, v22, v23
	v_cvt_pk_bf16_f32 v1, v24, v25
	v_cvt_pk_bf16_f32 v2, v26, v27
	v_cvt_pk_bf16_f32 v3, v28, v29
	v_add_u32_e32 v20, 0x42000, v16
	v_ashrrev_i32_e32 v21, 31, v20
	v_lshl_add_u64 v[20:21], v[20:21], 1, v[14:15]
	global_store_dwordx4 v[20:21], v[0:3], off
	s_nop 1
	s_waitcnt lgkmcnt(0)
	v_add_u32_e32 v16, 0x4d000, v16
	v_cvt_pk_bf16_f32 v0, v30, v31
	v_ashrrev_i32_e32 v17, 31, v16
	v_cvt_pk_bf16_f32 v1, v32, v33
	v_lshl_add_u64 v[14:15], v[16:17], 1, v[14:15]
	v_cvt_pk_bf16_f32 v2, v34, v35
	v_cvt_pk_bf16_f32 v3, v36, v37
	global_store_dwordx4 v[14:15], v[0:3], off
	s_nop 1
	s_waitcnt lgkmcnt(0)
	s_cbranch_scc0 .LBB0_603

; #define LAS __attribute__((address_space(3)))
; __device__ __forceinline__ void transpose_item(const float* __restrict__ W, int K, int N, bf16_t* __restrict__ WT, int drow0, LAS float* scr, int k0, int n0, int lane, const float* __restrict__ gk) {
;     const float* src = W + (size_t)k0 * N + n0 + lane;
; #pragma unroll
;     for (int hb = 0; hb < 1; ++hb) {
;         float v[64];
; #pragma unroll
;         for (int i = 0; i < 64; ++i) v[i] = __builtin_nontemporal_load(src + (size_t)(hb * 64 + i) * N);
; __device__ __forceinline__ void transpose_matrix(const float* W, int K, int N, bf16_t* WT, int mode, LAS float* scr, int gw, int NGW, int lane, const float* gA, const float* gB, int it_lo, int it_hi) {
;     const int nblk = N / 64, w8 = gw & 7;
;     for (int j = (it_lo >> 3) + (gw >> 3); j < (it_hi >> 3); j += (NGW >> 3)) {
;         const int kb = (j / nblk) * 8 + w8, nb = j % nblk, n0 = nb * 64;
;         int drow0 = n0;
;         if (mode) { const int up = n0 >= DFF, j = n0 - up * DFF; drow0 = 256 * (j / 128) + (j % 128) + up * 128; }
;         transpose_item(W, K, N, WT, drow0, scr, kb * 64, n0, lane, gA ? (kb * 64 < 1024 ? gA : gB - 1024) : nullptr);
.LBB0_607:
	s_mul_hi_i32 s6, s10, 0x38e38e39
	s_lshr_b32 s7, s6, 31
	s_ashr_i32 s6, s6, 4
	s_add_i32 s7, s6, s7
	s_mul_i32 s6, s7, 0xffffee00
	s_lshl_b32 s7, s7, 9
	s_or_b32 s8, s7, s40
	s_add_i32 s6, s14, s6
	s_ashr_i32 s9, s8, 31
	s_mul_i32 s16, s8, 0x4800
	s_mul_hi_i32 s7, s8, 0x4800
	s_add_u32 s18, s12, s16
	s_addc_u32 s19, s13, s7
	s_ashr_i32 s7, s6, 31
	s_lshl_b64 s[16:17], s[6:7], 2
	s_add_u32 s16, s18, s16
	s_addc_u32 s17, s19, s17
	v_lshl_add_u64 v[70:71], s[16:17], 0, v[112:113]
	v_add_co_u32_e32 v0, vcc, s24, v70
	global_load_dword v74, v112, s[16:17] nt
	s_nop 0
	v_addc_co_u32_e32 v1, vcc, 0, v71, vcc
	global_load_dword v75, v[0:1], off offset:2048 nt
	v_add_co_u32_e32 v0, vcc, s30, v70
	s_add_i32 s10, s10, s31
	s_nop 0
	v_addc_co_u32_e32 v1, vcc, 0, v71, vcc
	global_load_dword v87, v[0:1], off nt
	v_add_co_u32_e32 v0, vcc, s23, v70
	s_add_i32 s14, s14, s15
	s_nop 0
	v_addc_co_u32_e32 v1, vcc, 0, v71, vcc
	global_load_dword v88, v[0:1], off offset:2048 nt
	v_add_co_u32_e32 v0, vcc, s33, v70
	s_cmp_ge_i32 s10, s11
	s_nop 0
	v_addc_co_u32_e32 v1, vcc, 0, v71, vcc
	v_add_co_u32_e32 v2, vcc, s36, v70
	global_load_dword v0, v[0:1], off nt
	s_nop 0
	v_addc_co_u32_e32 v3, vcc, 0, v71, vcc
	v_add_co_u32_e32 v14, vcc, s28, v70
	global_load_dword v3, v[2:3], off offset:2048 nt
	s_nop 0
	v_addc_co_u32_e32 v15, vcc, 0, v71, vcc
	global_load_dword v17, v[14:15], off nt
	v_add_co_u32_e32 v14, vcc, s29, v70
	s_nop 1
	v_addc_co_u32_e32 v15, vcc, 0, v71, vcc
	global_load_dword v26, v[14:15], off offset:2048 nt
	v_add_co_u32_e32 v14, vcc, s37, v70
	s_nop 1
	v_addc_co_u32_e32 v15, vcc, 0, v71, vcc
	global_load_dword v1, v[14:15], off nt
	v_add_co_u32_e32 v14, vcc, s38, v70
	s_nop 1
	v_addc_co_u32_e32 v15, vcc, 0, v71, vcc
	v_add_co_u32_e32 v18, vcc, s43, v70
	global_load_dword v15, v[14:15], off offset:2048 nt
	s_nop 0
	v_addc_co_u32_e32 v19, vcc, 0, v71, vcc
	global_load_dword v20, v[18:19], off nt
	v_add_co_u32_e32 v18, vcc, s53, v70
	s_nop 1
	v_addc_co_u32_e32 v19, vcc, 0, v71, vcc
	global_load_dword v30, v[18:19], off offset:2048 nt
	v_add_co_u32_e32 v18, vcc, s46, v70
	s_nop 1
	v_addc_co_u32_e32 v19, vcc, 0, v71, vcc
	global_load_dword v2, v[18:19], off nt
	v_add_co_u32_e32 v18, vcc, s47, v70
	s_nop 1
	v_addc_co_u32_e32 v19, vcc, 0, v71, vcc
	v_add_co_u32_e32 v22, vcc, s54, v70
	global_load_dword v18, v[18:19], off offset:2048 nt
	s_nop 0
	v_addc_co_u32_e32 v23, vcc, 0, v71, vcc
	v_add_co_u32_e32 v24, vcc, s55, v70
	global_load_dword v23, v[22:23], off nt
	s_nop 0
	v_addc_co_u32_e32 v25, vcc, 0, v71, vcc
	global_load_dword v34, v[24:25], off offset:2048 nt
	v_add_co_u32_e32 v24, vcc, s48, v70
	s_nop 1
	v_addc_co_u32_e32 v25, vcc, 0, v71, vcc
	global_load_dword v14, v[24:25], off nt
	v_add_co_u32_e32 v24, vcc, s49, v70
	s_nop 1
	v_addc_co_u32_e32 v25, vcc, 0, v71, vcc
	global_load_dword v21, v[24:25], off offset:2048 nt
	v_add_co_u32_e32 v24, vcc, s56, v70
	s_nop 1
	v_addc_co_u32_e32 v25, vcc, 0, v71, vcc
	global_load_dword v27, v[24:25], off nt
	v_add_co_u32_e32 v24, vcc, s57, v70
	s_nop 1
	v_addc_co_u32_e32 v25, vcc, 0, v71, vcc
	global_load_dword v38, v[24:25], off offset:2048 nt
	v_add_co_u32_e32 v24, vcc, s50, v70
	s_nop 1
	v_addc_co_u32_e32 v25, vcc, 0, v71, vcc
	global_load_dword v16, v[24:25], off nt
	v_add_co_u32_e32 v24, vcc, s51, v70
	s_nop 1
	v_addc_co_u32_e32 v25, vcc, 0, v71, vcc
	v_add_co_u32_e32 v28, vcc, s58, v70
	global_load_dword v24, v[24:25], off offset:2048 nt
	s_nop 0
	v_addc_co_u32_e32 v29, vcc, 0, v71, vcc
	global_load_dword v31, v[28:29], off nt
	v_add_co_u32_e32 v28, vcc, s59, v70
	s_nop 1
	v_addc_co_u32_e32 v29, vcc, 0, v71, vcc
	global_load_dword v42, v[28:29], off offset:2048 nt
	v_add_co_u32_e32 v28, vcc, s52, v70
	s_nop 1
	v_addc_co_u32_e32 v29, vcc, 0, v71, vcc
	global_load_dword v19, v[28:29], off nt
	v_add_co_u32_e32 v28, vcc, s71, v70
	s_nop 1
	v_addc_co_u32_e32 v29, vcc, 0, v71, vcc
	v_add_co_u32_e32 v32, vcc, s60, v70
	global_load_dword v28, v[28:29], off offset:2048 nt
	s_nop 0
	v_addc_co_u32_e32 v33, vcc, 0, v71, vcc
	global_load_dword v35, v[32:33], off nt
	v_add_co_u32_e32 v32, vcc, s61, v70
	s_nop 1
	v_addc_co_u32_e32 v33, vcc, 0, v71, vcc
	global_load_dword v46, v[32:33], off offset:2048 nt
	v_add_co_u32_e32 v32, vcc, s39, v70
	s_nop 1
	v_addc_co_u32_e32 v33, vcc, 0, v71, vcc
	global_load_dword v22, v[32:33], off nt
	v_add_co_u32_e32 v32, vcc, s62, v70
	s_nop 1
	v_addc_co_u32_e32 v33, vcc, 0, v71, vcc
	v_add_co_u32_e32 v36, vcc, s63, v70
	global_load_dword v32, v[32:33], off offset:2048 nt
	s_nop 0
	v_addc_co_u32_e32 v37, vcc, 0, v71, vcc
	global_load_dword v39, v[36:37], off nt
	v_add_co_u32_e32 v36, vcc, s64, v70
	s_nop 1
	v_addc_co_u32_e32 v37, vcc, 0, v71, vcc
	global_load_dword v50, v[36:37], off offset:2048 nt
	v_add_co_u32_e32 v36, vcc, s25, v70
	s_nop 1
	v_addc_co_u32_e32 v37, vcc, 0, v71, vcc
	global_load_dword v25, v[36:37], off nt
	v_add_co_u32_e32 v36, vcc, s65, v70
	s_nop 1
	v_addc_co_u32_e32 v37, vcc, 0, v71, vcc
	v_add_co_u32_e32 v40, vcc, s66, v70
	global_load_dword v36, v[36:37], off offset:2048 nt
	s_nop 0
	v_addc_co_u32_e32 v41, vcc, 0, v71, vcc
	global_load_dword v43, v[40:41], off nt
	v_add_co_u32_e32 v40, vcc, s67, v70
	s_nop 1
	v_addc_co_u32_e32 v41, vcc, 0, v71, vcc
	global_load_dword v54, v[40:41], off offset:2048 nt
	v_add_co_u32_e32 v40, vcc, s68, v70
	s_nop 1
	v_addc_co_u32_e32 v41, vcc, 0, v71, vcc
	global_load_dword v29, v[40:41], off nt
	v_add_co_u32_e32 v40, vcc, s69, v70
	s_nop 1
	v_addc_co_u32_e32 v41, vcc, 0, v71, vcc
	v_add_co_u32_e32 v44, vcc, s72, v70
	global_load_dword v40, v[40:41], off offset:2048 nt
	s_nop 0
	v_addc_co_u32_e32 v45, vcc, 0, v71, vcc
; __device__ __forceinline__ void transpose_item(const float* __restrict__ W, int K, int N, bf16_t* __restrict__ WT, int drow0, LAS float* scr, int k0, int n0, int lane, const float* __restrict__ gk) {
;     ...
;         for (int i = 0; i < 64; ++i) v[i] = __builtin_nontemporal_load(src + (size_t)(hb * 64 + i) * N);
;         if (gk) {
; #pragma unroll
;             for (int i = 0; i < 64; ++i) v[i] *= gk[k0 + hb * 64 + i];
;         }
; #pragma unroll
;         for (int i = 0; i < 64; ++i) scr[(hb * 64 + i) * 65 + lane] = v[i];
;     }
;     asm volatile("s_waitcnt lgkmcnt(0)" ::: "memory");
	global_load_dword v47, v[44:45], off nt
	v_add_co_u32_e32 v44, vcc, s73, v70
	s_nop 1
	v_addc_co_u32_e32 v45, vcc, 0, v71, vcc
	global_load_dword v57, v[44:45], off offset:2048 nt
	v_add_co_u32_e32 v44, vcc, s74, v70
	s_nop 1
	v_addc_co_u32_e32 v45, vcc, 0, v71, vcc
	global_load_dword v33, v[44:45], off nt
	v_add_co_u32_e32 v44, vcc, s75, v70
	s_nop 1
	v_addc_co_u32_e32 v45, vcc, 0, v71, vcc
	v_add_co_u32_e32 v48, vcc, s76, v70
	global_load_dword v44, v[44:45], off offset:2048 nt
	s_nop 0
	v_addc_co_u32_e32 v49, vcc, 0, v71, vcc
	global_load_dword v51, v[48:49], off nt
	v_add_co_u32_e32 v48, vcc, s77, v70
	s_nop 1
	v_addc_co_u32_e32 v49, vcc, 0, v71, vcc
	global_load_dword v60, v[48:49], off offset:2048 nt
	v_add_co_u32_e32 v48, vcc, s78, v70
	s_nop 1
	v_addc_co_u32_e32 v49, vcc, 0, v71, vcc
	global_load_dword v37, v[48:49], off nt
	v_add_co_u32_e32 v48, vcc, s79, v70
	s_nop 1
	v_addc_co_u32_e32 v49, vcc, 0, v71, vcc
	v_add_co_u32_e32 v52, vcc, s80, v70
	global_load_dword v48, v[48:49], off offset:2048 nt
	s_nop 0
	v_addc_co_u32_e32 v53, vcc, 0, v71, vcc
	global_load_dword v55, v[52:53], off nt
	v_add_co_u32_e32 v52, vcc, s81, v70
	s_nop 1
	v_addc_co_u32_e32 v53, vcc, 0, v71, vcc
	global_load_dword v63, v[52:53], off offset:2048 nt
	v_add_co_u32_e32 v52, vcc, s82, v70
	s_nop 1
	v_addc_co_u32_e32 v53, vcc, 0, v71, vcc
	global_load_dword v41, v[52:53], off nt
	v_add_co_u32_e32 v52, vcc, s83, v70
	s_nop 1
	v_addc_co_u32_e32 v53, vcc, 0, v71, vcc
	v_add_co_u32_e32 v58, vcc, s84, v70
	global_load_dword v52, v[52:53], off offset:2048 nt
	s_nop 0
	v_addc_co_u32_e32 v59, vcc, 0, v71, vcc
	v_add_co_u32_e32 v64, vcc, s85, v70
	global_load_dword v58, v[58:59], off nt
	s_nop 0
	v_addc_co_u32_e32 v65, vcc, 0, v71, vcc
	v_add_co_u32_e32 v66, vcc, s86, v70
	global_load_dword v65, v[64:65], off offset:2048 nt
	s_nop 0
	v_addc_co_u32_e32 v67, vcc, 0, v71, vcc
	global_load_dword v45, v[66:67], off nt
	v_add_co_u32_e32 v66, vcc, s87, v70
	s_nop 1
	v_addc_co_u32_e32 v67, vcc, 0, v71, vcc
	global_load_dword v56, v[66:67], off offset:2048 nt
	v_add_co_u32_e32 v66, vcc, s88, v70
	s_nop 1
	v_addc_co_u32_e32 v67, vcc, 0, v71, vcc
	global_load_dword v61, v[66:67], off nt
	v_add_co_u32_e32 v66, vcc, s89, v70
	s_nop 1
	v_addc_co_u32_e32 v67, vcc, 0, v71, vcc
	v_add_co_u32_e32 v68, vcc, s90, v70
	global_load_dword v67, v[66:67], off offset:2048 nt
	s_nop 0
	v_addc_co_u32_e32 v69, vcc, 0, v71, vcc
	global_load_dword v49, v[68:69], off nt
	v_add_co_u32_e32 v68, vcc, s91, v70
	s_nop 1
	v_addc_co_u32_e32 v69, vcc, 0, v71, vcc
	global_load_dword v59, v[68:69], off offset:2048 nt
	v_add_co_u32_e32 v68, vcc, s92, v70
	s_nop 1
	v_addc_co_u32_e32 v69, vcc, 0, v71, vcc
	global_load_dword v64, v[68:69], off nt
	v_add_co_u32_e32 v68, vcc, s93, v70
	s_nop 1
	v_addc_co_u32_e32 v69, vcc, 0, v71, vcc
	v_add_co_u32_e32 v72, vcc, s94, v70
	global_load_dword v68, v[68:69], off offset:2048 nt
	s_nop 0
	v_addc_co_u32_e32 v73, vcc, 0, v71, vcc
	global_load_dword v53, v[72:73], off nt
	v_add_co_u32_e32 v72, vcc, s95, v70
	s_nop 1
	v_addc_co_u32_e32 v73, vcc, 0, v71, vcc
	global_load_dword v62, v[72:73], off offset:2048 nt
	v_add_co_u32_e32 v72, vcc, s96, v70
	s_nop 1
	v_addc_co_u32_e32 v73, vcc, 0, v71, vcc
	v_add_co_u32_e32 v70, vcc, s97, v70
	global_load_dword v66, v[72:73], off nt
	s_nop 0
	v_addc_co_u32_e32 v71, vcc, 0, v71, vcc
	global_load_dword v69, v[70:71], off offset:2048 nt
	v_add_u32_e32 v70, 0x400, v76
	s_waitcnt vmcnt(0)
	ds_write2_b32 v76, v74, v75 offset1:65
	ds_write2_b32 v76, v87, v88 offset0:130 offset1:195
	ds_write2_b32 v70, v0, v3 offset0:4 offset1:69
	ds_write2_b32 v70, v17, v26 offset0:134 offset1:199
	v_add_u32_e32 v0, 0x800, v76
	ds_write2_b32 v0, v1, v15 offset0:8 offset1:73
	ds_write2_b32 v0, v20, v30 offset0:138 offset1:203
	v_add_u32_e32 v0, 0xc00, v76
	ds_write2_b32 v0, v2, v18 offset0:12 offset1:77
	ds_write2_b32 v0, v23, v34 offset0:142 offset1:207
	v_add_u32_e32 v0, 0x1000, v76
	ds_write2_b32 v0, v14, v21 offset0:16 offset1:81
	ds_write2_b32 v0, v27, v38 offset0:146 offset1:211
	v_add_u32_e32 v0, 0x1400, v76
	ds_write2_b32 v0, v16, v24 offset0:20 offset1:85
	ds_write2_b32 v0, v31, v42 offset0:150 offset1:215
	v_add_u32_e32 v0, 0x1800, v76
	ds_write2_b32 v0, v19, v28 offset0:24 offset1:89
	ds_write2_b32 v0, v35, v46 offset0:154 offset1:219
	v_add_u32_e32 v0, 0x1c00, v76
	ds_write2_b32 v0, v22, v32 offset0:28 offset1:93
	ds_write2_b32 v0, v39, v50 offset0:158 offset1:223
	v_add_u32_e32 v0, 0x2000, v76
	ds_write2_b32 v0, v25, v36 offset0:32 offset1:97
	ds_write2_b32 v0, v43, v54 offset0:162 offset1:227
	v_add_u32_e32 v0, 0x2400, v76
	ds_write2_b32 v0, v29, v40 offset0:36 offset1:101
	ds_write2_b32 v0, v47, v57 offset0:166 offset1:231
	v_add_u32_e32 v0, 0x2800, v76
	ds_write2_b32 v0, v33, v44 offset0:40 offset1:105
	ds_write2_b32 v0, v51, v60 offset0:170 offset1:235
	v_add_u32_e32 v0, 0x2c00, v76
	ds_write2_b32 v0, v37, v48 offset0:44 offset1:109
	ds_write2_b32 v0, v55, v63 offset0:174 offset1:239
	v_add_u32_e32 v0, 0x3000, v76
	ds_write2_b32 v0, v41, v52 offset0:48 offset1:113
	ds_write2_b32 v0, v58, v65 offset0:178 offset1:243
	v_add_u32_e32 v0, 0x3400, v76
	ds_write2_b32 v0, v45, v56 offset0:52 offset1:117
	ds_write2_b32 v0, v61, v67 offset0:182 offset1:247
	v_add_u32_e32 v0, 0x3800, v76
	ds_write2_b32 v0, v49, v59 offset0:56 offset1:121
	ds_write2_b32 v0, v64, v68 offset0:186 offset1:251
	v_add_u32_e32 v0, 0x3c00, v76
	ds_write2_b32 v0, v53, v62 offset0:60 offset1:125
	ds_write2_b32 v0, v66, v69 offset0:190 offset1:255
	s_waitcnt lgkmcnt(0)
; #define LAS __attribute__((address_space(3)))
; __device__ __forceinline__ unsigned pk2(float lo, float hi) { unsigned r; asm volatile("v_cvt_pk_bf16_f32 %0, %1, %2" : "=v"(r) : "v"(lo), "v"(hi)); return r; }
; __device__ __forceinline__ void transpose_item(const float* __restrict__ W, int K, int N, bf16_t* __restrict__ WT, int drow0, LAS float* scr, int k0, int n0, int lane, const float* __restrict__ gk) {
;     ...
;     const int c = lane & 7;
; #pragma unroll
;     for (int j = 0; j < 8; ++j) { const int n = (lane >> 3) + 8 * j; const LAS float* s = scr + (8 * c) * 65 + n;
;         u32x4 o; o.x = pk2(s[0 * 65], s[1 * 65]); o.y = pk2(s[2 * 65], s[3 * 65]); o.z = pk2(s[4 * 65], s[5 * 65]); o.w = pk2(s[6 * 65], s[7 * 65]);
;         *(u32x4*)(WT + (size_t)(drow0 + n) * K + k0 + 8 * c) = o; }
;     asm volatile("s_waitcnt lgkmcnt(0)" ::: "memory");
	v_add_u32_e32 v20, 0x400, v78
	ds_read2_b32 v[22:23], v78 offset1:65
	ds_read2_b32 v[24:25], v78 offset0:130 offset1:195
	ds_read2_b32 v[26:27], v20 offset0:4 offset1:69
	ds_read2_b32 v[28:29], v20 offset0:134 offset1:199
	ds_read2_b32 v[30:31], v78 offset0:8 offset1:73
	ds_read2_b32 v[32:33], v78 offset0:138 offset1:203
	ds_read2_b32 v[34:35], v20 offset0:12 offset1:77
	ds_read2_b32 v[36:37], v20 offset0:142 offset1:207
	s_waitcnt lgkmcnt(4)
	v_cvt_pk_bf16_f32 v0, v22, v23
	v_cvt_pk_bf16_f32 v1, v24, v25
	v_cvt_pk_bf16_f32 v2, v26, v27
	v_cvt_pk_bf16_f32 v3, v28, v29
	v_add_u32_e32 v16, s6, v77
	v_ashrrev_i32_e32 v17, 31, v16
	v_lshl_add_u64 v[14:15], s[8:9], 1, v[12:13]
	v_lshlrev_b64 v[18:19], 12, v[16:17]
	v_lshl_add_u64 v[18:19], v[14:15], 0, v[18:19]
	global_store_dwordx4 v[18:19], v[0:3], off
	s_nop 1
	ds_read2_b32 v[22:23], v78 offset0:16 offset1:81
	ds_read2_b32 v[24:25], v78 offset0:146 offset1:211
	ds_read2_b32 v[26:27], v20 offset0:20 offset1:85
	ds_read2_b32 v[28:29], v20 offset0:150 offset1:215
	s_waitcnt lgkmcnt(4)
	v_cvt_pk_bf16_f32 v0, v30, v31
	v_cvt_pk_bf16_f32 v1, v32, v33
	v_cvt_pk_bf16_f32 v2, v34, v35
	v_cvt_pk_bf16_f32 v3, v36, v37
	v_add_u32_e32 v18, 8, v16
	v_ashrrev_i32_e32 v19, 31, v18
	v_lshlrev_b64 v[18:19], 12, v[18:19]
	v_lshl_add_u64 v[18:19], v[14:15], 0, v[18:19]
	global_store_dwordx4 v[18:19], v[0:3], off
	s_nop 1
	ds_read2_b32 v[30:31], v78 offset0:24 offset1:89
	ds_read2_b32 v[32:33], v78 offset0:154 offset1:219
	ds_read2_b32 v[34:35], v20 offset0:28 offset1:93
	ds_read2_b32 v[36:37], v20 offset0:158 offset1:223
	s_waitcnt lgkmcnt(4)
	v_cvt_pk_bf16_f32 v0, v22, v23
	v_cvt_pk_bf16_f32 v1, v24, v25
	v_cvt_pk_bf16_f32 v2, v26, v27
	v_cvt_pk_bf16_f32 v3, v28, v29
	v_add_u32_e32 v18, 16, v16
	v_ashrrev_i32_e32 v19, 31, v18
	v_lshlrev_b64 v[18:19], 12, v[18:19]
	v_lshl_add_u64 v[18:19], v[14:15], 0, v[18:19]
	global_store_dwordx4 v[18:19], v[0:3], off
	s_nop 1
	ds_read2_b32 v[22:23], v78 offset0:32 offset1:97
	ds_read2_b32 v[24:25], v78 offset0:162 offset1:227
	ds_read2_b32 v[26:27], v20 offset0:36 offset1:101
	ds_read2_b32 v[28:29], v20 offset0:166 offset1:231
	s_waitcnt lgkmcnt(4)
	v_cvt_pk_bf16_f32 v0, v30, v31
	v_cvt_pk_bf16_f32 v1, v32, v33
	v_cvt_pk_bf16_f32 v2, v34, v35
	v_cvt_pk_bf16_f32 v3, v36, v37
	v_add_u32_e32 v18, 24, v16
	v_ashrrev_i32_e32 v19, 31, v18
	v_lshlrev_b64 v[18:19], 12, v[18:19]
	v_lshl_add_u64 v[18:19], v[14:15], 0, v[18:19]
	global_store_dwordx4 v[18:19], v[0:3], off
	s_nop 1
	ds_read2_b32 v[30:31], v78 offset0:40 offset1:105
	ds_read2_b32 v[32:33], v78 offset0:170 offset1:235
	ds_read2_b32 v[34:35], v20 offset0:44 offset1:109
	ds_read2_b32 v[36:37], v20 offset0:174 offset1:239
	s_waitcnt lgkmcnt(4)
	v_cvt_pk_bf16_f32 v0, v22, v23
	v_cvt_pk_bf16_f32 v1, v24, v25
	v_cvt_pk_bf16_f32 v2, v26, v27
	v_cvt_pk_bf16_f32 v3, v28, v29
	v_add_u32_e32 v18, 32, v16
	v_ashrrev_i32_e32 v19, 31, v18
	v_lshlrev_b64 v[18:19], 12, v[18:19]
	v_lshl_add_u64 v[18:19], v[14:15], 0, v[18:19]
	global_store_dwordx4 v[18:19], v[0:3], off
	s_nop 1
	ds_read2_b32 v[22:23], v78 offset0:48 offset1:113
	ds_read2_b32 v[24:25], v78 offset0:178 offset1:243
	ds_read2_b32 v[26:27], v20 offset0:52 offset1:117
	ds_read2_b32 v[28:29], v20 offset0:182 offset1:247
	s_waitcnt lgkmcnt(4)
	v_cvt_pk_bf16_f32 v0, v30, v31
	v_cvt_pk_bf16_f32 v1, v32, v33
	v_cvt_pk_bf16_f32 v2, v34, v35
	v_cvt_pk_bf16_f32 v3, v36, v37
	v_add_u32_e32 v18, 40, v16
	v_ashrrev_i32_e32 v19, 31, v18
	v_lshlrev_b64 v[18:19], 12, v[18:19]
	v_lshl_add_u64 v[18:19], v[14:15], 0, v[18:19]
	global_store_dwordx4 v[18:19], v[0:3], off
	s_nop 1
	ds_read2_b32 v[30:31], v78 offset0:56 offset1:121
	ds_read2_b32 v[32:33], v78 offset0:186 offset1:251
	ds_read2_b32 v[34:35], v20 offset0:60 offset1:125
	ds_read2_b32 v[36:37], v20 offset0:190 offset1:255
	s_waitcnt lgkmcnt(4)
	v_cvt_pk_bf16_f32 v0, v22, v23
	v_cvt_pk_bf16_f32 v1, v24, v25
	v_cvt_pk_bf16_f32 v2, v26, v27
	v_cvt_pk_bf16_f32 v3, v28, v29
	v_add_u32_e32 v18, 48, v16
	v_ashrrev_i32_e32 v19, 31, v18
	v_lshlrev_b64 v[18:19], 12, v[18:19]
	v_lshl_add_u64 v[18:19], v[14:15], 0, v[18:19]
	v_add_u32_e32 v16, 56, v16
	global_store_dwordx4 v[18:19], v[0:3], off
	s_nop 1
	s_waitcnt lgkmcnt(0)
	v_ashrrev_i32_e32 v17, 31, v16
	v_cvt_pk_bf16_f32 v0, v30, v31
	v_lshlrev_b64 v[16:17], 12, v[16:17]
	v_cvt_pk_bf16_f32 v1, v32, v33
	v_lshl_add_u64 v[14:15], v[14:15], 0, v[16:17]
	v_cvt_pk_bf16_f32 v2, v34, v35
	v_cvt_pk_bf16_f32 v3, v36, v37
	global_store_dwordx4 v[14:15], v[0:3], off
	s_nop 1
	s_waitcnt lgkmcnt(0)
	s_cbranch_scc0 .LBB0_607
	v_readlane_b32 s28, v254, 34
	v_readlane_b32 s95, v254, 26
	v_readlane_b32 s96, v254, 39
	v_readlane_b32 s97, v254, 51
	v_readlane_b32 s23, v254, 47
	v_readlane_b32 s29, v254, 35

; #define LAS __attribute__((address_space(3)))
; __device__ __forceinline__ void transpose_item(const float* __restrict__ W, int K, int N, bf16_t* __restrict__ WT, int drow0, LAS float* scr, int k0, int n0, int lane, const float* __restrict__ gk) {
;     const float* src = W + (size_t)k0 * N + n0 + lane;
; #pragma unroll
;     for (int hb = 0; hb < 1; ++hb) {
;         float v[64];
; #pragma unroll
;         for (int i = 0; i < 64; ++i) v[i] = __builtin_nontemporal_load(src + (size_t)(hb * 64 + i) * N);
; __device__ __forceinline__ void transpose_matrix(const float* W, int K, int N, bf16_t* WT, int mode, LAS float* scr, int gw, int NGW, int lane, const float* gA, const float* gB, int it_lo, int it_hi) {
;     const int nblk = N / 64, w8 = gw & 7;
;     for (int j = (it_lo >> 3) + (gw >> 3); j < (it_hi >> 3); j += (NGW >> 3)) {
;         const int kb = (j / nblk) * 8 + w8, nb = j % nblk, n0 = nb * 64;
;         int drow0 = n0;
;         if (mode) { const int up = n0 >= DFF, j = n0 - up * DFF; drow0 = 256 * (j / 128) + (j % 128) + up * 128; }
;         transpose_item(W, K, N, WT, drow0, scr, kb * 64, n0, lane, gA ? (kb * 64 < 1024 ? gA : gB - 1024) : nullptr);
.LBB0_613:
	s_mul_hi_i32 s0, s6, 0x2e8ba2e9
	s_lshr_b32 s1, s0, 31
	s_ashr_i32 s0, s0, 5
	s_add_i32 s0, s0, s1
	s_mul_i32 s1, s0, 0xffffff50
	s_mul_i32 s10, s0, 0xffffd400
	s_add_i32 s1, s6, s1
	s_add_i32 s12, s8, s10
	s_cmpk_gt_i32 s1, 0x57
	s_cselect_b32 s1, 0xea00, 0
	s_cselect_b32 s10, 0x80, 0
	s_add_i32 s1, s12, s1
	s_sext_i32_i16 s11, s1
	s_bfe_u32 s11, s11, 0x70018
	s_add_i32 s11, s1, s11
	s_sext_i32_i16 s13, s11
	s_and_b32 s11, s11, 0xff80
	s_sub_i32 s1, s1, s11
	s_lshl_b32 s13, s13, 1
	s_sext_i32_i16 s1, s1
	s_lshl_b32 s0, s0, 9
	s_and_b32 s13, s13, 0xffffff00
	s_add_i32 s10, s10, s1
	s_or_b32 s0, s0, s40
	s_add_i32 s10, s10, s13
	s_ashr_i32 s1, s0, 31
	s_mul_i32 s13, s0, 0xb000
	s_mul_hi_i32 s11, s0, 0xb000
	s_add_u32 s14, s4, s13
	s_addc_u32 s11, s5, s11
	s_ashr_i32 s13, s12, 31
	s_lshl_b64 s[12:13], s[12:13], 2
	s_add_u32 s12, s14, s12
	s_addc_u32 s13, s11, s13
	v_lshl_add_u64 v[70:71], s[12:13], 0, v[112:113]
	v_add_co_u32_e32 v0, vcc, s23, v70
	global_load_dword v74, v112, s[12:13] nt
	s_nop 0
	v_addc_co_u32_e32 v1, vcc, 0, v71, vcc
	global_load_dword v75, v[0:1], off nt
	v_add_co_u32_e32 v0, vcc, s15, v70
	s_add_i32 s6, s6, s31
	s_nop 0
	v_addc_co_u32_e32 v1, vcc, 0, v71, vcc
	global_load_dword v87, v[0:1], off nt
	v_add_co_u32_e32 v0, vcc, s24, v70
	s_add_i32 s8, s8, s9
	s_nop 0
	v_addc_co_u32_e32 v1, vcc, 0, v71, vcc
	global_load_dword v88, v[0:1], off nt
	v_add_co_u32_e32 v0, vcc, s16, v70
	s_cmp_ge_i32 s6, s7
	s_nop 0
	v_addc_co_u32_e32 v1, vcc, 0, v71, vcc
	v_add_co_u32_e32 v2, vcc, s25, v70
	global_load_dword v0, v[0:1], off nt
	s_nop 0
	v_addc_co_u32_e32 v3, vcc, 0, v71, vcc
	v_add_co_u32_e32 v14, vcc, s17, v70
	global_load_dword v3, v[2:3], off nt
	s_nop 0
	v_addc_co_u32_e32 v15, vcc, 0, v71, vcc
	global_load_dword v17, v[14:15], off nt
	v_add_co_u32_e32 v14, vcc, s28, v70
	s_nop 1
	v_addc_co_u32_e32 v15, vcc, 0, v71, vcc
	global_load_dword v26, v[14:15], off nt
	v_add_co_u32_e32 v14, vcc, s18, v70
	s_nop 1
	v_addc_co_u32_e32 v15, vcc, 0, v71, vcc
	global_load_dword v1, v[14:15], off nt
	v_add_co_u32_e32 v14, vcc, s29, v70
	s_nop 1
	v_addc_co_u32_e32 v15, vcc, 0, v71, vcc
	v_add_co_u32_e32 v18, vcc, s19, v70
	global_load_dword v15, v[14:15], off nt
	s_nop 0
	v_addc_co_u32_e32 v19, vcc, 0, v71, vcc
	global_load_dword v20, v[18:19], off nt
	v_add_co_u32_e32 v18, vcc, s33, v70
	s_nop 1
	v_addc_co_u32_e32 v19, vcc, 0, v71, vcc
	global_load_dword v30, v[18:19], off nt
	v_add_co_u32_e32 v18, vcc, s38, v70
	s_nop 1
	v_addc_co_u32_e32 v19, vcc, 0, v71, vcc
	global_load_dword v2, v[18:19], off nt
	v_add_co_u32_e32 v18, vcc, s43, v70
	s_nop 1
	v_addc_co_u32_e32 v19, vcc, 0, v71, vcc
	v_add_co_u32_e32 v22, vcc, s44, v70
	global_load_dword v18, v[18:19], off nt
	s_nop 0
	v_addc_co_u32_e32 v23, vcc, 0, v71, vcc
	v_add_co_u32_e32 v24, vcc, s45, v70
	global_load_dword v23, v[22:23], off nt
	s_nop 0
	v_addc_co_u32_e32 v25, vcc, 0, v71, vcc
	global_load_dword v34, v[24:25], off nt
	v_add_co_u32_e32 v24, vcc, s46, v70
	s_nop 1
	v_addc_co_u32_e32 v25, vcc, 0, v71, vcc
	global_load_dword v14, v[24:25], off nt
	v_add_co_u32_e32 v24, vcc, s47, v70
	s_nop 1
	v_addc_co_u32_e32 v25, vcc, 0, v71, vcc
	global_load_dword v21, v[24:25], off nt
	v_add_co_u32_e32 v24, vcc, s36, v70
	s_nop 1
	v_addc_co_u32_e32 v25, vcc, 0, v71, vcc
	global_load_dword v27, v[24:25], off nt
	v_add_co_u32_e32 v24, vcc, s48, v70
	s_nop 1
	v_addc_co_u32_e32 v25, vcc, 0, v71, vcc
	global_load_dword v38, v[24:25], off nt
	v_add_co_u32_e32 v24, vcc, s37, v70
	s_nop 1
	v_addc_co_u32_e32 v25, vcc, 0, v71, vcc
	global_load_dword v16, v[24:25], off nt
	v_add_co_u32_e32 v24, vcc, s49, v70
	s_nop 1
	v_addc_co_u32_e32 v25, vcc, 0, v71, vcc
	v_add_co_u32_e32 v28, vcc, s50, v70
	global_load_dword v24, v[24:25], off nt
	s_nop 0
	v_addc_co_u32_e32 v29, vcc, 0, v71, vcc
	global_load_dword v31, v[28:29], off nt
	v_add_co_u32_e32 v28, vcc, s51, v70
	s_nop 1
	v_addc_co_u32_e32 v29, vcc, 0, v71, vcc
	global_load_dword v42, v[28:29], off nt
	v_add_co_u32_e32 v28, vcc, s52, v70
	s_nop 1
	v_addc_co_u32_e32 v29, vcc, 0, v71, vcc
	global_load_dword v19, v[28:29], off nt
	v_add_co_u32_e32 v28, vcc, s53, v70
	s_nop 1
	v_addc_co_u32_e32 v29, vcc, 0, v71, vcc
	v_add_co_u32_e32 v32, vcc, s54, v70
	global_load_dword v28, v[28:29], off nt
	s_nop 0
	v_addc_co_u32_e32 v33, vcc, 0, v71, vcc
	global_load_dword v35, v[32:33], off nt
	v_add_co_u32_e32 v32, vcc, s55, v70
	s_nop 1
	v_addc_co_u32_e32 v33, vcc, 0, v71, vcc
	global_load_dword v46, v[32:33], off nt
	v_add_co_u32_e32 v32, vcc, s56, v70
	s_nop 1
	v_addc_co_u32_e32 v33, vcc, 0, v71, vcc
	global_load_dword v22, v[32:33], off nt
	v_add_co_u32_e32 v32, vcc, s57, v70
	s_nop 1
	v_addc_co_u32_e32 v33, vcc, 0, v71, vcc
	v_add_co_u32_e32 v36, vcc, s58, v70
	global_load_dword v32, v[32:33], off nt
	s_nop 0
	v_addc_co_u32_e32 v37, vcc, 0, v71, vcc
	global_load_dword v39, v[36:37], off nt
	v_add_co_u32_e32 v36, vcc, s59, v70
	s_nop 1
	v_addc_co_u32_e32 v37, vcc, 0, v71, vcc
	global_load_dword v50, v[36:37], off nt
	v_add_co_u32_e32 v36, vcc, s60, v70
	s_nop 1
	v_addc_co_u32_e32 v37, vcc, 0, v71, vcc
	global_load_dword v25, v[36:37], off nt
	v_add_co_u32_e32 v36, vcc, s61, v70
	s_nop 1
	v_addc_co_u32_e32 v37, vcc, 0, v71, vcc
	v_add_co_u32_e32 v40, vcc, s62, v70
	global_load_dword v36, v[36:37], off nt
	s_nop 0
	v_addc_co_u32_e32 v41, vcc, 0, v71, vcc
	global_load_dword v43, v[40:41], off nt
	v_add_co_u32_e32 v40, vcc, s63, v70
	s_nop 1
	v_addc_co_u32_e32 v41, vcc, 0, v71, vcc
	global_load_dword v54, v[40:41], off nt
	v_add_co_u32_e32 v40, vcc, s64, v70
	s_nop 1
	v_addc_co_u32_e32 v41, vcc, 0, v71, vcc
	global_load_dword v29, v[40:41], off nt
; __device__ __forceinline__ void transpose_item(const float* __restrict__ W, int K, int N, bf16_t* __restrict__ WT, int drow0, LAS float* scr, int k0, int n0, int lane, const float* __restrict__ gk) {
;     ...
;         for (int i = 0; i < 64; ++i) v[i] = __builtin_nontemporal_load(src + (size_t)(hb * 64 + i) * N);
;         if (gk) {
; #pragma unroll
;             for (int i = 0; i < 64; ++i) v[i] *= gk[k0 + hb * 64 + i];
;         }
; #pragma unroll
;         for (int i = 0; i < 64; ++i) scr[(hb * 64 + i) * 65 + lane] = v[i];
;     }
;     asm volatile("s_waitcnt lgkmcnt(0)" ::: "memory");
	v_add_co_u32_e32 v40, vcc, s65, v70
	s_nop 1
	v_addc_co_u32_e32 v41, vcc, 0, v71, vcc
	v_add_co_u32_e32 v44, vcc, s66, v70
	global_load_dword v40, v[40:41], off nt
	s_nop 0
	v_addc_co_u32_e32 v45, vcc, 0, v71, vcc
	global_load_dword v47, v[44:45], off nt
	v_add_co_u32_e32 v44, vcc, s67, v70
	s_nop 1
	v_addc_co_u32_e32 v45, vcc, 0, v71, vcc
	global_load_dword v57, v[44:45], off nt
	v_add_co_u32_e32 v44, vcc, s68, v70
	s_nop 1
	v_addc_co_u32_e32 v45, vcc, 0, v71, vcc
	global_load_dword v33, v[44:45], off nt
	v_add_co_u32_e32 v44, vcc, s69, v70
	s_nop 1
	v_addc_co_u32_e32 v45, vcc, 0, v71, vcc
	v_add_co_u32_e32 v48, vcc, s72, v70
	global_load_dword v44, v[44:45], off nt
	s_nop 0
	v_addc_co_u32_e32 v49, vcc, 0, v71, vcc
	global_load_dword v51, v[48:49], off nt
	v_add_co_u32_e32 v48, vcc, s73, v70
	s_nop 1
	v_addc_co_u32_e32 v49, vcc, 0, v71, vcc
	global_load_dword v60, v[48:49], off nt
	v_add_co_u32_e32 v48, vcc, s74, v70
	s_nop 1
	v_addc_co_u32_e32 v49, vcc, 0, v71, vcc
	global_load_dword v37, v[48:49], off nt
	v_add_co_u32_e32 v48, vcc, s75, v70
	s_nop 1
	v_addc_co_u32_e32 v49, vcc, 0, v71, vcc
	v_add_co_u32_e32 v52, vcc, s76, v70
	global_load_dword v48, v[48:49], off nt
	s_nop 0
	v_addc_co_u32_e32 v53, vcc, 0, v71, vcc
	global_load_dword v55, v[52:53], off nt
	v_add_co_u32_e32 v52, vcc, s77, v70
	s_nop 1
	v_addc_co_u32_e32 v53, vcc, 0, v71, vcc
	global_load_dword v63, v[52:53], off nt
	v_add_co_u32_e32 v52, vcc, s78, v70
	s_nop 1
	v_addc_co_u32_e32 v53, vcc, 0, v71, vcc
	global_load_dword v41, v[52:53], off nt
	v_add_co_u32_e32 v52, vcc, s79, v70
	s_nop 1
	v_addc_co_u32_e32 v53, vcc, 0, v71, vcc
	v_add_co_u32_e32 v58, vcc, s80, v70
	global_load_dword v52, v[52:53], off nt
	s_nop 0
	v_addc_co_u32_e32 v59, vcc, 0, v71, vcc
	v_add_co_u32_e32 v64, vcc, s81, v70
	global_load_dword v58, v[58:59], off nt
	s_nop 0
	v_addc_co_u32_e32 v65, vcc, 0, v71, vcc
	v_add_co_u32_e32 v66, vcc, s82, v70
	global_load_dword v65, v[64:65], off nt
	s_nop 0
	v_addc_co_u32_e32 v67, vcc, 0, v71, vcc
	global_load_dword v45, v[66:67], off nt
	v_add_co_u32_e32 v66, vcc, s83, v70
	s_nop 1
	v_addc_co_u32_e32 v67, vcc, 0, v71, vcc
	global_load_dword v56, v[66:67], off nt
	v_add_co_u32_e32 v66, vcc, s84, v70
	s_nop 1
	v_addc_co_u32_e32 v67, vcc, 0, v71, vcc
	global_load_dword v61, v[66:67], off nt
	v_add_co_u32_e32 v66, vcc, s85, v70
	s_nop 1
	v_addc_co_u32_e32 v67, vcc, 0, v71, vcc
	v_add_co_u32_e32 v68, vcc, s86, v70
	global_load_dword v67, v[66:67], off nt
	s_nop 0
	v_addc_co_u32_e32 v69, vcc, 0, v71, vcc
	global_load_dword v49, v[68:69], off nt
	v_add_co_u32_e32 v68, vcc, s87, v70
	s_nop 1
	v_addc_co_u32_e32 v69, vcc, 0, v71, vcc
	global_load_dword v59, v[68:69], off nt
	v_add_co_u32_e32 v68, vcc, s88, v70
	s_nop 1
	v_addc_co_u32_e32 v69, vcc, 0, v71, vcc
	global_load_dword v64, v[68:69], off nt
	v_add_co_u32_e32 v68, vcc, s89, v70
	s_nop 1
	v_addc_co_u32_e32 v69, vcc, 0, v71, vcc
	v_add_co_u32_e32 v72, vcc, s90, v70
	global_load_dword v68, v[68:69], off nt
	s_nop 0
	v_addc_co_u32_e32 v73, vcc, 0, v71, vcc
	global_load_dword v53, v[72:73], off nt
	v_add_co_u32_e32 v72, vcc, s91, v70
	s_nop 1
	v_addc_co_u32_e32 v73, vcc, 0, v71, vcc
	global_load_dword v62, v[72:73], off nt
	v_add_co_u32_e32 v72, vcc, s92, v70
	s_nop 1
	v_addc_co_u32_e32 v73, vcc, 0, v71, vcc
	v_add_co_u32_e32 v70, vcc, s93, v70
	global_load_dword v66, v[72:73], off nt
	s_nop 0
	v_addc_co_u32_e32 v71, vcc, 0, v71, vcc
	global_load_dword v69, v[70:71], off nt
	v_add_u32_e32 v70, 0x400, v76
	s_waitcnt vmcnt(0)
	ds_write2_b32 v76, v74, v75 offset1:65
	ds_write2_b32 v76, v87, v88 offset0:130 offset1:195
	ds_write2_b32 v70, v0, v3 offset0:4 offset1:69
	ds_write2_b32 v70, v17, v26 offset0:134 offset1:199
	v_add_u32_e32 v0, 0x800, v76
	ds_write2_b32 v0, v1, v15 offset0:8 offset1:73
	ds_write2_b32 v0, v20, v30 offset0:138 offset1:203
	v_add_u32_e32 v0, 0xc00, v76
	ds_write2_b32 v0, v2, v18 offset0:12 offset1:77
	ds_write2_b32 v0, v23, v34 offset0:142 offset1:207
	v_add_u32_e32 v0, 0x1000, v76
	ds_write2_b32 v0, v14, v21 offset0:16 offset1:81
	ds_write2_b32 v0, v27, v38 offset0:146 offset1:211
	v_add_u32_e32 v0, 0x1400, v76
	ds_write2_b32 v0, v16, v24 offset0:20 offset1:85
	ds_write2_b32 v0, v31, v42 offset0:150 offset1:215
	v_add_u32_e32 v0, 0x1800, v76
	ds_write2_b32 v0, v19, v28 offset0:24 offset1:89
	ds_write2_b32 v0, v35, v46 offset0:154 offset1:219
	v_add_u32_e32 v0, 0x1c00, v76
	ds_write2_b32 v0, v22, v32 offset0:28 offset1:93
	ds_write2_b32 v0, v39, v50 offset0:158 offset1:223
	v_add_u32_e32 v0, 0x2000, v76
	ds_write2_b32 v0, v25, v36 offset0:32 offset1:97
	ds_write2_b32 v0, v43, v54 offset0:162 offset1:227
	v_add_u32_e32 v0, 0x2400, v76
	ds_write2_b32 v0, v29, v40 offset0:36 offset1:101
	ds_write2_b32 v0, v47, v57 offset0:166 offset1:231
	v_add_u32_e32 v0, 0x2800, v76
	ds_write2_b32 v0, v33, v44 offset0:40 offset1:105
	ds_write2_b32 v0, v51, v60 offset0:170 offset1:235
	v_add_u32_e32 v0, 0x2c00, v76
	ds_write2_b32 v0, v37, v48 offset0:44 offset1:109
	ds_write2_b32 v0, v55, v63 offset0:174 offset1:239
	v_add_u32_e32 v0, 0x3000, v76
	ds_write2_b32 v0, v41, v52 offset0:48 offset1:113
	ds_write2_b32 v0, v58, v65 offset0:178 offset1:243
	v_add_u32_e32 v0, 0x3400, v76
	ds_write2_b32 v0, v45, v56 offset0:52 offset1:117
	ds_write2_b32 v0, v61, v67 offset0:182 offset1:247
	v_add_u32_e32 v0, 0x3800, v76
	ds_write2_b32 v0, v49, v59 offset0:56 offset1:121
	ds_write2_b32 v0, v64, v68 offset0:186 offset1:251
	v_add_u32_e32 v0, 0x3c00, v76
	ds_write2_b32 v0, v53, v62 offset0:60 offset1:125
	ds_write2_b32 v0, v66, v69 offset0:190 offset1:255
	s_waitcnt lgkmcnt(0)
; #define LAS __attribute__((address_space(3)))
; __device__ __forceinline__ unsigned pk2(float lo, float hi) { unsigned r; asm volatile("v_cvt_pk_bf16_f32 %0, %1, %2" : "=v"(r) : "v"(lo), "v"(hi)); return r; }
; __device__ __forceinline__ void transpose_item(const float* __restrict__ W, int K, int N, bf16_t* __restrict__ WT, int drow0, LAS float* scr, int k0, int n0, int lane, const float* __restrict__ gk) {
;     ...
;     const int c = lane & 7;
; #pragma unroll
;     for (int j = 0; j < 8; ++j) { const int n = (lane >> 3) + 8 * j; const LAS float* s = scr + (8 * c) * 65 + n;
;         u32x4 o; o.x = pk2(s[0 * 65], s[1 * 65]); o.y = pk2(s[2 * 65], s[3 * 65]); o.z = pk2(s[4 * 65], s[5 * 65]); o.w = pk2(s[6 * 65], s[7 * 65]);
;         *(u32x4*)(WT + (size_t)(drow0 + n) * K + k0 + 8 * c) = o; }
;     asm volatile("s_waitcnt lgkmcnt(0)" ::: "memory");
	v_add_u32_e32 v18, 0x400, v78
	ds_read2_b32 v[20:21], v78 offset1:65
	ds_read2_b32 v[22:23], v78 offset0:130 offset1:195
	ds_read2_b32 v[24:25], v18 offset0:4 offset1:69
	ds_read2_b32 v[26:27], v18 offset0:134 offset1:199
	ds_read2_b32 v[28:29], v78 offset0:8 offset1:73
	ds_read2_b32 v[30:31], v78 offset0:138 offset1:203
	ds_read2_b32 v[32:33], v18 offset0:12 offset1:77
	ds_read2_b32 v[34:35], v18 offset0:142 offset1:207
	s_waitcnt lgkmcnt(4)
	v_cvt_pk_bf16_f32 v0, v20, v21
	v_cvt_pk_bf16_f32 v1, v22, v23
	v_cvt_pk_bf16_f32 v2, v24, v25
	v_cvt_pk_bf16_f32 v3, v26, v27
	v_add_u32_e32 v16, s10, v77
	v_ashrrev_i32_e32 v17, 31, v16
	v_lshl_add_u64 v[14:15], s[0:1], 1, v[12:13]
	v_lshlrev_b64 v[16:17], 12, v[16:17]
	v_lshl_add_u64 v[16:17], v[14:15], 0, v[16:17]
	global_store_dwordx4 v[16:17], v[0:3], off
	s_nop 1
	ds_read2_b32 v[20:21], v78 offset0:16 offset1:81
	ds_read2_b32 v[22:23], v78 offset0:146 offset1:211
	ds_read2_b32 v[24:25], v18 offset0:20 offset1:85
	ds_read2_b32 v[26:27], v18 offset0:150 offset1:215
	s_waitcnt lgkmcnt(4)
	v_cvt_pk_bf16_f32 v0, v28, v29
	v_cvt_pk_bf16_f32 v1, v30, v31
	v_cvt_pk_bf16_f32 v2, v32, v33
	v_cvt_pk_bf16_f32 v3, v34, v35
	v_add_u32_e32 v16, s10, v79
	v_ashrrev_i32_e32 v17, 31, v16
	v_lshlrev_b64 v[16:17], 12, v[16:17]
	v_lshl_add_u64 v[16:17], v[14:15], 0, v[16:17]
	global_store_dwordx4 v[16:17], v[0:3], off
	s_nop 1
	ds_read2_b32 v[28:29], v78 offset0:24 offset1:89
	ds_read2_b32 v[30:31], v78 offset0:154 offset1:219
	ds_read2_b32 v[32:33], v18 offset0:28 offset1:93
	ds_read2_b32 v[34:35], v18 offset0:158 offset1:223
	s_waitcnt lgkmcnt(4)
	v_cvt_pk_bf16_f32 v0, v20, v21
	v_cvt_pk_bf16_f32 v1, v22, v23
	v_cvt_pk_bf16_f32 v2, v24, v25
	v_cvt_pk_bf16_f32 v3, v26, v27
	v_add_u32_e32 v16, s10, v80
	v_ashrrev_i32_e32 v17, 31, v16
	v_lshlrev_b64 v[16:17], 12, v[16:17]
	v_lshl_add_u64 v[16:17], v[14:15], 0, v[16:17]
	global_store_dwordx4 v[16:17], v[0:3], off
	s_nop 1
	ds_read2_b32 v[20:21], v78 offset0:32 offset1:97
	ds_read2_b32 v[22:23], v78 offset0:162 offset1:227
	ds_read2_b32 v[24:25], v18 offset0:36 offset1:101
	ds_read2_b32 v[26:27], v18 offset0:166 offset1:231
	s_waitcnt lgkmcnt(4)
	v_cvt_pk_bf16_f32 v0, v28, v29
	v_cvt_pk_bf16_f32 v1, v30, v31
	v_cvt_pk_bf16_f32 v2, v32, v33
	v_cvt_pk_bf16_f32 v3, v34, v35
	v_add_u32_e32 v16, s10, v81
	v_ashrrev_i32_e32 v17, 31, v16
	v_lshlrev_b64 v[16:17], 12, v[16:17]
	v_lshl_add_u64 v[16:17], v[14:15], 0, v[16:17]
	global_store_dwordx4 v[16:17], v[0:3], off
	s_nop 1
	ds_read2_b32 v[28:29], v78 offset0:40 offset1:105
	ds_read2_b32 v[30:31], v78 offset0:170 offset1:235
	ds_read2_b32 v[32:33], v18 offset0:44 offset1:109
	ds_read2_b32 v[34:35], v18 offset0:174 offset1:239
	s_waitcnt lgkmcnt(4)
	v_cvt_pk_bf16_f32 v0, v20, v21
	v_cvt_pk_bf16_f32 v1, v22, v23
	v_cvt_pk_bf16_f32 v2, v24, v25
	v_cvt_pk_bf16_f32 v3, v26, v27
	v_add_u32_e32 v16, s10, v82
	v_ashrrev_i32_e32 v17, 31, v16
	v_lshlrev_b64 v[16:17], 12, v[16:17]
	v_lshl_add_u64 v[16:17], v[14:15], 0, v[16:17]
	global_store_dwordx4 v[16:17], v[0:3], off
	s_nop 1
	ds_read2_b32 v[20:21], v78 offset0:48 offset1:113
	ds_read2_b32 v[22:23], v78 offset0:178 offset1:243
	ds_read2_b32 v[24:25], v18 offset0:52 offset1:117
	ds_read2_b32 v[26:27], v18 offset0:182 offset1:247
	s_waitcnt lgkmcnt(4)
	v_cvt_pk_bf16_f32 v0, v28, v29
	v_cvt_pk_bf16_f32 v1, v30, v31
	v_cvt_pk_bf16_f32 v2, v32, v33
	v_cvt_pk_bf16_f32 v3, v34, v35
	v_add_u32_e32 v16, s10, v83
	v_ashrrev_i32_e32 v17, 31, v16
	v_lshlrev_b64 v[16:17], 12, v[16:17]
	v_lshl_add_u64 v[16:17], v[14:15], 0, v[16:17]
	global_store_dwordx4 v[16:17], v[0:3], off
	s_nop 1
	ds_read2_b32 v[28:29], v78 offset0:56 offset1:121
	ds_read2_b32 v[30:31], v78 offset0:186 offset1:251
	ds_read2_b32 v[32:33], v18 offset0:60 offset1:125
	ds_read2_b32 v[34:35], v18 offset0:190 offset1:255
	s_waitcnt lgkmcnt(4)
	v_cvt_pk_bf16_f32 v0, v20, v21
	v_cvt_pk_bf16_f32 v1, v22, v23
	v_cvt_pk_bf16_f32 v2, v24, v25
	v_cvt_pk_bf16_f32 v3, v26, v27
	v_add_u32_e32 v16, s10, v84
	v_ashrrev_i32_e32 v17, 31, v16
	v_lshlrev_b64 v[16:17], 12, v[16:17]
	v_lshl_add_u64 v[16:17], v[14:15], 0, v[16:17]
	global_store_dwordx4 v[16:17], v[0:3], off
	s_nop 1
	s_waitcnt lgkmcnt(0)
	v_cvt_pk_bf16_f32 v0, v28, v29
	v_cvt_pk_bf16_f32 v1, v30, v31
	v_cvt_pk_bf16_f32 v2, v32, v33
	v_cvt_pk_bf16_f32 v3, v34, v35
	v_add_u32_e32 v16, s10, v85
	v_ashrrev_i32_e32 v17, 31, v16
	v_lshlrev_b64 v[16:17], 12, v[16:17]
	v_lshl_add_u64 v[14:15], v[14:15], 0, v[16:17]
	global_store_dwordx4 v[14:15], v[0:3], off
	s_nop 1
	s_waitcnt lgkmcnt(0)
	s_cbranch_scc0 .LBB0_613
	s_branch .LBB0_567

; #define LAS __attribute__((address_space(3)))
; __device__ __forceinline__ void transpose_item(const float* __restrict__ W, int K, int N, bf16_t* __restrict__ WT, int drow0, LAS float* scr, int k0, int n0, int lane, const float* __restrict__ gk) {
;     const float* src = W + (size_t)k0 * N + n0 + lane;
; #pragma unroll
;     for (int hb = 0; hb < 1; ++hb) {
;         float v[64];
; #pragma unroll
;         for (int i = 0; i < 64; ++i) v[i] = __builtin_nontemporal_load(src + (size_t)(hb * 64 + i) * N);
; __device__ __forceinline__ void transpose_matrix(const float* W, int K, int N, bf16_t* WT, int mode, LAS float* scr, int gw, int NGW, int lane, const float* gA, const float* gB, int it_lo, int it_hi) {
;     const int nblk = N / 64, w8 = gw & 7;
;     for (int j = (it_lo >> 3) + (gw >> 3); j < (it_hi >> 3); j += (NGW >> 3)) {
;         const int kb = (j / nblk) * 8 + w8, nb = j % nblk, n0 = nb * 64;
;         int drow0 = n0;
;         if (mode) { const int up = n0 >= DFF, j = n0 - up * DFF; drow0 = 256 * (j / 128) + (j % 128) + up * 128; }
;         transpose_item(W, K, N, WT, drow0, scr, kb * 64, n0, lane, gA ? (kb * 64 < 1024 ? gA : gB - 1024) : nullptr);
.LBB0_618:
	s_mul_hi_i32 s4, s14, 0x2e8ba2e9
	s_lshr_b32 s5, s4, 31
	s_ashr_i32 s4, s4, 5
	s_add_i32 s5, s4, s5
	s_mul_i32 s4, s5, 0xffffff50
	s_mul_i32 s6, s5, 0xffffd400
	s_add_i32 s7, s14, s4
	s_add_i32 s4, s16, s6
	s_cmpk_gt_i32 s7, 0x57
	s_cselect_b32 s6, 0xea00, 0
	s_cselect_b32 s7, 0x80, 0
	s_lshl_b32 s5, s5, 9
	s_add_i32 s6, s4, s6
	s_or_b32 s22, s5, s15
	s_sext_i32_i16 s5, s6
	s_bfe_u32 s5, s5, 0x70018
	s_add_i32 s5, s6, s5
	s_sext_i32_i16 s10, s5
	s_and_b32 s5, s5, 0xff80
	s_sub_i32 s5, s6, s5
	s_lshl_b32 s10, s10, 1
	s_sext_i32_i16 s5, s5
	s_and_b32 s6, s10, 0xffffff00
	s_add_i32 s24, s7, s5
	s_ashr_i32 s23, s22, 31
	s_mul_i32 s9, s22, 0xb000
	s_add_i32 s24, s24, s6
	s_mul_hi_i32 s8, s22, 0xb000
	s_waitcnt lgkmcnt(0)
	s_add_u32 s6, s0, s9
	s_addc_u32 s7, s1, s8
	s_ashr_i32 s5, s4, 31
	s_lshl_b64 s[4:5], s[4:5], 2
	s_add_u32 s18, s6, s4
	s_addc_u32 s19, s7, s5
	v_lshl_add_u64 v[90:91], s[18:19], 0, v[112:113]
	v_add_co_u32_e32 v4, vcc, s30, v90
	v_add_co_u32_e64 v6, s[4:5], s25, v90
	v_add_co_u32_e64 v2, s[6:7], s37, v90
	v_addc_co_u32_e32 v5, vcc, 0, v91, vcc
	v_addc_co_u32_e64 v7, s[4:5], 0, v91, s[4:5]
	v_addc_co_u32_e64 v3, s[6:7], 0, v91, s[6:7]
	v_add_co_u32_e64 v128, s[8:9], s28, v90
	v_add_co_u32_e64 v92, s[10:11], s38, v90
	v_add_co_u32_e64 v126, s[12:13], s29, v90
	v_add_co_u32_e32 v118, vcc, s40, v90
	v_add_co_u32_e64 v124, s[4:5], s33, v90
	v_add_co_u32_e64 v120, s[6:7], s41, v90
	v_addc_co_u32_e64 v129, s[8:9], 0, v91, s[8:9]
	v_addc_co_u32_e64 v93, s[10:11], 0, v91, s[10:11]
	v_addc_co_u32_e64 v127, s[12:13], 0, v91, s[12:13]
	v_addc_co_u32_e32 v119, vcc, 0, v91, vcc
	v_addc_co_u32_e64 v125, s[4:5], 0, v91, s[4:5]
	v_addc_co_u32_e64 v121, s[6:7], 0, v91, s[6:7]
	v_add_co_u32_e64 v122, s[8:9], s36, v90
	v_add_co_u32_e64 v114, s[10:11], s42, v90
	v_add_co_u32_e64 v116, s[12:13], s45, v90
	v_add_co_u32_e32 v108, vcc, s46, v90
	v_add_co_u32_e64 v110, s[4:5], s47, v90
	v_add_co_u32_e64 v104, s[6:7], s48, v90
	v_addc_co_u32_e64 v123, s[8:9], 0, v91, s[8:9]
	v_addc_co_u32_e64 v115, s[10:11], 0, v91, s[10:11]
	v_addc_co_u32_e64 v117, s[12:13], 0, v91, s[12:13]
	v_addc_co_u32_e32 v109, vcc, 0, v91, vcc
	v_addc_co_u32_e64 v111, s[4:5], 0, v91, s[4:5]
	v_addc_co_u32_e64 v105, s[6:7], 0, v91, s[6:7]
	v_add_co_u32_e64 v106, s[8:9], s49, v90
	v_add_co_u32_e64 v100, s[10:11], s50, v90
	v_add_co_u32_e64 v102, s[12:13], s43, v90
	v_add_co_u32_e32 v96, vcc, s51, v90
	v_add_co_u32_e64 v98, s[4:5], s44, v90
	v_add_co_u32_e64 v94, s[6:7], s52, v90
	v_addc_co_u32_e64 v107, s[8:9], 0, v91, s[8:9]
	v_addc_co_u32_e64 v101, s[10:11], 0, v91, s[10:11]
	v_addc_co_u32_e64 v103, s[12:13], 0, v91, s[12:13]
	v_addc_co_u32_e32 v97, vcc, 0, v91, vcc
	v_addc_co_u32_e64 v99, s[4:5], 0, v91, s[4:5]
	v_addc_co_u32_e64 v95, s[6:7], 0, v91, s[6:7]
	v_add_co_u32_e64 v8, s[8:9], s53, v90
	v_add_co_u32_e64 v10, s[10:11], s54, v90
	v_add_co_u32_e64 v12, s[12:13], s55, v90
	v_add_co_u32_e32 v14, vcc, s56, v90
	v_add_co_u32_e64 v16, s[4:5], s57, v90
	v_add_co_u32_e64 v20, s[6:7], s58, v90
	v_addc_co_u32_e64 v9, s[8:9], 0, v91, s[8:9]
	v_addc_co_u32_e64 v11, s[10:11], 0, v91, s[10:11]
	v_addc_co_u32_e64 v13, s[12:13], 0, v91, s[12:13]
	v_addc_co_u32_e32 v15, vcc, 0, v91, vcc
	v_addc_co_u32_e64 v17, s[4:5], 0, v91, s[4:5]
	v_addc_co_u32_e64 v21, s[6:7], 0, v91, s[6:7]
	v_add_co_u32_e64 v24, s[8:9], s59, v90
	v_add_co_u32_e64 v28, s[10:11], s60, v90
	v_add_co_u32_e64 v32, s[12:13], s61, v90
	v_add_co_u32_e32 v36, vcc, s62, v90
	v_add_co_u32_e64 v18, s[4:5], s63, v90
	v_add_co_u32_e64 v22, s[6:7], s64, v90
	v_addc_co_u32_e64 v25, s[8:9], 0, v91, s[8:9]
	v_addc_co_u32_e64 v29, s[10:11], 0, v91, s[10:11]
	v_addc_co_u32_e64 v33, s[12:13], 0, v91, s[12:13]
	v_addc_co_u32_e32 v37, vcc, 0, v91, vcc
	v_addc_co_u32_e64 v19, s[4:5], 0, v91, s[4:5]
	v_addc_co_u32_e64 v23, s[6:7], 0, v91, s[6:7]
	v_add_co_u32_e64 v26, s[8:9], s65, v90
	v_add_co_u32_e64 v30, s[10:11], s66, v90
	v_add_co_u32_e64 v34, s[12:13], s67, v90
	v_add_co_u32_e32 v38, vcc, s68, v90
	v_add_co_u32_e64 v42, s[4:5], s69, v90
	v_add_co_u32_e64 v46, s[6:7], s72, v90
	v_addc_co_u32_e64 v27, s[8:9], 0, v91, s[8:9]
	v_addc_co_u32_e64 v31, s[10:11], 0, v91, s[10:11]
	v_addc_co_u32_e64 v35, s[12:13], 0, v91, s[12:13]
	v_addc_co_u32_e32 v39, vcc, 0, v91, vcc
	v_addc_co_u32_e64 v43, s[4:5], 0, v91, s[4:5]
	v_addc_co_u32_e64 v47, s[6:7], 0, v91, s[6:7]
	v_add_co_u32_e64 v50, s[8:9], s73, v90
	v_add_co_u32_e64 v54, s[10:11], s74, v90
	v_add_co_u32_e64 v58, s[12:13], s75, v90
	v_add_co_u32_e32 v62, vcc, s76, v90
	v_add_co_u32_e64 v66, s[4:5], s77, v90
	v_add_co_u32_e64 v70, s[6:7], s78, v90
	v_addc_co_u32_e64 v51, s[8:9], 0, v91, s[8:9]
	v_addc_co_u32_e64 v55, s[10:11], 0, v91, s[10:11]
	v_addc_co_u32_e64 v59, s[12:13], 0, v91, s[12:13]
	v_addc_co_u32_e32 v63, vcc, 0, v91, vcc
	v_addc_co_u32_e64 v67, s[4:5], 0, v91, s[4:5]
	v_addc_co_u32_e64 v71, s[6:7], 0, v91, s[6:7]
	v_add_co_u32_e64 v74, s[8:9], s79, v90
	v_add_co_u32_e64 v78, s[10:11], s80, v90
	v_add_co_u32_e64 v82, s[12:13], s81, v90
	v_add_co_u32_e32 v86, vcc, s82, v90
	v_add_co_u32_e64 v40, s[4:5], s83, v90
	v_add_co_u32_e64 v44, s[6:7], s84, v90
	v_addc_co_u32_e64 v75, s[8:9], 0, v91, s[8:9]
	v_addc_co_u32_e64 v79, s[10:11], 0, v91, s[10:11]
	v_addc_co_u32_e64 v83, s[12:13], 0, v91, s[12:13]
	v_addc_co_u32_e32 v87, vcc, 0, v91, vcc
	v_addc_co_u32_e64 v41, s[4:5], 0, v91, s[4:5]
	v_addc_co_u32_e64 v45, s[6:7], 0, v91, s[6:7]
	v_add_co_u32_e64 v48, s[8:9], s85, v90
	v_add_co_u32_e64 v52, s[10:11], s86, v90
	v_add_co_u32_e64 v56, s[12:13], s87, v90
	v_add_co_u32_e32 v60, vcc, s88, v90
	v_add_co_u32_e64 v64, s[4:5], s89, v90
	v_add_co_u32_e64 v68, s[6:7], s90, v90
; __device__ __forceinline__ void transpose_item(const float* __restrict__ W, int K, int N, bf16_t* __restrict__ WT, int drow0, LAS float* scr, int k0, int n0, int lane, const float* __restrict__ gk) {
;     ...
;         for (int i = 0; i < 64; ++i) v[i] = __builtin_nontemporal_load(src + (size_t)(hb * 64 + i) * N);
;         if (gk) {
; #pragma unroll
;             for (int i = 0; i < 64; ++i) v[i] *= gk[k0 + hb * 64 + i];
;         }
; #pragma unroll
;         for (int i = 0; i < 64; ++i) scr[(hb * 64 + i) * 65 + lane] = v[i];
;     }
;     asm volatile("s_waitcnt lgkmcnt(0)" ::: "memory");
	v_addc_co_u32_e64 v49, s[8:9], 0, v91, s[8:9]
	v_addc_co_u32_e64 v53, s[10:11], 0, v91, s[10:11]
	v_addc_co_u32_e64 v57, s[12:13], 0, v91, s[12:13]
	v_addc_co_u32_e32 v61, vcc, 0, v91, vcc
	v_addc_co_u32_e64 v65, s[4:5], 0, v91, s[4:5]
	v_addc_co_u32_e64 v69, s[6:7], 0, v91, s[6:7]
	v_add_co_u32_e64 v72, s[8:9], s91, v90
	v_add_co_u32_e64 v76, s[10:11], s92, v90
	v_add_co_u32_e64 v80, s[12:13], s93, v90
	v_add_co_u32_e32 v84, vcc, s94, v90
	v_add_co_u32_e64 v88, s[4:5], s95, v90
	v_add_co_u32_e64 v90, s[6:7], s96, v90
	v_addc_co_u32_e64 v73, s[8:9], 0, v91, s[8:9]
	v_addc_co_u32_e64 v77, s[8:9], 0, v91, s[10:11]
	v_addc_co_u32_e64 v81, s[8:9], 0, v91, s[12:13]
	v_addc_co_u32_e32 v85, vcc, 0, v91, vcc
	v_addc_co_u32_e64 v89, vcc, 0, v91, s[4:5]
	v_addc_co_u32_e64 v91, vcc, 0, v91, s[6:7]
	global_load_dword v129, v[128:129], off nt
	s_nop 0
	global_load_dword v155, v[92:93], off nt
	s_nop 0
	global_load_dword v126, v[126:127], off nt
	s_nop 0
	global_load_dword v127, v[118:119], off nt
	s_nop 0
	global_load_dword v124, v[124:125], off nt
	s_nop 0
	global_load_dword v125, v[120:121], off nt
	s_nop 0
	global_load_dword v122, v[122:123], off nt
	s_nop 0
	global_load_dword v123, v[114:115], off nt
	s_nop 0
	global_load_dword v116, v[116:117], off nt
	s_nop 0
	global_load_dword v117, v[108:109], off nt
	s_nop 0
	global_load_dword v110, v[110:111], off nt
	s_nop 0
	global_load_dword v111, v[104:105], off nt
	s_nop 0
	global_load_dword v106, v[106:107], off nt
	s_nop 0
	global_load_dword v107, v[100:101], off nt
	s_nop 0
	global_load_dword v102, v[102:103], off nt
	s_nop 0
	global_load_dword v103, v[96:97], off nt
	s_nop 0
	global_load_dword v98, v[98:99], off nt
	s_nop 0
	global_load_dword v94, v[94:95], off nt
	s_nop 0
	global_load_dword v95, v112, s[18:19] nt
	global_load_dword v99, v[8:9], off nt
	global_load_dword v156, v[10:11], off nt
	global_load_dword v157, v[12:13], off nt
	global_load_dword v158, v[14:15], off nt
	global_load_dword v159, v[16:17], off nt
	s_nop 0
	global_load_dword v20, v[20:21], off nt
	s_nop 0
	global_load_dword v21, v[24:25], off nt
	s_nop 0
	global_load_dword v24, v[28:29], off nt
	global_load_dword v25, v[32:33], off nt
	s_nop 0
	global_load_dword v28, v[36:37], off nt
	global_load_dword v29, v[4:5], off nt
	global_load_dword v32, v[6:7], off nt
	global_load_dword v33, v[18:19], off nt
	s_nop 0
	global_load_dword v22, v[22:23], off nt
	s_nop 0
	global_load_dword v23, v[26:27], off nt
	s_nop 0
	global_load_dword v26, v[30:31], off nt
	global_load_dword v27, v[34:35], off nt
	s_nop 0
	global_load_dword v30, v[38:39], off nt
	global_load_dword v31, v[42:43], off nt
	global_load_dword v34, v[46:47], off nt
	global_load_dword v35, v[50:51], off nt
	global_load_dword v36, v[54:55], off nt
	global_load_dword v37, v[58:59], off nt
	global_load_dword v38, v[62:63], off nt
	global_load_dword v39, v[66:67], off nt
	global_load_dword v42, v[70:71], off nt
	global_load_dword v43, v[74:75], off nt
	global_load_dword v46, v[78:79], off nt
	global_load_dword v47, v[82:83], off nt
	global_load_dword v50, v[86:87], off nt
	global_load_dword v51, v[2:3], off nt
	s_nop 0
	global_load_dword v40, v[40:41], off nt
	s_nop 0
	global_load_dword v41, v[44:45], off nt
	s_nop 0
	global_load_dword v44, v[48:49], off nt
	global_load_dword v45, v[52:53], off nt
	s_nop 0
	global_load_dword v48, v[56:57], off nt
	global_load_dword v49, v[60:61], off nt
	global_load_dword v52, v[64:65], off nt
	global_load_dword v53, v[68:69], off nt
	global_load_dword v54, v[72:73], off nt
	global_load_dword v55, v[76:77], off nt
	global_load_dword v56, v[80:81], off nt
	global_load_dword v57, v[84:85], off nt
	global_load_dword v58, v[88:89], off nt
	global_load_dword v59, v[90:91], off nt
	v_add_u32_e32 v140, 0x400, v130
	v_add_u32_e32 v118, s24, v131
	v_add_u32_e32 v141, 0x800, v130
	v_add_u32_e32 v142, 0xc00, v130
	v_add_u32_e32 v143, 0x1000, v130
	v_add_u32_e32 v144, 0x1400, v130
	v_add_u32_e32 v145, 0x1800, v130
	v_add_u32_e32 v146, 0x1c00, v130
	v_add_u32_e32 v147, 0x2000, v130
	v_add_u32_e32 v148, 0x2400, v130
	v_add_u32_e32 v149, 0x2800, v130
	v_add_u32_e32 v150, 0x2c00, v130
	v_add_u32_e32 v151, 0x3000, v130
	v_add_u32_e32 v152, 0x3400, v130
	v_add_u32_e32 v153, 0x3800, v130
	v_add_u32_e32 v154, 0x3c00, v130
	v_add_u32_e32 v120, s24, v133
	v_ashrrev_i32_e32 v119, 31, v118
	s_waitcnt vmcnt(0)
	ds_write2_b32 v140, v129, v155 offset0:4 offset1:69
	ds_write2_b32 v140, v126, v127 offset0:134 offset1:199
	ds_write2_b32 v141, v124, v125 offset0:8 offset1:73
	ds_write2_b32 v141, v122, v123 offset0:138 offset1:203
	ds_write2_b32 v142, v116, v117 offset0:12 offset1:77
	ds_write2_b32 v142, v110, v111 offset0:142 offset1:207
	ds_write2_b32 v143, v106, v107 offset0:16 offset1:81
	ds_write2_b32 v143, v102, v103 offset0:146 offset1:211
	ds_write2_b32 v144, v98, v94 offset0:20 offset1:85
	ds_write2_b32 v144, v99, v156 offset0:150 offset1:215
	ds_write2_b32 v145, v157, v158 offset0:24 offset1:89
	ds_write2_b32 v145, v159, v20 offset0:154 offset1:219
	ds_write2_b32 v146, v21, v24 offset0:28 offset1:93
	ds_write2_b32 v146, v25, v28 offset0:158 offset1:223
	ds_write2_b32 v147, v33, v22 offset0:32 offset1:97
	ds_write2_b32 v147, v23, v26 offset0:162 offset1:227
	ds_write2_b32 v130, v95, v29 offset1:65
	ds_write2_b32 v130, v32, v51 offset0:130 offset1:195
	ds_write2_b32 v148, v27, v30 offset0:36 offset1:101
	ds_write2_b32 v148, v31, v34 offset0:166 offset1:231
	ds_write2_b32 v149, v35, v36 offset0:40 offset1:105
	ds_write2_b32 v149, v37, v38 offset0:170 offset1:235
	ds_write2_b32 v150, v39, v42 offset0:44 offset1:109
	ds_write2_b32 v150, v43, v46 offset0:174 offset1:239
	ds_write2_b32 v151, v47, v50 offset0:48 offset1:113
	ds_write2_b32 v151, v40, v41 offset0:178 offset1:243
	ds_write2_b32 v152, v44, v45 offset0:52 offset1:117
	ds_write2_b32 v152, v48, v49 offset0:182 offset1:247
	ds_write2_b32 v153, v52, v53 offset0:56 offset1:121
	ds_write2_b32 v153, v54, v55 offset0:186 offset1:251
	ds_write2_b32 v154, v56, v57 offset0:60 offset1:125
	ds_write2_b32 v154, v58, v59 offset0:190 offset1:255
	v_lshl_add_u64 v[92:93], s[22:23], 1, v[0:1]
	v_ashrrev_i32_e32 v121, 31, v120
	v_lshlrev_b64 v[2:3], 12, v[118:119]
	s_waitcnt lgkmcnt(0)
; #define LAS __attribute__((address_space(3)))
; __device__ __forceinline__ unsigned pk2(float lo, float hi) { unsigned r; asm volatile("v_cvt_pk_bf16_f32 %0, %1, %2" : "=v"(r) : "v"(lo), "v"(hi)); return r; }
; __device__ __forceinline__ void transpose_item(const float* __restrict__ W, int K, int N, bf16_t* __restrict__ WT, int drow0, LAS float* scr, int k0, int n0, int lane, const float* __restrict__ gk) {
;     ...
;     const int c = lane & 7;
; #pragma unroll
;     for (int j = 0; j < 8; ++j) { const int n = (lane >> 3) + 8 * j; const LAS float* s = scr + (8 * c) * 65 + n;
;         u32x4 o; o.x = pk2(s[0 * 65], s[1 * 65]); o.y = pk2(s[2 * 65], s[3 * 65]); o.z = pk2(s[4 * 65], s[5 * 65]); o.w = pk2(s[6 * 65], s[7 * 65]);
;         *(u32x4*)(WT + (size_t)(drow0 + n) * K + k0 + 8 * c) = o; }
;     asm volatile("s_waitcnt lgkmcnt(0)" ::: "memory");
	v_lshlrev_b64 v[4:5], 12, v[120:121]
	v_lshl_add_u64 v[16:17], v[92:93], 0, v[2:3]
	v_add_u32_e32 v128, 0x400, v132
	ds_read2_b32 v[22:23], v132 offset1:65
	ds_read2_b32 v[24:25], v132 offset0:130 offset1:195
	ds_read2_b32 v[26:27], v128 offset0:4 offset1:69
	ds_read2_b32 v[28:29], v128 offset0:134 offset1:199
	ds_read2_b32 v[30:31], v132 offset0:8 offset1:73
	ds_read2_b32 v[32:33], v132 offset0:138 offset1:203
	ds_read2_b32 v[34:35], v128 offset0:12 offset1:77
	ds_read2_b32 v[36:37], v128 offset0:142 offset1:207
	s_waitcnt lgkmcnt(4)
	v_lshl_add_u64 v[18:19], v[92:93], 0, v[4:5]
	v_cvt_pk_bf16_f32 v2, v22, v23
	v_cvt_pk_bf16_f32 v3, v24, v25
	v_cvt_pk_bf16_f32 v4, v26, v27
	v_cvt_pk_bf16_f32 v5, v28, v29
	ds_read2_b32 v[22:23], v132 offset0:16 offset1:81
	ds_read2_b32 v[24:25], v132 offset0:146 offset1:211
	ds_read2_b32 v[26:27], v128 offset0:20 offset1:85
	ds_read2_b32 v[28:29], v128 offset0:150 offset1:215
	s_waitcnt lgkmcnt(4)
	global_store_dwordx4 v[16:17], v[2:5], off
	s_nop 1
	v_add_u32_e32 v114, s24, v134
	v_ashrrev_i32_e32 v115, 31, v114
	v_cvt_pk_bf16_f32 v2, v30, v31
	v_cvt_pk_bf16_f32 v3, v32, v33
	v_cvt_pk_bf16_f32 v4, v34, v35
	v_cvt_pk_bf16_f32 v5, v36, v37
	ds_read2_b32 v[30:31], v132 offset0:24 offset1:89
	ds_read2_b32 v[32:33], v132 offset0:154 offset1:219
	ds_read2_b32 v[34:35], v128 offset0:28 offset1:93
	ds_read2_b32 v[36:37], v128 offset0:158 offset1:223
	s_waitcnt lgkmcnt(4)
	global_store_dwordx4 v[18:19], v[2:5], off
	s_nop 1
	v_lshlrev_b64 v[6:7], 12, v[114:115]
	v_add_u32_e32 v108, s24, v135
	v_cvt_pk_bf16_f32 v2, v22, v23
	v_cvt_pk_bf16_f32 v3, v24, v25
	v_lshl_add_u64 v[6:7], v[92:93], 0, v[6:7]
	v_cvt_pk_bf16_f32 v4, v26, v27
	v_cvt_pk_bf16_f32 v5, v28, v29
	v_ashrrev_i32_e32 v109, 31, v108
	ds_read2_b32 v[22:23], v132 offset0:32 offset1:97
	ds_read2_b32 v[24:25], v132 offset0:162 offset1:227
	ds_read2_b32 v[26:27], v128 offset0:36 offset1:101
	ds_read2_b32 v[28:29], v128 offset0:166 offset1:231
	s_waitcnt lgkmcnt(4)
	global_store_dwordx4 v[6:7], v[2:5], off
	s_nop 1
	v_lshlrev_b64 v[8:9], 12, v[108:109]
	v_add_u32_e32 v104, s24, v136
	v_cvt_pk_bf16_f32 v2, v30, v31
	v_cvt_pk_bf16_f32 v3, v32, v33
	v_lshl_add_u64 v[8:9], v[92:93], 0, v[8:9]
	v_cvt_pk_bf16_f32 v4, v34, v35
	v_cvt_pk_bf16_f32 v5, v36, v37
	v_ashrrev_i32_e32 v105, 31, v104
	ds_read2_b32 v[30:31], v132 offset0:40 offset1:105
	ds_read2_b32 v[32:33], v132 offset0:170 offset1:235
	ds_read2_b32 v[34:35], v128 offset0:44 offset1:109
	ds_read2_b32 v[36:37], v128 offset0:174 offset1:239
	s_waitcnt lgkmcnt(4)
	global_store_dwordx4 v[8:9], v[2:5], off
	s_nop 1
	v_lshlrev_b64 v[10:11], 12, v[104:105]
	v_add_u32_e32 v100, s24, v137
	v_cvt_pk_bf16_f32 v2, v22, v23
	v_cvt_pk_bf16_f32 v3, v24, v25
	v_lshl_add_u64 v[10:11], v[92:93], 0, v[10:11]
	v_cvt_pk_bf16_f32 v4, v26, v27
	v_cvt_pk_bf16_f32 v5, v28, v29
	v_ashrrev_i32_e32 v101, 31, v100
	ds_read2_b32 v[22:23], v132 offset0:48 offset1:113
	ds_read2_b32 v[24:25], v132 offset0:178 offset1:243
	ds_read2_b32 v[26:27], v128 offset0:52 offset1:117
	ds_read2_b32 v[28:29], v128 offset0:182 offset1:247
	s_waitcnt lgkmcnt(4)
	global_store_dwordx4 v[10:11], v[2:5], off
	s_nop 1
	v_lshlrev_b64 v[12:13], 12, v[100:101]
	v_lshl_add_u64 v[12:13], v[92:93], 0, v[12:13]
	v_cvt_pk_bf16_f32 v2, v30, v31
	v_cvt_pk_bf16_f32 v3, v32, v33
	v_cvt_pk_bf16_f32 v4, v34, v35
	v_cvt_pk_bf16_f32 v5, v36, v37
	v_add_u32_e32 v96, s24, v138
	ds_read2_b32 v[30:31], v132 offset0:56 offset1:121
	ds_read2_b32 v[32:33], v132 offset0:186 offset1:251
	ds_read2_b32 v[34:35], v128 offset0:60 offset1:125
	ds_read2_b32 v[36:37], v128 offset0:190 offset1:255
	s_waitcnt lgkmcnt(4)
	global_store_dwordx4 v[12:13], v[2:5], off
	s_nop 1
	v_ashrrev_i32_e32 v97, 31, v96
	v_lshlrev_b64 v[14:15], 12, v[96:97]
	v_cvt_pk_bf16_f32 v2, v22, v23
	v_cvt_pk_bf16_f32 v3, v24, v25
	v_cvt_pk_bf16_f32 v4, v26, v27
	v_lshl_add_u64 v[14:15], v[92:93], 0, v[14:15]
	v_cvt_pk_bf16_f32 v5, v28, v29
	s_waitcnt lgkmcnt(0)
	global_store_dwordx4 v[14:15], v[2:5], off
	s_nop 1
	s_add_i32 s14, s14, s70
	s_add_i32 s16, s16, s17
	v_cvt_pk_bf16_f32 v2, v30, v31
	v_add_u32_e32 v6, s24, v139
	v_ashrrev_i32_e32 v7, 31, v6
	v_lshlrev_b64 v[6:7], 12, v[6:7]
	v_cvt_pk_bf16_f32 v3, v32, v33
	v_lshl_add_u64 v[6:7], v[92:93], 0, v[6:7]
	v_cvt_pk_bf16_f32 v4, v34, v35
	v_cvt_pk_bf16_f32 v5, v36, v37
	global_store_dwordx4 v[6:7], v[2:5], off
	s_nop 1
	s_waitcnt lgkmcnt(0)
	s_cmpk_lt_i32 s14, 0x2c0
	s_cbranch_scc1 .LBB0_618
